# split-K parts 20/20/20/28 K-tiles; MFMA order inside each 8-group changed so consecutive MFMAs share one source operand
# speedup vs baseline: 1.0123x; 1.0005x over previous
.LBB0_296:
	s_ashr_i32 s23, s22, 31
	s_lshl_b64 s[56:57], s[22:23], 21
	s_add_u32 s72, s2, s56
	s_addc_u32 s73, s3, s57
	s_and_b64 s[56:57], s[4:5], exec
	s_cselect_b32 s23, s73, s81
	s_cselect_b32 s56, s72, s80
	s_ashr_i32 s21, s20, 31
	s_lshl_b64 s[60:61], s[20:21], 20
	s_add_u32 s74, s14, s60
	s_addc_u32 s75, s15, s61
	s_and_b64 s[60:61], s[4:5], exec
	s_cselect_b32 s21, s75, s83
	s_cselect_b32 s57, s74, s82
	s_add_u32 s80, s80, 0x100080
	s_addc_u32 s81, s81, 0
	s_add_u32 s60, s82, 0x100
	s_addc_u32 s61, s83, 0
	s_mov_b32 s68, -2
	s_add_u32 s67, s80, 0xfff00080
	s_addc_u32 s69, s81, -1
	s_add_i32 s70, 0, 0x10000
	s_cmp_eq_u32 s68, 28
	s_cselect_b32 s85, s23, s69
	s_cselect_b32 s84, s56, s67
	s_cselect_b32 s83, s21, s61
	s_cselect_b32 s82, s57, s60
	s_add_i32 s67, 0, 0x14000
	v_add_u32_e32 v140, s70, v168
	v_add_u32_e32 v166, s67, v168
	ds_read_b128 v[80:83], v140
	ds_read_b128 v[116:119], v140 offset:1024
	ds_read_b128 v[136:139], v140 offset:2048
	ds_read_b128 v[140:143], v140 offset:3072
	ds_read_b128 v[158:161], v166
	ds_read_b128 v[162:165], v166 offset:1024
	ds_read_b128 v[170:173], v166 offset:2048
	ds_read_b128 v[174:177], v166 offset:3072
	v_lshl_add_u64 v[166:167], s[80:81], 0, v[154:155]
	s_add_i32 m0, s26, 0xc000
	ds_read_b128 v[178:181], v169
	ds_read_b128 v[182:185], v169 offset:1024
	ds_read_b128 v[186:189], v169 offset:2048
	ds_read_b128 v[190:193], v169 offset:3072
	ds_read_b128 v[194:197], v169 offset:4096
	ds_read_b128 v[198:201], v169 offset:5120
	ds_read_b128 v[202:205], v169 offset:6144
	ds_read_b128 v[206:209], v169 offset:7168
	global_load_lds_dwordx4 v[166:167], off
	v_lshl_add_u64 v[166:167], s[80:81], 0, v[156:157]
	s_add_i32 m0, s26, 0xe000
	s_nop 0
	global_load_lds_dwordx4 v[166:167], off
	s_waitcnt vmcnt(8)
	s_waitcnt lgkmcnt(0)
	s_barrier
	s_waitcnt lgkmcnt(0)
	v_mfma_f32_16x16x32_bf16 v[132:135], v[80:83], v[178:181], 0
	v_mfma_f32_16x16x32_bf16 v[128:131], v[136:139], v[178:181], 0
	v_mfma_f32_16x16x32_bf16 v[108:111], v[136:139], v[186:189], 0
	v_mfma_f32_16x16x32_bf16 v[112:115], v[80:83], v[186:189], 0
	v_mfma_f32_16x16x32_bf16 v[96:99], v[80:83], v[194:197], 0
	v_mfma_f32_16x16x32_bf16 v[92:95], v[136:139], v[194:197], 0
	v_mfma_f32_16x16x32_bf16 v[72:75], v[136:139], v[202:205], 0
	v_mfma_f32_16x16x32_bf16 v[76:79], v[80:83], v[202:205], 0
	v_mfma_f32_16x16x32_bf16 v[132:135], v[116:119], v[182:185], v[132:135]
	v_mfma_f32_16x16x32_bf16 v[128:131], v[140:143], v[182:185], v[128:131]
	v_mfma_f32_16x16x32_bf16 v[108:111], v[140:143], v[190:193], v[108:111]
	v_mfma_f32_16x16x32_bf16 v[112:115], v[116:119], v[190:193], v[112:115]
	v_mfma_f32_16x16x32_bf16 v[96:99], v[116:119], v[198:201], v[96:99]
	v_mfma_f32_16x16x32_bf16 v[92:95], v[140:143], v[198:201], v[92:95]
	v_mfma_f32_16x16x32_bf16 v[72:75], v[140:143], v[206:209], v[72:75]
	v_mfma_f32_16x16x32_bf16 v[76:79], v[116:119], v[206:209], v[76:79]
	v_mfma_f32_16x16x32_bf16 v[124:127], v[158:161], v[178:181], 0
	v_mfma_f32_16x16x32_bf16 v[120:123], v[170:173], v[178:181], 0
	v_mfma_f32_16x16x32_bf16 v[100:103], v[170:173], v[186:189], 0
	v_mfma_f32_16x16x32_bf16 v[104:107], v[158:161], v[186:189], 0
	v_mfma_f32_16x16x32_bf16 v[88:91], v[158:161], v[194:197], 0
	v_mfma_f32_16x16x32_bf16 v[84:87], v[170:173], v[194:197], 0
	v_mfma_f32_16x16x32_bf16 v[64:67], v[170:173], v[202:205], 0
	v_mfma_f32_16x16x32_bf16 v[68:71], v[158:161], v[202:205], 0
	v_mfma_f32_16x16x32_bf16 v[124:127], v[162:165], v[182:185], v[124:127]
	v_mfma_f32_16x16x32_bf16 v[120:123], v[174:177], v[182:185], v[120:123]
	v_mfma_f32_16x16x32_bf16 v[100:103], v[174:177], v[190:193], v[100:103]
	v_mfma_f32_16x16x32_bf16 v[104:107], v[162:165], v[190:193], v[104:107]
	v_mfma_f32_16x16x32_bf16 v[88:91], v[162:165], v[198:201], v[88:91]
	v_mfma_f32_16x16x32_bf16 v[84:87], v[174:177], v[198:201], v[84:87]
	v_mfma_f32_16x16x32_bf16 v[64:67], v[174:177], v[206:209], v[64:67]
	v_mfma_f32_16x16x32_bf16 v[68:71], v[162:165], v[206:209], v[68:71]
	s_barrier
	s_add_i32 s69, s70, s24
	v_lshl_add_u64 v[166:167], s[82:83], 0, v[146:147]
	s_mov_b32 m0, s69
	ds_read_b128 v[178:181], v169 offset:16384
	ds_read_b128 v[182:185], v169 offset:17408
	ds_read_b128 v[186:189], v169 offset:18432
	ds_read_b128 v[190:193], v169 offset:19456
	ds_read_b128 v[194:197], v169 offset:20480
	ds_read_b128 v[198:201], v169 offset:21504
	ds_read_b128 v[202:205], v169 offset:22528
	ds_read_b128 v[206:209], v169 offset:23552
	global_load_lds_dwordx4 v[166:167], off
	s_add_i32 m0, s69, 0x2000
	s_add_u32 s70, s82, 0x80000
	v_lshl_add_u64 v[210:211], s[82:83], 0, v[150:151]
	s_addc_u32 s71, s83, 0
	s_add_i32 s67, s67, s24
	global_load_lds_dwordx4 v[210:211], off
	v_lshl_add_u64 v[212:213], s[70:71], 0, v[146:147]
	s_mov_b32 m0, s67
	v_lshl_add_u64 v[214:215], s[84:85], 0, v[148:149]
	global_load_lds_dwordx4 v[212:213], off
	v_lshl_add_u64 v[212:213], s[70:71], 0, v[150:151]
	s_add_i32 m0, s67, 0x2000
	s_nop 0
	global_load_lds_dwordx4 v[212:213], off
	v_lshl_add_u64 v[212:213], s[84:85], 0, v[144:145]
	s_mov_b32 m0, s26
	s_nop 0
	global_load_lds_dwordx4 v[212:213], off
	s_mov_b32 m0, s28
	s_nop 0
	global_load_lds_dwordx4 v[214:215], off
	s_waitcnt vmcnt(8)
	s_waitcnt lgkmcnt(0)
	s_barrier
	s_waitcnt lgkmcnt(0)
	v_mfma_f32_16x16x32_bf16 v[60:63], v[80:83], v[178:181], 0
	v_mfma_f32_16x16x32_bf16 v[56:59], v[136:139], v[178:181], 0
	v_mfma_f32_16x16x32_bf16 v[40:43], v[136:139], v[186:189], 0
	v_mfma_f32_16x16x32_bf16 v[44:47], v[80:83], v[186:189], 0
	v_mfma_f32_16x16x32_bf16 v[28:31], v[80:83], v[194:197], 0
	v_mfma_f32_16x16x32_bf16 v[24:27], v[136:139], v[194:197], 0
	v_mfma_f32_16x16x32_bf16 v[8:11], v[136:139], v[202:205], 0
	v_mfma_f32_16x16x32_bf16 v[12:15], v[80:83], v[202:205], 0
	v_mfma_f32_16x16x32_bf16 v[60:63], v[116:119], v[182:185], v[60:63]
	v_mfma_f32_16x16x32_bf16 v[56:59], v[140:143], v[182:185], v[56:59]
	v_mfma_f32_16x16x32_bf16 v[40:43], v[140:143], v[190:193], v[40:43]
	v_mfma_f32_16x16x32_bf16 v[44:47], v[116:119], v[190:193], v[44:47]
	v_mfma_f32_16x16x32_bf16 v[28:31], v[116:119], v[198:201], v[28:31]
	v_mfma_f32_16x16x32_bf16 v[24:27], v[140:143], v[198:201], v[24:27]
	v_mfma_f32_16x16x32_bf16 v[8:11], v[140:143], v[206:209], v[8:11]
	v_mfma_f32_16x16x32_bf16 v[12:15], v[116:119], v[206:209], v[12:15]
	v_mfma_f32_16x16x32_bf16 v[52:55], v[158:161], v[178:181], 0
	v_mfma_f32_16x16x32_bf16 v[48:51], v[170:173], v[178:181], 0
	v_mfma_f32_16x16x32_bf16 v[32:35], v[170:173], v[186:189], 0
	v_mfma_f32_16x16x32_bf16 v[36:39], v[158:161], v[186:189], 0
	v_mfma_f32_16x16x32_bf16 v[20:23], v[158:161], v[194:197], 0
	v_mfma_f32_16x16x32_bf16 v[16:19], v[170:173], v[194:197], 0
	v_mfma_f32_16x16x32_bf16 v[0:3], v[170:173], v[202:205], 0
	v_mfma_f32_16x16x32_bf16 v[4:7], v[158:161], v[202:205], 0
	v_mfma_f32_16x16x32_bf16 v[52:55], v[162:165], v[182:185], v[52:55]
	v_mfma_f32_16x16x32_bf16 v[48:51], v[174:177], v[182:185], v[48:51]
	v_mfma_f32_16x16x32_bf16 v[32:35], v[174:177], v[190:193], v[32:35]
	v_mfma_f32_16x16x32_bf16 v[36:39], v[162:165], v[190:193], v[36:39]
	v_mfma_f32_16x16x32_bf16 v[20:23], v[162:165], v[198:201], v[20:23]
	v_mfma_f32_16x16x32_bf16 v[16:19], v[174:177], v[198:201], v[16:19]
	v_mfma_f32_16x16x32_bf16 v[0:3], v[174:177], v[206:209], v[0:3]
	v_mfma_f32_16x16x32_bf16 v[4:7], v[162:165], v[206:209], v[4:7]
	s_barrier
	s_add_i32 s67, 0, 0x18000
	s_add_i32 s69, 0, 0x1c000
	v_add_u32_e32 v140, s67, v168
	v_add_u32_e32 v174, s69, v168
	ds_read_b128 v[80:83], v140
	ds_read_b128 v[116:119], v140 offset:1024
	ds_read_b128 v[136:139], v140 offset:2048
	ds_read_b128 v[140:143], v140 offset:3072
	ds_read_b128 v[158:161], v174
	ds_read_b128 v[162:165], v174 offset:1024
	ds_read_b128 v[170:173], v174 offset:2048
	ds_read_b128 v[174:177], v174 offset:3072
	s_add_u32 s70, s84, 0x100000
	s_addc_u32 s71, s85, 0
	s_mov_b32 m0, s29
	v_lshl_add_u64 v[218:219], s[70:71], 0, v[144:145]
	ds_read_b128 v[178:181], v169 offset:32768
	ds_read_b128 v[182:185], v169 offset:33792
	ds_read_b128 v[186:189], v169 offset:34816
	ds_read_b128 v[190:193], v169 offset:35840
	ds_read_b128 v[194:197], v169 offset:36864
	ds_read_b128 v[198:201], v169 offset:37888
	ds_read_b128 v[202:205], v169 offset:38912
	ds_read_b128 v[206:209], v169 offset:39936
	global_load_lds_dwordx4 v[218:219], off
	v_lshl_add_u64 v[218:219], s[70:71], 0, v[148:149]
	s_mov_b32 m0, s34
	s_nop 0
	global_load_lds_dwordx4 v[218:219], off
	s_waitcnt vmcnt(8)
	s_waitcnt lgkmcnt(0)
	s_barrier
	s_waitcnt lgkmcnt(0)
	v_mfma_f32_16x16x32_bf16 v[132:135], v[80:83], v[178:181], v[132:135]
	v_mfma_f32_16x16x32_bf16 v[128:131], v[136:139], v[178:181], v[128:131]
	v_mfma_f32_16x16x32_bf16 v[108:111], v[136:139], v[186:189], v[108:111]
	v_mfma_f32_16x16x32_bf16 v[112:115], v[80:83], v[186:189], v[112:115]
	v_mfma_f32_16x16x32_bf16 v[96:99], v[80:83], v[194:197], v[96:99]
	v_mfma_f32_16x16x32_bf16 v[92:95], v[136:139], v[194:197], v[92:95]
	v_mfma_f32_16x16x32_bf16 v[72:75], v[136:139], v[202:205], v[72:75]
	v_mfma_f32_16x16x32_bf16 v[76:79], v[80:83], v[202:205], v[76:79]
	v_mfma_f32_16x16x32_bf16 v[132:135], v[116:119], v[182:185], v[132:135]
	v_mfma_f32_16x16x32_bf16 v[128:131], v[140:143], v[182:185], v[128:131]
	v_mfma_f32_16x16x32_bf16 v[108:111], v[140:143], v[190:193], v[108:111]
	v_mfma_f32_16x16x32_bf16 v[112:115], v[116:119], v[190:193], v[112:115]
	v_mfma_f32_16x16x32_bf16 v[96:99], v[116:119], v[198:201], v[96:99]
	v_mfma_f32_16x16x32_bf16 v[92:95], v[140:143], v[198:201], v[92:95]
	v_mfma_f32_16x16x32_bf16 v[72:75], v[140:143], v[206:209], v[72:75]
	v_mfma_f32_16x16x32_bf16 v[76:79], v[116:119], v[206:209], v[76:79]
	v_mfma_f32_16x16x32_bf16 v[124:127], v[158:161], v[178:181], v[124:127]
	v_mfma_f32_16x16x32_bf16 v[120:123], v[170:173], v[178:181], v[120:123]
	v_mfma_f32_16x16x32_bf16 v[100:103], v[170:173], v[186:189], v[100:103]
	v_mfma_f32_16x16x32_bf16 v[104:107], v[158:161], v[186:189], v[104:107]
	v_mfma_f32_16x16x32_bf16 v[88:91], v[158:161], v[194:197], v[88:91]
	v_mfma_f32_16x16x32_bf16 v[84:87], v[170:173], v[194:197], v[84:87]
	v_mfma_f32_16x16x32_bf16 v[64:67], v[170:173], v[202:205], v[64:67]
	v_mfma_f32_16x16x32_bf16 v[68:71], v[158:161], v[202:205], v[68:71]
	v_mfma_f32_16x16x32_bf16 v[124:127], v[162:165], v[182:185], v[124:127]
	v_mfma_f32_16x16x32_bf16 v[120:123], v[174:177], v[182:185], v[120:123]
	v_mfma_f32_16x16x32_bf16 v[100:103], v[174:177], v[190:193], v[100:103]
	v_mfma_f32_16x16x32_bf16 v[104:107], v[162:165], v[190:193], v[104:107]
	v_mfma_f32_16x16x32_bf16 v[88:91], v[162:165], v[198:201], v[88:91]
	v_mfma_f32_16x16x32_bf16 v[84:87], v[174:177], v[198:201], v[84:87]
	v_mfma_f32_16x16x32_bf16 v[64:67], v[174:177], v[206:209], v[64:67]
	v_mfma_f32_16x16x32_bf16 v[68:71], v[162:165], v[206:209], v[68:71]
	s_barrier
	s_add_i32 s67, s67, s24
	v_lshl_add_u64 v[166:167], v[166:167], 0, s[30:31]
	s_mov_b32 m0, s67
	ds_read_b128 v[178:181], v169 offset:49152
	ds_read_b128 v[182:185], v169 offset:50176
	ds_read_b128 v[186:189], v169 offset:51200
	ds_read_b128 v[190:193], v169 offset:52224
	ds_read_b128 v[194:197], v169 offset:53248
	ds_read_b128 v[198:201], v169 offset:54272
	ds_read_b128 v[202:205], v169 offset:55296
	ds_read_b128 v[206:209], v169 offset:56320
	global_load_lds_dwordx4 v[166:167], off
	s_add_i32 m0, s67, 0x2000
	s_add_u32 s70, s82, 0x80080
	v_lshl_add_u64 v[166:167], v[210:211], 0, s[30:31]
	s_addc_u32 s71, s83, 0
	s_add_i32 s67, s69, s24
	global_load_lds_dwordx4 v[166:167], off
	v_lshl_add_u64 v[166:167], s[70:71], 0, v[146:147]
	s_mov_b32 m0, s67
	s_nop 0
	global_load_lds_dwordx4 v[166:167], off
	v_lshl_add_u64 v[166:167], s[70:71], 0, v[150:151]
	s_add_i32 m0, s67, 0x2000
	s_nop 0
	global_load_lds_dwordx4 v[166:167], off
	v_lshl_add_u64 v[166:167], v[212:213], 0, s[30:31]
	s_mov_b32 m0, s39
	s_nop 0
	global_load_lds_dwordx4 v[166:167], off
	v_lshl_add_u64 v[166:167], v[214:215], 0, s[30:31]
	s_mov_b32 m0, s40
	s_nop 0
	global_load_lds_dwordx4 v[166:167], off
	s_waitcnt vmcnt(8)
	s_waitcnt lgkmcnt(0)
	s_barrier
	s_waitcnt lgkmcnt(0)
	v_mfma_f32_16x16x32_bf16 v[60:63], v[80:83], v[178:181], v[60:63]
	v_mfma_f32_16x16x32_bf16 v[56:59], v[136:139], v[178:181], v[56:59]
	v_mfma_f32_16x16x32_bf16 v[40:43], v[136:139], v[186:189], v[40:43]
	v_mfma_f32_16x16x32_bf16 v[44:47], v[80:83], v[186:189], v[44:47]
	v_mfma_f32_16x16x32_bf16 v[28:31], v[80:83], v[194:197], v[28:31]
	v_mfma_f32_16x16x32_bf16 v[24:27], v[136:139], v[194:197], v[24:27]
	v_mfma_f32_16x16x32_bf16 v[8:11], v[136:139], v[202:205], v[8:11]
	v_mfma_f32_16x16x32_bf16 v[12:15], v[80:83], v[202:205], v[12:15]
	v_mfma_f32_16x16x32_bf16 v[60:63], v[116:119], v[182:185], v[60:63]
	v_mfma_f32_16x16x32_bf16 v[56:59], v[140:143], v[182:185], v[56:59]
	v_mfma_f32_16x16x32_bf16 v[40:43], v[140:143], v[190:193], v[40:43]
	v_mfma_f32_16x16x32_bf16 v[44:47], v[116:119], v[190:193], v[44:47]
	v_mfma_f32_16x16x32_bf16 v[28:31], v[116:119], v[198:201], v[28:31]
	v_mfma_f32_16x16x32_bf16 v[24:27], v[140:143], v[198:201], v[24:27]
	v_mfma_f32_16x16x32_bf16 v[8:11], v[140:143], v[206:209], v[8:11]
	v_mfma_f32_16x16x32_bf16 v[12:15], v[116:119], v[206:209], v[12:15]
	v_mfma_f32_16x16x32_bf16 v[52:55], v[158:161], v[178:181], v[52:55]
	v_mfma_f32_16x16x32_bf16 v[48:51], v[170:173], v[178:181], v[48:51]
	v_mfma_f32_16x16x32_bf16 v[32:35], v[170:173], v[186:189], v[32:35]
	v_mfma_f32_16x16x32_bf16 v[36:39], v[158:161], v[186:189], v[36:39]
	v_mfma_f32_16x16x32_bf16 v[20:23], v[158:161], v[194:197], v[20:23]
	v_mfma_f32_16x16x32_bf16 v[16:19], v[170:173], v[194:197], v[16:19]
	v_mfma_f32_16x16x32_bf16 v[0:3], v[170:173], v[202:205], v[0:3]
	v_mfma_f32_16x16x32_bf16 v[4:7], v[158:161], v[202:205], v[4:7]
	v_mfma_f32_16x16x32_bf16 v[52:55], v[162:165], v[182:185], v[52:55]
	v_mfma_f32_16x16x32_bf16 v[48:51], v[174:177], v[182:185], v[48:51]
	v_mfma_f32_16x16x32_bf16 v[32:35], v[174:177], v[190:193], v[32:35]
	v_mfma_f32_16x16x32_bf16 v[36:39], v[162:165], v[190:193], v[36:39]
	v_mfma_f32_16x16x32_bf16 v[20:23], v[162:165], v[198:201], v[20:23]
	v_mfma_f32_16x16x32_bf16 v[16:19], v[174:177], v[198:201], v[16:19]
	v_mfma_f32_16x16x32_bf16 v[0:3], v[174:177], v[206:209], v[0:3]
	v_mfma_f32_16x16x32_bf16 v[4:7], v[162:165], v[206:209], v[4:7]
	s_barrier
	s_add_i32 s68, s68, 2
	s_add_u32 s80, s80, 0x100
	s_addc_u32 s81, s81, 0
	s_add_u32 s60, s60, 0x100
	s_addc_u32 s61, s61, 0
.LBB0_297:
	s_add_u32 s67, s80, 0xfff00080
	s_addc_u32 s69, s81, -1
	s_add_i32 s70, 0, 0x10000
	s_cmp_eq_u32 s68, 28
	s_cselect_b32 s85, s23, s69
	s_cselect_b32 s84, s56, s67
	s_cselect_b32 s83, s21, s61
	s_cselect_b32 s82, s57, s60
	s_add_i32 s67, 0, 0x14000
	v_add_u32_e32 v140, s70, v168
	v_add_u32_e32 v166, s67, v168
	ds_read_b128 v[80:83], v140
	ds_read_b128 v[116:119], v140 offset:1024
	ds_read_b128 v[136:139], v140 offset:2048
	ds_read_b128 v[140:143], v140 offset:3072
	ds_read_b128 v[158:161], v166
	ds_read_b128 v[162:165], v166 offset:1024
	ds_read_b128 v[170:173], v166 offset:2048
	ds_read_b128 v[174:177], v166 offset:3072
	v_lshl_add_u64 v[166:167], s[80:81], 0, v[154:155]
	s_add_i32 m0, s26, 0xc000
	ds_read_b128 v[178:181], v169
	ds_read_b128 v[182:185], v169 offset:1024
	ds_read_b128 v[186:189], v169 offset:2048
	ds_read_b128 v[190:193], v169 offset:3072
	ds_read_b128 v[194:197], v169 offset:4096
	ds_read_b128 v[198:201], v169 offset:5120
	ds_read_b128 v[202:205], v169 offset:6144
	ds_read_b128 v[206:209], v169 offset:7168
	global_load_lds_dwordx4 v[166:167], off
	v_lshl_add_u64 v[166:167], s[80:81], 0, v[156:157]
	s_add_i32 m0, s26, 0xe000
	s_nop 0
	global_load_lds_dwordx4 v[166:167], off
	s_waitcnt vmcnt(8)
	s_waitcnt lgkmcnt(0)
	s_barrier
	s_waitcnt lgkmcnt(0)
	v_mfma_f32_16x16x32_bf16 v[132:135], v[80:83], v[178:181], v[132:135]
	v_mfma_f32_16x16x32_bf16 v[128:131], v[136:139], v[178:181], v[128:131]
	v_mfma_f32_16x16x32_bf16 v[108:111], v[136:139], v[186:189], v[108:111]
	v_mfma_f32_16x16x32_bf16 v[112:115], v[80:83], v[186:189], v[112:115]
	v_mfma_f32_16x16x32_bf16 v[96:99], v[80:83], v[194:197], v[96:99]
	v_mfma_f32_16x16x32_bf16 v[92:95], v[136:139], v[194:197], v[92:95]
	v_mfma_f32_16x16x32_bf16 v[72:75], v[136:139], v[202:205], v[72:75]
	v_mfma_f32_16x16x32_bf16 v[76:79], v[80:83], v[202:205], v[76:79]
	v_mfma_f32_16x16x32_bf16 v[132:135], v[116:119], v[182:185], v[132:135]
	v_mfma_f32_16x16x32_bf16 v[128:131], v[140:143], v[182:185], v[128:131]
	v_mfma_f32_16x16x32_bf16 v[108:111], v[140:143], v[190:193], v[108:111]
	v_mfma_f32_16x16x32_bf16 v[112:115], v[116:119], v[190:193], v[112:115]
	v_mfma_f32_16x16x32_bf16 v[96:99], v[116:119], v[198:201], v[96:99]
	v_mfma_f32_16x16x32_bf16 v[92:95], v[140:143], v[198:201], v[92:95]
	v_mfma_f32_16x16x32_bf16 v[72:75], v[140:143], v[206:209], v[72:75]
	v_mfma_f32_16x16x32_bf16 v[76:79], v[116:119], v[206:209], v[76:79]
	v_mfma_f32_16x16x32_bf16 v[124:127], v[158:161], v[178:181], v[124:127]
	v_mfma_f32_16x16x32_bf16 v[120:123], v[170:173], v[178:181], v[120:123]
	v_mfma_f32_16x16x32_bf16 v[100:103], v[170:173], v[186:189], v[100:103]
	v_mfma_f32_16x16x32_bf16 v[104:107], v[158:161], v[186:189], v[104:107]
	v_mfma_f32_16x16x32_bf16 v[88:91], v[158:161], v[194:197], v[88:91]
	v_mfma_f32_16x16x32_bf16 v[84:87], v[170:173], v[194:197], v[84:87]
	v_mfma_f32_16x16x32_bf16 v[64:67], v[170:173], v[202:205], v[64:67]
	v_mfma_f32_16x16x32_bf16 v[68:71], v[158:161], v[202:205], v[68:71]
	v_mfma_f32_16x16x32_bf16 v[124:127], v[162:165], v[182:185], v[124:127]
	v_mfma_f32_16x16x32_bf16 v[120:123], v[174:177], v[182:185], v[120:123]
	v_mfma_f32_16x16x32_bf16 v[100:103], v[174:177], v[190:193], v[100:103]
	v_mfma_f32_16x16x32_bf16 v[104:107], v[162:165], v[190:193], v[104:107]
	v_mfma_f32_16x16x32_bf16 v[88:91], v[162:165], v[198:201], v[88:91]
	v_mfma_f32_16x16x32_bf16 v[84:87], v[174:177], v[198:201], v[84:87]
	v_mfma_f32_16x16x32_bf16 v[64:67], v[174:177], v[206:209], v[64:67]
	v_mfma_f32_16x16x32_bf16 v[68:71], v[162:165], v[206:209], v[68:71]
	s_barrier
	s_add_i32 s69, s70, s24
	v_lshl_add_u64 v[166:167], s[82:83], 0, v[146:147]
	s_mov_b32 m0, s69
	ds_read_b128 v[178:181], v169 offset:16384
	ds_read_b128 v[182:185], v169 offset:17408
	ds_read_b128 v[186:189], v169 offset:18432
	ds_read_b128 v[190:193], v169 offset:19456
	ds_read_b128 v[194:197], v169 offset:20480
	ds_read_b128 v[198:201], v169 offset:21504
	ds_read_b128 v[202:205], v169 offset:22528
	ds_read_b128 v[206:209], v169 offset:23552
	global_load_lds_dwordx4 v[166:167], off
	s_add_i32 m0, s69, 0x2000
	s_add_u32 s70, s82, 0x80000
	v_lshl_add_u64 v[210:211], s[82:83], 0, v[150:151]
	s_addc_u32 s71, s83, 0
	s_add_i32 s67, s67, s24
	global_load_lds_dwordx4 v[210:211], off
	v_lshl_add_u64 v[212:213], s[70:71], 0, v[146:147]
	s_mov_b32 m0, s67
	v_lshl_add_u64 v[214:215], s[84:85], 0, v[148:149]
	global_load_lds_dwordx4 v[212:213], off
	v_lshl_add_u64 v[212:213], s[70:71], 0, v[150:151]
	s_add_i32 m0, s67, 0x2000
	s_nop 0
	global_load_lds_dwordx4 v[212:213], off
	v_lshl_add_u64 v[212:213], s[84:85], 0, v[144:145]
	s_mov_b32 m0, s26
	s_nop 0
	global_load_lds_dwordx4 v[212:213], off
	s_mov_b32 m0, s28
	s_nop 0
	global_load_lds_dwordx4 v[214:215], off
	s_waitcnt vmcnt(8)
	s_waitcnt lgkmcnt(0)
	s_barrier
	s_waitcnt lgkmcnt(0)
	v_mfma_f32_16x16x32_bf16 v[60:63], v[80:83], v[178:181], v[60:63]
	v_mfma_f32_16x16x32_bf16 v[56:59], v[136:139], v[178:181], v[56:59]
	v_mfma_f32_16x16x32_bf16 v[40:43], v[136:139], v[186:189], v[40:43]
	v_mfma_f32_16x16x32_bf16 v[44:47], v[80:83], v[186:189], v[44:47]
	v_mfma_f32_16x16x32_bf16 v[28:31], v[80:83], v[194:197], v[28:31]
	v_mfma_f32_16x16x32_bf16 v[24:27], v[136:139], v[194:197], v[24:27]
	v_mfma_f32_16x16x32_bf16 v[8:11], v[136:139], v[202:205], v[8:11]
	v_mfma_f32_16x16x32_bf16 v[12:15], v[80:83], v[202:205], v[12:15]
	v_mfma_f32_16x16x32_bf16 v[60:63], v[116:119], v[182:185], v[60:63]
	v_mfma_f32_16x16x32_bf16 v[56:59], v[140:143], v[182:185], v[56:59]
	v_mfma_f32_16x16x32_bf16 v[40:43], v[140:143], v[190:193], v[40:43]
	v_mfma_f32_16x16x32_bf16 v[44:47], v[116:119], v[190:193], v[44:47]
	v_mfma_f32_16x16x32_bf16 v[28:31], v[116:119], v[198:201], v[28:31]
	v_mfma_f32_16x16x32_bf16 v[24:27], v[140:143], v[198:201], v[24:27]
	v_mfma_f32_16x16x32_bf16 v[8:11], v[140:143], v[206:209], v[8:11]
	v_mfma_f32_16x16x32_bf16 v[12:15], v[116:119], v[206:209], v[12:15]
	v_mfma_f32_16x16x32_bf16 v[52:55], v[158:161], v[178:181], v[52:55]
	v_mfma_f32_16x16x32_bf16 v[48:51], v[170:173], v[178:181], v[48:51]
	v_mfma_f32_16x16x32_bf16 v[32:35], v[170:173], v[186:189], v[32:35]
	v_mfma_f32_16x16x32_bf16 v[36:39], v[158:161], v[186:189], v[36:39]
	v_mfma_f32_16x16x32_bf16 v[20:23], v[158:161], v[194:197], v[20:23]
	v_mfma_f32_16x16x32_bf16 v[16:19], v[170:173], v[194:197], v[16:19]
	v_mfma_f32_16x16x32_bf16 v[0:3], v[170:173], v[202:205], v[0:3]
	v_mfma_f32_16x16x32_bf16 v[4:7], v[158:161], v[202:205], v[4:7]
	v_mfma_f32_16x16x32_bf16 v[52:55], v[162:165], v[182:185], v[52:55]
	v_mfma_f32_16x16x32_bf16 v[48:51], v[174:177], v[182:185], v[48:51]
	v_mfma_f32_16x16x32_bf16 v[32:35], v[174:177], v[190:193], v[32:35]
	v_mfma_f32_16x16x32_bf16 v[36:39], v[162:165], v[190:193], v[36:39]
	v_mfma_f32_16x16x32_bf16 v[20:23], v[162:165], v[198:201], v[20:23]
	v_mfma_f32_16x16x32_bf16 v[16:19], v[174:177], v[198:201], v[16:19]
	v_mfma_f32_16x16x32_bf16 v[0:3], v[174:177], v[206:209], v[0:3]
	v_mfma_f32_16x16x32_bf16 v[4:7], v[162:165], v[206:209], v[4:7]
	s_barrier
	s_add_i32 s67, 0, 0x18000
	s_add_i32 s69, 0, 0x1c000
	v_add_u32_e32 v140, s67, v168
	v_add_u32_e32 v174, s69, v168
	ds_read_b128 v[80:83], v140
	ds_read_b128 v[116:119], v140 offset:1024
	ds_read_b128 v[136:139], v140 offset:2048
	ds_read_b128 v[140:143], v140 offset:3072
	ds_read_b128 v[158:161], v174
	ds_read_b128 v[162:165], v174 offset:1024
	ds_read_b128 v[170:173], v174 offset:2048
	ds_read_b128 v[174:177], v174 offset:3072
	s_add_u32 s70, s84, 0x100000
	s_addc_u32 s71, s85, 0
	s_mov_b32 m0, s29
	v_lshl_add_u64 v[218:219], s[70:71], 0, v[144:145]
	ds_read_b128 v[178:181], v169 offset:32768
	ds_read_b128 v[182:185], v169 offset:33792
	ds_read_b128 v[186:189], v169 offset:34816
	ds_read_b128 v[190:193], v169 offset:35840
	ds_read_b128 v[194:197], v169 offset:36864
	ds_read_b128 v[198:201], v169 offset:37888
	ds_read_b128 v[202:205], v169 offset:38912
	ds_read_b128 v[206:209], v169 offset:39936
	global_load_lds_dwordx4 v[218:219], off
	v_lshl_add_u64 v[218:219], s[70:71], 0, v[148:149]
	s_mov_b32 m0, s34
	s_nop 0
	global_load_lds_dwordx4 v[218:219], off
	s_waitcnt vmcnt(8)
	s_waitcnt lgkmcnt(0)
	s_barrier
	s_waitcnt lgkmcnt(0)
	v_mfma_f32_16x16x32_bf16 v[132:135], v[80:83], v[178:181], v[132:135]
	v_mfma_f32_16x16x32_bf16 v[128:131], v[136:139], v[178:181], v[128:131]
	v_mfma_f32_16x16x32_bf16 v[108:111], v[136:139], v[186:189], v[108:111]
	v_mfma_f32_16x16x32_bf16 v[112:115], v[80:83], v[186:189], v[112:115]
	v_mfma_f32_16x16x32_bf16 v[96:99], v[80:83], v[194:197], v[96:99]
	v_mfma_f32_16x16x32_bf16 v[92:95], v[136:139], v[194:197], v[92:95]
	v_mfma_f32_16x16x32_bf16 v[72:75], v[136:139], v[202:205], v[72:75]
	v_mfma_f32_16x16x32_bf16 v[76:79], v[80:83], v[202:205], v[76:79]
	v_mfma_f32_16x16x32_bf16 v[132:135], v[116:119], v[182:185], v[132:135]
	v_mfma_f32_16x16x32_bf16 v[128:131], v[140:143], v[182:185], v[128:131]
	v_mfma_f32_16x16x32_bf16 v[108:111], v[140:143], v[190:193], v[108:111]
	v_mfma_f32_16x16x32_bf16 v[112:115], v[116:119], v[190:193], v[112:115]
	v_mfma_f32_16x16x32_bf16 v[96:99], v[116:119], v[198:201], v[96:99]
	v_mfma_f32_16x16x32_bf16 v[92:95], v[140:143], v[198:201], v[92:95]
	v_mfma_f32_16x16x32_bf16 v[72:75], v[140:143], v[206:209], v[72:75]
	v_mfma_f32_16x16x32_bf16 v[76:79], v[116:119], v[206:209], v[76:79]
	v_mfma_f32_16x16x32_bf16 v[124:127], v[158:161], v[178:181], v[124:127]
	v_mfma_f32_16x16x32_bf16 v[120:123], v[170:173], v[178:181], v[120:123]
	v_mfma_f32_16x16x32_bf16 v[100:103], v[170:173], v[186:189], v[100:103]
	v_mfma_f32_16x16x32_bf16 v[104:107], v[158:161], v[186:189], v[104:107]
	v_mfma_f32_16x16x32_bf16 v[88:91], v[158:161], v[194:197], v[88:91]
	v_mfma_f32_16x16x32_bf16 v[84:87], v[170:173], v[194:197], v[84:87]
	v_mfma_f32_16x16x32_bf16 v[64:67], v[170:173], v[202:205], v[64:67]
	v_mfma_f32_16x16x32_bf16 v[68:71], v[158:161], v[202:205], v[68:71]
	v_mfma_f32_16x16x32_bf16 v[124:127], v[162:165], v[182:185], v[124:127]
	v_mfma_f32_16x16x32_bf16 v[120:123], v[174:177], v[182:185], v[120:123]
	v_mfma_f32_16x16x32_bf16 v[100:103], v[174:177], v[190:193], v[100:103]
	v_mfma_f32_16x16x32_bf16 v[104:107], v[162:165], v[190:193], v[104:107]
	v_mfma_f32_16x16x32_bf16 v[88:91], v[162:165], v[198:201], v[88:91]
	v_mfma_f32_16x16x32_bf16 v[84:87], v[174:177], v[198:201], v[84:87]
	v_mfma_f32_16x16x32_bf16 v[64:67], v[174:177], v[206:209], v[64:67]
	v_mfma_f32_16x16x32_bf16 v[68:71], v[162:165], v[206:209], v[68:71]
	s_barrier
	s_add_i32 s67, s67, s24
	v_lshl_add_u64 v[166:167], v[166:167], 0, s[30:31]
	s_mov_b32 m0, s67
	ds_read_b128 v[178:181], v169 offset:49152
	ds_read_b128 v[182:185], v169 offset:50176
	ds_read_b128 v[186:189], v169 offset:51200
	ds_read_b128 v[190:193], v169 offset:52224
	ds_read_b128 v[194:197], v169 offset:53248
	ds_read_b128 v[198:201], v169 offset:54272
	ds_read_b128 v[202:205], v169 offset:55296
	ds_read_b128 v[206:209], v169 offset:56320
	global_load_lds_dwordx4 v[166:167], off
	s_add_i32 m0, s67, 0x2000
	s_add_u32 s70, s82, 0x80080
	v_lshl_add_u64 v[166:167], v[210:211], 0, s[30:31]
	s_addc_u32 s71, s83, 0
	s_add_i32 s67, s69, s24
	global_load_lds_dwordx4 v[166:167], off
	v_lshl_add_u64 v[166:167], s[70:71], 0, v[146:147]
	s_mov_b32 m0, s67
	s_nop 0
	global_load_lds_dwordx4 v[166:167], off
	v_lshl_add_u64 v[166:167], s[70:71], 0, v[150:151]
	s_add_i32 m0, s67, 0x2000
	s_nop 0
	global_load_lds_dwordx4 v[166:167], off
	v_lshl_add_u64 v[166:167], v[212:213], 0, s[30:31]
	s_mov_b32 m0, s39
	s_nop 0
	global_load_lds_dwordx4 v[166:167], off
	v_lshl_add_u64 v[166:167], v[214:215], 0, s[30:31]
	s_mov_b32 m0, s40
	s_nop 0
	global_load_lds_dwordx4 v[166:167], off
	s_waitcnt vmcnt(8)
	s_waitcnt lgkmcnt(0)
	s_barrier
	s_waitcnt lgkmcnt(0)
	v_mfma_f32_16x16x32_bf16 v[60:63], v[80:83], v[178:181], v[60:63]
	v_mfma_f32_16x16x32_bf16 v[56:59], v[136:139], v[178:181], v[56:59]
	v_mfma_f32_16x16x32_bf16 v[40:43], v[136:139], v[186:189], v[40:43]
	v_mfma_f32_16x16x32_bf16 v[44:47], v[80:83], v[186:189], v[44:47]
	v_mfma_f32_16x16x32_bf16 v[28:31], v[80:83], v[194:197], v[28:31]
	v_mfma_f32_16x16x32_bf16 v[24:27], v[136:139], v[194:197], v[24:27]
	v_mfma_f32_16x16x32_bf16 v[8:11], v[136:139], v[202:205], v[8:11]
	v_mfma_f32_16x16x32_bf16 v[12:15], v[80:83], v[202:205], v[12:15]
	v_mfma_f32_16x16x32_bf16 v[60:63], v[116:119], v[182:185], v[60:63]
	v_mfma_f32_16x16x32_bf16 v[56:59], v[140:143], v[182:185], v[56:59]
	v_mfma_f32_16x16x32_bf16 v[40:43], v[140:143], v[190:193], v[40:43]
	v_mfma_f32_16x16x32_bf16 v[44:47], v[116:119], v[190:193], v[44:47]
	v_mfma_f32_16x16x32_bf16 v[28:31], v[116:119], v[198:201], v[28:31]
	v_mfma_f32_16x16x32_bf16 v[24:27], v[140:143], v[198:201], v[24:27]
	v_mfma_f32_16x16x32_bf16 v[8:11], v[140:143], v[206:209], v[8:11]
	v_mfma_f32_16x16x32_bf16 v[12:15], v[116:119], v[206:209], v[12:15]
	v_mfma_f32_16x16x32_bf16 v[52:55], v[158:161], v[178:181], v[52:55]
	v_mfma_f32_16x16x32_bf16 v[48:51], v[170:173], v[178:181], v[48:51]
	v_mfma_f32_16x16x32_bf16 v[32:35], v[170:173], v[186:189], v[32:35]
	v_mfma_f32_16x16x32_bf16 v[36:39], v[158:161], v[186:189], v[36:39]
	v_mfma_f32_16x16x32_bf16 v[20:23], v[158:161], v[194:197], v[20:23]
	v_mfma_f32_16x16x32_bf16 v[16:19], v[170:173], v[194:197], v[16:19]
	v_mfma_f32_16x16x32_bf16 v[0:3], v[170:173], v[202:205], v[0:3]
	v_mfma_f32_16x16x32_bf16 v[4:7], v[158:161], v[202:205], v[4:7]
	v_mfma_f32_16x16x32_bf16 v[52:55], v[162:165], v[182:185], v[52:55]
	v_mfma_f32_16x16x32_bf16 v[48:51], v[174:177], v[182:185], v[48:51]
	v_mfma_f32_16x16x32_bf16 v[32:35], v[174:177], v[190:193], v[32:35]
	v_mfma_f32_16x16x32_bf16 v[36:39], v[162:165], v[190:193], v[36:39]
	v_mfma_f32_16x16x32_bf16 v[20:23], v[162:165], v[198:201], v[20:23]
	v_mfma_f32_16x16x32_bf16 v[16:19], v[174:177], v[198:201], v[16:19]
	v_mfma_f32_16x16x32_bf16 v[0:3], v[174:177], v[206:209], v[0:3]
	v_mfma_f32_16x16x32_bf16 v[4:7], v[162:165], v[206:209], v[4:7]
	s_barrier
	s_add_i32 s68, s68, 2
	s_add_u32 s80, s80, 0x100
	s_addc_u32 s81, s81, 0
	s_add_u32 s60, s60, 0x100
	s_addc_u32 s61, s61, 0
	s_cmp_gt_u32 s68, 29
	s_cbranch_scc0 .LBB0_297
	s_and_b64 vcc, exec, s[18:19]
	s_cbranch_vccz .LBB0_300
	s_barrier

.LBB0_384:
	s_ashr_i32 s73, s72, 31
	s_lshl_b64 s[74:75], s[72:73], 20
	s_add_u32 s74, s2, s74
	s_addc_u32 s75, s3, s75
	s_and_b64 s[76:77], s[4:5], exec
	s_cselect_b32 s73, s75, s81
	s_cselect_b32 s79, s74, s80
	s_ashr_i32 s23, s22, 31
	s_lshl_b64 s[76:77], s[22:23], 20
	s_add_u32 s76, s14, s76
	s_addc_u32 s77, s15, s77
	s_and_b64 s[84:85], s[4:5], exec
	s_cselect_b32 s23, s77, s83
	s_cselect_b32 s86, s76, s82
	s_add_u32 s80, s80, 0x80080
	s_addc_u32 s81, s81, 0
	s_add_u32 s87, s82, 0x100
	s_addc_u32 s88, s83, 0
	s_mov_b32 s89, -2
	s_add_u32 s67, s80, 0xfff80080
	s_addc_u32 s82, s81, -1
	s_add_i32 s90, 0, 0x10000
	s_cmp_eq_u32 s89, 28
	s_cselect_b32 s85, s73, s82
	s_cselect_b32 s84, s79, s67
	s_cselect_b32 s83, s23, s88
	s_cselect_b32 s82, s86, s87
	s_add_i32 s67, 0, 0x14000
	v_add_u32_e32 v140, s90, v186
	v_add_u32_e32 v156, s67, v186
	ds_read_b128 v[128:131], v140
	ds_read_b128 v[132:135], v140 offset:1024
	ds_read_b128 v[136:139], v140 offset:2048
	ds_read_b128 v[140:143], v140 offset:3072
	ds_read_b128 v[144:147], v156
	ds_read_b128 v[148:151], v156 offset:1024
	ds_read_b128 v[152:155], v156 offset:2048
	ds_read_b128 v[156:159], v156 offset:3072
	v_lshl_add_u64 v[208:209], s[80:81], 0, v[178:179]
	s_add_i32 m0, s29, 0xc000
	ds_read_b128 v[160:163], v187
	ds_read_b128 v[164:167], v187 offset:1024
	ds_read_b128 v[182:185], v187 offset:2048
	ds_read_b128 v[188:191], v187 offset:3072
	ds_read_b128 v[192:195], v187 offset:4096
	ds_read_b128 v[196:199], v187 offset:5120
	ds_read_b128 v[200:203], v187 offset:6144
	ds_read_b128 v[204:207], v187 offset:7168
	global_load_lds_dwordx4 v[208:209], off
	v_lshl_add_u64 v[208:209], s[80:81], 0, v[180:181]
	s_add_i32 m0, s29, 0xe000
	s_nop 0
	global_load_lds_dwordx4 v[208:209], off
	s_waitcnt vmcnt(8)
	s_waitcnt lgkmcnt(0)
	s_barrier
	s_waitcnt lgkmcnt(0)
	v_mfma_f32_16x16x32_bf16 v[124:127], v[128:131], v[160:163], 0
	v_mfma_f32_16x16x32_bf16 v[120:123], v[136:139], v[160:163], 0
	v_mfma_f32_16x16x32_bf16 v[104:107], v[136:139], v[182:185], 0
	v_mfma_f32_16x16x32_bf16 v[108:111], v[128:131], v[182:185], 0
	v_mfma_f32_16x16x32_bf16 v[92:95], v[128:131], v[192:195], 0
	v_mfma_f32_16x16x32_bf16 v[88:91], v[136:139], v[192:195], 0
	v_mfma_f32_16x16x32_bf16 v[72:75], v[136:139], v[200:203], 0
	v_mfma_f32_16x16x32_bf16 v[76:79], v[128:131], v[200:203], 0
	v_mfma_f32_16x16x32_bf16 v[124:127], v[132:135], v[164:167], v[124:127]
	v_mfma_f32_16x16x32_bf16 v[120:123], v[140:143], v[164:167], v[120:123]
	v_mfma_f32_16x16x32_bf16 v[104:107], v[140:143], v[188:191], v[104:107]
	v_mfma_f32_16x16x32_bf16 v[108:111], v[132:135], v[188:191], v[108:111]
	v_mfma_f32_16x16x32_bf16 v[92:95], v[132:135], v[196:199], v[92:95]
	v_mfma_f32_16x16x32_bf16 v[88:91], v[140:143], v[196:199], v[88:91]
	v_mfma_f32_16x16x32_bf16 v[72:75], v[140:143], v[204:207], v[72:75]
	v_mfma_f32_16x16x32_bf16 v[76:79], v[132:135], v[204:207], v[76:79]
	v_mfma_f32_16x16x32_bf16 v[116:119], v[144:147], v[160:163], 0
	v_mfma_f32_16x16x32_bf16 v[112:115], v[152:155], v[160:163], 0
	v_mfma_f32_16x16x32_bf16 v[96:99], v[152:155], v[182:185], 0
	v_mfma_f32_16x16x32_bf16 v[100:103], v[144:147], v[182:185], 0
	v_mfma_f32_16x16x32_bf16 v[84:87], v[144:147], v[192:195], 0
	v_mfma_f32_16x16x32_bf16 v[80:83], v[152:155], v[192:195], 0
	v_mfma_f32_16x16x32_bf16 v[64:67], v[152:155], v[200:203], 0
	v_mfma_f32_16x16x32_bf16 v[68:71], v[144:147], v[200:203], 0
	v_mfma_f32_16x16x32_bf16 v[116:119], v[148:151], v[164:167], v[116:119]
	v_mfma_f32_16x16x32_bf16 v[112:115], v[156:159], v[164:167], v[112:115]
	v_mfma_f32_16x16x32_bf16 v[96:99], v[156:159], v[188:191], v[96:99]
	v_mfma_f32_16x16x32_bf16 v[100:103], v[148:151], v[188:191], v[100:103]
	v_mfma_f32_16x16x32_bf16 v[84:87], v[148:151], v[196:199], v[84:87]
	v_mfma_f32_16x16x32_bf16 v[80:83], v[156:159], v[196:199], v[80:83]
	v_mfma_f32_16x16x32_bf16 v[64:67], v[156:159], v[204:207], v[64:67]
	v_mfma_f32_16x16x32_bf16 v[68:71], v[148:151], v[204:207], v[68:71]
	s_barrier
	s_add_i32 s90, s90, s24
	v_lshl_add_u64 v[208:209], s[82:83], 0, v[172:173]
	s_mov_b32 m0, s90
	ds_read_b128 v[160:163], v187 offset:16384
	ds_read_b128 v[164:167], v187 offset:17408
	ds_read_b128 v[182:185], v187 offset:18432
	ds_read_b128 v[188:191], v187 offset:19456
	ds_read_b128 v[192:195], v187 offset:20480
	ds_read_b128 v[196:199], v187 offset:21504
	ds_read_b128 v[200:203], v187 offset:22528
	ds_read_b128 v[204:207], v187 offset:23552
	global_load_lds_dwordx4 v[208:209], off
	s_add_i32 m0, s90, 0x2000
	s_add_u32 s90, s82, 0x80000
	v_lshl_add_u64 v[210:211], s[82:83], 0, v[168:169]
	s_addc_u32 s91, s83, 0
	s_add_i32 s67, s67, s24
	global_load_lds_dwordx4 v[210:211], off
	v_lshl_add_u64 v[212:213], s[90:91], 0, v[172:173]
	s_mov_b32 m0, s67
	v_lshl_add_u64 v[214:215], s[84:85], 0, v[170:171]
	global_load_lds_dwordx4 v[212:213], off
	v_lshl_add_u64 v[212:213], s[90:91], 0, v[168:169]
	s_add_i32 m0, s67, 0x2000
	s_nop 0
	global_load_lds_dwordx4 v[212:213], off
	v_lshl_add_u64 v[212:213], s[84:85], 0, v[174:175]
	s_mov_b32 m0, s29
	s_nop 0
	global_load_lds_dwordx4 v[212:213], off
	s_mov_b32 m0, s34
	s_nop 0
	global_load_lds_dwordx4 v[214:215], off
	s_waitcnt vmcnt(8)
	s_waitcnt lgkmcnt(0)
	s_barrier
	s_waitcnt lgkmcnt(0)
	v_mfma_f32_16x16x32_bf16 v[60:63], v[128:131], v[160:163], 0
	v_mfma_f32_16x16x32_bf16 v[56:59], v[136:139], v[160:163], 0
	v_mfma_f32_16x16x32_bf16 v[40:43], v[136:139], v[182:185], 0
	v_mfma_f32_16x16x32_bf16 v[44:47], v[128:131], v[182:185], 0
	v_mfma_f32_16x16x32_bf16 v[28:31], v[128:131], v[192:195], 0
	v_mfma_f32_16x16x32_bf16 v[24:27], v[136:139], v[192:195], 0
	v_mfma_f32_16x16x32_bf16 v[8:11], v[136:139], v[200:203], 0
	v_mfma_f32_16x16x32_bf16 v[12:15], v[128:131], v[200:203], 0
	v_mfma_f32_16x16x32_bf16 v[60:63], v[132:135], v[164:167], v[60:63]
	v_mfma_f32_16x16x32_bf16 v[56:59], v[140:143], v[164:167], v[56:59]
	v_mfma_f32_16x16x32_bf16 v[40:43], v[140:143], v[188:191], v[40:43]
	v_mfma_f32_16x16x32_bf16 v[44:47], v[132:135], v[188:191], v[44:47]
	v_mfma_f32_16x16x32_bf16 v[28:31], v[132:135], v[196:199], v[28:31]
	v_mfma_f32_16x16x32_bf16 v[24:27], v[140:143], v[196:199], v[24:27]
	v_mfma_f32_16x16x32_bf16 v[8:11], v[140:143], v[204:207], v[8:11]
	v_mfma_f32_16x16x32_bf16 v[12:15], v[132:135], v[204:207], v[12:15]
	v_mfma_f32_16x16x32_bf16 v[52:55], v[144:147], v[160:163], 0
	v_mfma_f32_16x16x32_bf16 v[48:51], v[152:155], v[160:163], 0
	v_mfma_f32_16x16x32_bf16 v[32:35], v[152:155], v[182:185], 0
	v_mfma_f32_16x16x32_bf16 v[36:39], v[144:147], v[182:185], 0
	v_mfma_f32_16x16x32_bf16 v[20:23], v[144:147], v[192:195], 0
	v_mfma_f32_16x16x32_bf16 v[16:19], v[152:155], v[192:195], 0
	v_mfma_f32_16x16x32_bf16 v[0:3], v[152:155], v[200:203], 0
	v_mfma_f32_16x16x32_bf16 v[4:7], v[144:147], v[200:203], 0
	v_mfma_f32_16x16x32_bf16 v[52:55], v[148:151], v[164:167], v[52:55]
	v_mfma_f32_16x16x32_bf16 v[48:51], v[156:159], v[164:167], v[48:51]
	v_mfma_f32_16x16x32_bf16 v[32:35], v[156:159], v[188:191], v[32:35]
	v_mfma_f32_16x16x32_bf16 v[36:39], v[148:151], v[188:191], v[36:39]
	v_mfma_f32_16x16x32_bf16 v[20:23], v[148:151], v[196:199], v[20:23]
	v_mfma_f32_16x16x32_bf16 v[16:19], v[156:159], v[196:199], v[16:19]
	v_mfma_f32_16x16x32_bf16 v[0:3], v[156:159], v[204:207], v[0:3]
	v_mfma_f32_16x16x32_bf16 v[4:7], v[148:151], v[204:207], v[4:7]
	s_barrier
	s_add_i32 s67, 0, 0x18000
	s_add_i32 s90, 0, 0x1c000
	v_add_u32_e32 v140, s67, v186
	v_add_u32_e32 v156, s90, v186
	ds_read_b128 v[128:131], v140
	ds_read_b128 v[132:135], v140 offset:1024
	ds_read_b128 v[136:139], v140 offset:2048
	ds_read_b128 v[140:143], v140 offset:3072
	ds_read_b128 v[144:147], v156
	ds_read_b128 v[148:151], v156 offset:1024
	ds_read_b128 v[152:155], v156 offset:2048
	ds_read_b128 v[156:159], v156 offset:3072
	s_add_u32 s84, s84, 0x80000
	s_addc_u32 s85, s85, 0
	s_mov_b32 m0, s35
	v_lshl_add_u64 v[218:219], s[84:85], 0, v[174:175]
	ds_read_b128 v[160:163], v187 offset:32768
	ds_read_b128 v[164:167], v187 offset:33792
	ds_read_b128 v[182:185], v187 offset:34816
	ds_read_b128 v[188:191], v187 offset:35840
	ds_read_b128 v[192:195], v187 offset:36864
	ds_read_b128 v[196:199], v187 offset:37888
	ds_read_b128 v[200:203], v187 offset:38912
	ds_read_b128 v[204:207], v187 offset:39936
	global_load_lds_dwordx4 v[218:219], off
	v_lshl_add_u64 v[218:219], s[84:85], 0, v[170:171]
	s_mov_b32 m0, s38
	s_nop 0
	global_load_lds_dwordx4 v[218:219], off
	s_waitcnt vmcnt(8)
	s_waitcnt lgkmcnt(0)
	s_barrier
	s_waitcnt lgkmcnt(0)
	v_mfma_f32_16x16x32_bf16 v[124:127], v[128:131], v[160:163], v[124:127]
	v_mfma_f32_16x16x32_bf16 v[120:123], v[136:139], v[160:163], v[120:123]
	v_mfma_f32_16x16x32_bf16 v[104:107], v[136:139], v[182:185], v[104:107]
	v_mfma_f32_16x16x32_bf16 v[108:111], v[128:131], v[182:185], v[108:111]
	v_mfma_f32_16x16x32_bf16 v[92:95], v[128:131], v[192:195], v[92:95]
	v_mfma_f32_16x16x32_bf16 v[88:91], v[136:139], v[192:195], v[88:91]
	v_mfma_f32_16x16x32_bf16 v[72:75], v[136:139], v[200:203], v[72:75]
	v_mfma_f32_16x16x32_bf16 v[76:79], v[128:131], v[200:203], v[76:79]
	v_mfma_f32_16x16x32_bf16 v[124:127], v[132:135], v[164:167], v[124:127]
	v_mfma_f32_16x16x32_bf16 v[120:123], v[140:143], v[164:167], v[120:123]
	v_mfma_f32_16x16x32_bf16 v[104:107], v[140:143], v[188:191], v[104:107]
	v_mfma_f32_16x16x32_bf16 v[108:111], v[132:135], v[188:191], v[108:111]
	v_mfma_f32_16x16x32_bf16 v[92:95], v[132:135], v[196:199], v[92:95]
	v_mfma_f32_16x16x32_bf16 v[88:91], v[140:143], v[196:199], v[88:91]
	v_mfma_f32_16x16x32_bf16 v[72:75], v[140:143], v[204:207], v[72:75]
	v_mfma_f32_16x16x32_bf16 v[76:79], v[132:135], v[204:207], v[76:79]
	v_mfma_f32_16x16x32_bf16 v[116:119], v[144:147], v[160:163], v[116:119]
	v_mfma_f32_16x16x32_bf16 v[112:115], v[152:155], v[160:163], v[112:115]
	v_mfma_f32_16x16x32_bf16 v[96:99], v[152:155], v[182:185], v[96:99]
	v_mfma_f32_16x16x32_bf16 v[100:103], v[144:147], v[182:185], v[100:103]
	v_mfma_f32_16x16x32_bf16 v[84:87], v[144:147], v[192:195], v[84:87]
	v_mfma_f32_16x16x32_bf16 v[80:83], v[152:155], v[192:195], v[80:83]
	v_mfma_f32_16x16x32_bf16 v[64:67], v[152:155], v[200:203], v[64:67]
	v_mfma_f32_16x16x32_bf16 v[68:71], v[144:147], v[200:203], v[68:71]
	v_mfma_f32_16x16x32_bf16 v[116:119], v[148:151], v[164:167], v[116:119]
	v_mfma_f32_16x16x32_bf16 v[112:115], v[156:159], v[164:167], v[112:115]
	v_mfma_f32_16x16x32_bf16 v[96:99], v[156:159], v[188:191], v[96:99]
	v_mfma_f32_16x16x32_bf16 v[100:103], v[148:151], v[188:191], v[100:103]
	v_mfma_f32_16x16x32_bf16 v[84:87], v[148:151], v[196:199], v[84:87]
	v_mfma_f32_16x16x32_bf16 v[80:83], v[156:159], v[196:199], v[80:83]
	v_mfma_f32_16x16x32_bf16 v[64:67], v[156:159], v[204:207], v[64:67]
	v_mfma_f32_16x16x32_bf16 v[68:71], v[148:151], v[204:207], v[68:71]
	s_barrier
	s_add_i32 s67, s67, s24
	v_lshl_add_u64 v[208:209], v[208:209], 0, s[30:31]
	s_mov_b32 m0, s67
	ds_read_b128 v[160:163], v187 offset:49152
	ds_read_b128 v[164:167], v187 offset:50176
	ds_read_b128 v[182:185], v187 offset:51200
	ds_read_b128 v[188:191], v187 offset:52224
	ds_read_b128 v[192:195], v187 offset:53248
	ds_read_b128 v[196:199], v187 offset:54272
	ds_read_b128 v[200:203], v187 offset:55296
	ds_read_b128 v[204:207], v187 offset:56320
	global_load_lds_dwordx4 v[208:209], off
	s_add_i32 m0, s67, 0x2000
	s_add_u32 s82, s82, 0x80080
	v_lshl_add_u64 v[208:209], v[210:211], 0, s[30:31]
	s_addc_u32 s83, s83, 0
	s_add_i32 s67, s90, s24
	global_load_lds_dwordx4 v[208:209], off
	v_lshl_add_u64 v[208:209], s[82:83], 0, v[172:173]
	s_mov_b32 m0, s67
	s_nop 0
	global_load_lds_dwordx4 v[208:209], off
	v_lshl_add_u64 v[208:209], s[82:83], 0, v[168:169]
	s_add_i32 m0, s67, 0x2000
	s_nop 0
	global_load_lds_dwordx4 v[208:209], off
	v_lshl_add_u64 v[208:209], v[212:213], 0, s[30:31]
	s_mov_b32 m0, s54
	s_nop 0
	global_load_lds_dwordx4 v[208:209], off
	v_lshl_add_u64 v[208:209], v[214:215], 0, s[30:31]
	s_mov_b32 m0, s55
	s_nop 0
	global_load_lds_dwordx4 v[208:209], off
	s_waitcnt vmcnt(8)
	s_waitcnt lgkmcnt(0)
	s_barrier
	s_waitcnt lgkmcnt(0)
	v_mfma_f32_16x16x32_bf16 v[60:63], v[128:131], v[160:163], v[60:63]
	v_mfma_f32_16x16x32_bf16 v[56:59], v[136:139], v[160:163], v[56:59]
	v_mfma_f32_16x16x32_bf16 v[40:43], v[136:139], v[182:185], v[40:43]
	v_mfma_f32_16x16x32_bf16 v[44:47], v[128:131], v[182:185], v[44:47]
	v_mfma_f32_16x16x32_bf16 v[28:31], v[128:131], v[192:195], v[28:31]
	v_mfma_f32_16x16x32_bf16 v[24:27], v[136:139], v[192:195], v[24:27]
	v_mfma_f32_16x16x32_bf16 v[8:11], v[136:139], v[200:203], v[8:11]
	v_mfma_f32_16x16x32_bf16 v[12:15], v[128:131], v[200:203], v[12:15]
	v_mfma_f32_16x16x32_bf16 v[60:63], v[132:135], v[164:167], v[60:63]
	v_mfma_f32_16x16x32_bf16 v[56:59], v[140:143], v[164:167], v[56:59]
	v_mfma_f32_16x16x32_bf16 v[40:43], v[140:143], v[188:191], v[40:43]
	v_mfma_f32_16x16x32_bf16 v[44:47], v[132:135], v[188:191], v[44:47]
	v_mfma_f32_16x16x32_bf16 v[28:31], v[132:135], v[196:199], v[28:31]
	v_mfma_f32_16x16x32_bf16 v[24:27], v[140:143], v[196:199], v[24:27]
	v_mfma_f32_16x16x32_bf16 v[8:11], v[140:143], v[204:207], v[8:11]
	v_mfma_f32_16x16x32_bf16 v[12:15], v[132:135], v[204:207], v[12:15]
	v_mfma_f32_16x16x32_bf16 v[52:55], v[144:147], v[160:163], v[52:55]
	v_mfma_f32_16x16x32_bf16 v[48:51], v[152:155], v[160:163], v[48:51]
	v_mfma_f32_16x16x32_bf16 v[32:35], v[152:155], v[182:185], v[32:35]
	v_mfma_f32_16x16x32_bf16 v[36:39], v[144:147], v[182:185], v[36:39]
	v_mfma_f32_16x16x32_bf16 v[20:23], v[144:147], v[192:195], v[20:23]
	v_mfma_f32_16x16x32_bf16 v[16:19], v[152:155], v[192:195], v[16:19]
	v_mfma_f32_16x16x32_bf16 v[0:3], v[152:155], v[200:203], v[0:3]
	v_mfma_f32_16x16x32_bf16 v[4:7], v[144:147], v[200:203], v[4:7]
	v_mfma_f32_16x16x32_bf16 v[52:55], v[148:151], v[164:167], v[52:55]
	v_mfma_f32_16x16x32_bf16 v[48:51], v[156:159], v[164:167], v[48:51]
	v_mfma_f32_16x16x32_bf16 v[32:35], v[156:159], v[188:191], v[32:35]
	v_mfma_f32_16x16x32_bf16 v[36:39], v[148:151], v[188:191], v[36:39]
	v_mfma_f32_16x16x32_bf16 v[20:23], v[148:151], v[196:199], v[20:23]
	v_mfma_f32_16x16x32_bf16 v[16:19], v[156:159], v[196:199], v[16:19]
	v_mfma_f32_16x16x32_bf16 v[0:3], v[156:159], v[204:207], v[0:3]
	v_mfma_f32_16x16x32_bf16 v[4:7], v[148:151], v[204:207], v[4:7]
	s_barrier
	s_add_i32 s89, s89, 2
	s_add_u32 s80, s80, 0x100
	s_addc_u32 s81, s81, 0
	s_add_u32 s87, s87, 0x100
	s_addc_u32 s88, s88, 0
.LBB0_385:
	s_add_u32 s67, s80, 0xfff80080
	s_addc_u32 s82, s81, -1
	s_add_i32 s90, 0, 0x10000
	s_cmp_eq_u32 s89, 28
	s_cselect_b32 s85, s73, s82
	s_cselect_b32 s84, s79, s67
	s_cselect_b32 s83, s23, s88
	s_cselect_b32 s82, s86, s87
	s_add_i32 s67, 0, 0x14000
	v_add_u32_e32 v140, s90, v186
	v_add_u32_e32 v156, s67, v186
	ds_read_b128 v[128:131], v140
	ds_read_b128 v[132:135], v140 offset:1024
	ds_read_b128 v[136:139], v140 offset:2048
	ds_read_b128 v[140:143], v140 offset:3072
	ds_read_b128 v[144:147], v156
	ds_read_b128 v[148:151], v156 offset:1024
	ds_read_b128 v[152:155], v156 offset:2048
	ds_read_b128 v[156:159], v156 offset:3072
	v_lshl_add_u64 v[208:209], s[80:81], 0, v[178:179]
	s_add_i32 m0, s29, 0xc000
	ds_read_b128 v[160:163], v187
	ds_read_b128 v[164:167], v187 offset:1024
	ds_read_b128 v[182:185], v187 offset:2048
	ds_read_b128 v[188:191], v187 offset:3072
	ds_read_b128 v[192:195], v187 offset:4096
	ds_read_b128 v[196:199], v187 offset:5120
	ds_read_b128 v[200:203], v187 offset:6144
	ds_read_b128 v[204:207], v187 offset:7168
	global_load_lds_dwordx4 v[208:209], off
	v_lshl_add_u64 v[208:209], s[80:81], 0, v[180:181]
	s_add_i32 m0, s29, 0xe000
	s_nop 0
	global_load_lds_dwordx4 v[208:209], off
	s_waitcnt vmcnt(8)
	s_waitcnt lgkmcnt(0)
	s_barrier
	s_waitcnt lgkmcnt(0)
	v_mfma_f32_16x16x32_bf16 v[124:127], v[128:131], v[160:163], v[124:127]
	v_mfma_f32_16x16x32_bf16 v[120:123], v[136:139], v[160:163], v[120:123]
	v_mfma_f32_16x16x32_bf16 v[104:107], v[136:139], v[182:185], v[104:107]
	v_mfma_f32_16x16x32_bf16 v[108:111], v[128:131], v[182:185], v[108:111]
	v_mfma_f32_16x16x32_bf16 v[92:95], v[128:131], v[192:195], v[92:95]
	v_mfma_f32_16x16x32_bf16 v[88:91], v[136:139], v[192:195], v[88:91]
	v_mfma_f32_16x16x32_bf16 v[72:75], v[136:139], v[200:203], v[72:75]
	v_mfma_f32_16x16x32_bf16 v[76:79], v[128:131], v[200:203], v[76:79]
	v_mfma_f32_16x16x32_bf16 v[124:127], v[132:135], v[164:167], v[124:127]
	v_mfma_f32_16x16x32_bf16 v[120:123], v[140:143], v[164:167], v[120:123]
	v_mfma_f32_16x16x32_bf16 v[104:107], v[140:143], v[188:191], v[104:107]
	v_mfma_f32_16x16x32_bf16 v[108:111], v[132:135], v[188:191], v[108:111]
	v_mfma_f32_16x16x32_bf16 v[92:95], v[132:135], v[196:199], v[92:95]
	v_mfma_f32_16x16x32_bf16 v[88:91], v[140:143], v[196:199], v[88:91]
	v_mfma_f32_16x16x32_bf16 v[72:75], v[140:143], v[204:207], v[72:75]
	v_mfma_f32_16x16x32_bf16 v[76:79], v[132:135], v[204:207], v[76:79]
	v_mfma_f32_16x16x32_bf16 v[116:119], v[144:147], v[160:163], v[116:119]
	v_mfma_f32_16x16x32_bf16 v[112:115], v[152:155], v[160:163], v[112:115]
	v_mfma_f32_16x16x32_bf16 v[96:99], v[152:155], v[182:185], v[96:99]
	v_mfma_f32_16x16x32_bf16 v[100:103], v[144:147], v[182:185], v[100:103]
	v_mfma_f32_16x16x32_bf16 v[84:87], v[144:147], v[192:195], v[84:87]
	v_mfma_f32_16x16x32_bf16 v[80:83], v[152:155], v[192:195], v[80:83]
	v_mfma_f32_16x16x32_bf16 v[64:67], v[152:155], v[200:203], v[64:67]
	v_mfma_f32_16x16x32_bf16 v[68:71], v[144:147], v[200:203], v[68:71]
	v_mfma_f32_16x16x32_bf16 v[116:119], v[148:151], v[164:167], v[116:119]
	v_mfma_f32_16x16x32_bf16 v[112:115], v[156:159], v[164:167], v[112:115]
	v_mfma_f32_16x16x32_bf16 v[96:99], v[156:159], v[188:191], v[96:99]
	v_mfma_f32_16x16x32_bf16 v[100:103], v[148:151], v[188:191], v[100:103]
	v_mfma_f32_16x16x32_bf16 v[84:87], v[148:151], v[196:199], v[84:87]
	v_mfma_f32_16x16x32_bf16 v[80:83], v[156:159], v[196:199], v[80:83]
	v_mfma_f32_16x16x32_bf16 v[64:67], v[156:159], v[204:207], v[64:67]
	v_mfma_f32_16x16x32_bf16 v[68:71], v[148:151], v[204:207], v[68:71]
	s_barrier
	s_add_i32 s90, s90, s24
	v_lshl_add_u64 v[208:209], s[82:83], 0, v[172:173]
	s_mov_b32 m0, s90
	ds_read_b128 v[160:163], v187 offset:16384
	ds_read_b128 v[164:167], v187 offset:17408
	ds_read_b128 v[182:185], v187 offset:18432
	ds_read_b128 v[188:191], v187 offset:19456
	ds_read_b128 v[192:195], v187 offset:20480
	ds_read_b128 v[196:199], v187 offset:21504
	ds_read_b128 v[200:203], v187 offset:22528
	ds_read_b128 v[204:207], v187 offset:23552
	global_load_lds_dwordx4 v[208:209], off
	s_add_i32 m0, s90, 0x2000
	s_add_u32 s90, s82, 0x80000
	v_lshl_add_u64 v[210:211], s[82:83], 0, v[168:169]
	s_addc_u32 s91, s83, 0
	s_add_i32 s67, s67, s24
	global_load_lds_dwordx4 v[210:211], off
	v_lshl_add_u64 v[212:213], s[90:91], 0, v[172:173]
	s_mov_b32 m0, s67
	v_lshl_add_u64 v[214:215], s[84:85], 0, v[170:171]
	global_load_lds_dwordx4 v[212:213], off
	v_lshl_add_u64 v[212:213], s[90:91], 0, v[168:169]
	s_add_i32 m0, s67, 0x2000
	s_nop 0
	global_load_lds_dwordx4 v[212:213], off
	v_lshl_add_u64 v[212:213], s[84:85], 0, v[174:175]
	s_mov_b32 m0, s29
	s_nop 0
	global_load_lds_dwordx4 v[212:213], off
	s_mov_b32 m0, s34
	s_nop 0
	global_load_lds_dwordx4 v[214:215], off
	s_waitcnt vmcnt(8)
	s_waitcnt lgkmcnt(0)
	s_barrier
	s_waitcnt lgkmcnt(0)
	v_mfma_f32_16x16x32_bf16 v[60:63], v[128:131], v[160:163], v[60:63]
	v_mfma_f32_16x16x32_bf16 v[56:59], v[136:139], v[160:163], v[56:59]
	v_mfma_f32_16x16x32_bf16 v[40:43], v[136:139], v[182:185], v[40:43]
	v_mfma_f32_16x16x32_bf16 v[44:47], v[128:131], v[182:185], v[44:47]
	v_mfma_f32_16x16x32_bf16 v[28:31], v[128:131], v[192:195], v[28:31]
	v_mfma_f32_16x16x32_bf16 v[24:27], v[136:139], v[192:195], v[24:27]
	v_mfma_f32_16x16x32_bf16 v[8:11], v[136:139], v[200:203], v[8:11]
	v_mfma_f32_16x16x32_bf16 v[12:15], v[128:131], v[200:203], v[12:15]
	v_mfma_f32_16x16x32_bf16 v[60:63], v[132:135], v[164:167], v[60:63]
	v_mfma_f32_16x16x32_bf16 v[56:59], v[140:143], v[164:167], v[56:59]
	v_mfma_f32_16x16x32_bf16 v[40:43], v[140:143], v[188:191], v[40:43]
	v_mfma_f32_16x16x32_bf16 v[44:47], v[132:135], v[188:191], v[44:47]
	v_mfma_f32_16x16x32_bf16 v[28:31], v[132:135], v[196:199], v[28:31]
	v_mfma_f32_16x16x32_bf16 v[24:27], v[140:143], v[196:199], v[24:27]
	v_mfma_f32_16x16x32_bf16 v[8:11], v[140:143], v[204:207], v[8:11]
	v_mfma_f32_16x16x32_bf16 v[12:15], v[132:135], v[204:207], v[12:15]
	v_mfma_f32_16x16x32_bf16 v[52:55], v[144:147], v[160:163], v[52:55]
	v_mfma_f32_16x16x32_bf16 v[48:51], v[152:155], v[160:163], v[48:51]
	v_mfma_f32_16x16x32_bf16 v[32:35], v[152:155], v[182:185], v[32:35]
	v_mfma_f32_16x16x32_bf16 v[36:39], v[144:147], v[182:185], v[36:39]
	v_mfma_f32_16x16x32_bf16 v[20:23], v[144:147], v[192:195], v[20:23]
	v_mfma_f32_16x16x32_bf16 v[16:19], v[152:155], v[192:195], v[16:19]
	v_mfma_f32_16x16x32_bf16 v[0:3], v[152:155], v[200:203], v[0:3]
	v_mfma_f32_16x16x32_bf16 v[4:7], v[144:147], v[200:203], v[4:7]
	v_mfma_f32_16x16x32_bf16 v[52:55], v[148:151], v[164:167], v[52:55]
	v_mfma_f32_16x16x32_bf16 v[48:51], v[156:159], v[164:167], v[48:51]
	v_mfma_f32_16x16x32_bf16 v[32:35], v[156:159], v[188:191], v[32:35]
	v_mfma_f32_16x16x32_bf16 v[36:39], v[148:151], v[188:191], v[36:39]
	v_mfma_f32_16x16x32_bf16 v[20:23], v[148:151], v[196:199], v[20:23]
	v_mfma_f32_16x16x32_bf16 v[16:19], v[156:159], v[196:199], v[16:19]
	v_mfma_f32_16x16x32_bf16 v[0:3], v[156:159], v[204:207], v[0:3]
	v_mfma_f32_16x16x32_bf16 v[4:7], v[148:151], v[204:207], v[4:7]
	s_barrier
	s_add_i32 s67, 0, 0x18000
	s_add_i32 s90, 0, 0x1c000
	v_add_u32_e32 v140, s67, v186
	v_add_u32_e32 v156, s90, v186
	ds_read_b128 v[128:131], v140
	ds_read_b128 v[132:135], v140 offset:1024
	ds_read_b128 v[136:139], v140 offset:2048
	ds_read_b128 v[140:143], v140 offset:3072
	ds_read_b128 v[144:147], v156
	ds_read_b128 v[148:151], v156 offset:1024
	ds_read_b128 v[152:155], v156 offset:2048
	ds_read_b128 v[156:159], v156 offset:3072
	s_add_u32 s84, s84, 0x80000
	s_addc_u32 s85, s85, 0
	s_mov_b32 m0, s35
	v_lshl_add_u64 v[218:219], s[84:85], 0, v[174:175]
	ds_read_b128 v[160:163], v187 offset:32768
	ds_read_b128 v[164:167], v187 offset:33792
	ds_read_b128 v[182:185], v187 offset:34816
	ds_read_b128 v[188:191], v187 offset:35840
	ds_read_b128 v[192:195], v187 offset:36864
	ds_read_b128 v[196:199], v187 offset:37888
	ds_read_b128 v[200:203], v187 offset:38912
	ds_read_b128 v[204:207], v187 offset:39936
	global_load_lds_dwordx4 v[218:219], off
	v_lshl_add_u64 v[218:219], s[84:85], 0, v[170:171]
	s_mov_b32 m0, s38
	s_nop 0
	global_load_lds_dwordx4 v[218:219], off
	s_waitcnt vmcnt(8)
	s_waitcnt lgkmcnt(0)
	s_barrier
	s_waitcnt lgkmcnt(0)
	v_mfma_f32_16x16x32_bf16 v[124:127], v[128:131], v[160:163], v[124:127]
	v_mfma_f32_16x16x32_bf16 v[120:123], v[136:139], v[160:163], v[120:123]
	v_mfma_f32_16x16x32_bf16 v[104:107], v[136:139], v[182:185], v[104:107]
	v_mfma_f32_16x16x32_bf16 v[108:111], v[128:131], v[182:185], v[108:111]
	v_mfma_f32_16x16x32_bf16 v[92:95], v[128:131], v[192:195], v[92:95]
	v_mfma_f32_16x16x32_bf16 v[88:91], v[136:139], v[192:195], v[88:91]
	v_mfma_f32_16x16x32_bf16 v[72:75], v[136:139], v[200:203], v[72:75]
	v_mfma_f32_16x16x32_bf16 v[76:79], v[128:131], v[200:203], v[76:79]
	v_mfma_f32_16x16x32_bf16 v[124:127], v[132:135], v[164:167], v[124:127]
	v_mfma_f32_16x16x32_bf16 v[120:123], v[140:143], v[164:167], v[120:123]
	v_mfma_f32_16x16x32_bf16 v[104:107], v[140:143], v[188:191], v[104:107]
	v_mfma_f32_16x16x32_bf16 v[108:111], v[132:135], v[188:191], v[108:111]
	v_mfma_f32_16x16x32_bf16 v[92:95], v[132:135], v[196:199], v[92:95]
	v_mfma_f32_16x16x32_bf16 v[88:91], v[140:143], v[196:199], v[88:91]
	v_mfma_f32_16x16x32_bf16 v[72:75], v[140:143], v[204:207], v[72:75]
	v_mfma_f32_16x16x32_bf16 v[76:79], v[132:135], v[204:207], v[76:79]
	v_mfma_f32_16x16x32_bf16 v[116:119], v[144:147], v[160:163], v[116:119]
	v_mfma_f32_16x16x32_bf16 v[112:115], v[152:155], v[160:163], v[112:115]
	v_mfma_f32_16x16x32_bf16 v[96:99], v[152:155], v[182:185], v[96:99]
	v_mfma_f32_16x16x32_bf16 v[100:103], v[144:147], v[182:185], v[100:103]
	v_mfma_f32_16x16x32_bf16 v[84:87], v[144:147], v[192:195], v[84:87]
	v_mfma_f32_16x16x32_bf16 v[80:83], v[152:155], v[192:195], v[80:83]
	v_mfma_f32_16x16x32_bf16 v[64:67], v[152:155], v[200:203], v[64:67]
	v_mfma_f32_16x16x32_bf16 v[68:71], v[144:147], v[200:203], v[68:71]
	v_mfma_f32_16x16x32_bf16 v[116:119], v[148:151], v[164:167], v[116:119]
	v_mfma_f32_16x16x32_bf16 v[112:115], v[156:159], v[164:167], v[112:115]
	v_mfma_f32_16x16x32_bf16 v[96:99], v[156:159], v[188:191], v[96:99]
	v_mfma_f32_16x16x32_bf16 v[100:103], v[148:151], v[188:191], v[100:103]
	v_mfma_f32_16x16x32_bf16 v[84:87], v[148:151], v[196:199], v[84:87]
	v_mfma_f32_16x16x32_bf16 v[80:83], v[156:159], v[196:199], v[80:83]
	v_mfma_f32_16x16x32_bf16 v[64:67], v[156:159], v[204:207], v[64:67]
	v_mfma_f32_16x16x32_bf16 v[68:71], v[148:151], v[204:207], v[68:71]
	s_barrier
	s_add_i32 s67, s67, s24
	v_lshl_add_u64 v[208:209], v[208:209], 0, s[30:31]
	s_mov_b32 m0, s67
	ds_read_b128 v[160:163], v187 offset:49152
	ds_read_b128 v[164:167], v187 offset:50176
	ds_read_b128 v[182:185], v187 offset:51200
	ds_read_b128 v[188:191], v187 offset:52224
	ds_read_b128 v[192:195], v187 offset:53248
	ds_read_b128 v[196:199], v187 offset:54272
	ds_read_b128 v[200:203], v187 offset:55296
	ds_read_b128 v[204:207], v187 offset:56320
	global_load_lds_dwordx4 v[208:209], off
	s_add_i32 m0, s67, 0x2000
	s_add_u32 s82, s82, 0x80080
	v_lshl_add_u64 v[208:209], v[210:211], 0, s[30:31]
	s_addc_u32 s83, s83, 0
	s_add_i32 s67, s90, s24
	global_load_lds_dwordx4 v[208:209], off
	v_lshl_add_u64 v[208:209], s[82:83], 0, v[172:173]
	s_mov_b32 m0, s67
	s_nop 0
	global_load_lds_dwordx4 v[208:209], off
	v_lshl_add_u64 v[208:209], s[82:83], 0, v[168:169]
	s_add_i32 m0, s67, 0x2000
	s_nop 0
	global_load_lds_dwordx4 v[208:209], off
	v_lshl_add_u64 v[208:209], v[212:213], 0, s[30:31]
	s_mov_b32 m0, s54
	s_nop 0
	global_load_lds_dwordx4 v[208:209], off
	v_lshl_add_u64 v[208:209], v[214:215], 0, s[30:31]
	s_mov_b32 m0, s55
	s_nop 0
	global_load_lds_dwordx4 v[208:209], off
	s_waitcnt vmcnt(8)
	s_waitcnt lgkmcnt(0)
	s_barrier
	s_waitcnt lgkmcnt(0)
	v_mfma_f32_16x16x32_bf16 v[60:63], v[128:131], v[160:163], v[60:63]
	v_mfma_f32_16x16x32_bf16 v[56:59], v[136:139], v[160:163], v[56:59]
	v_mfma_f32_16x16x32_bf16 v[40:43], v[136:139], v[182:185], v[40:43]
	v_mfma_f32_16x16x32_bf16 v[44:47], v[128:131], v[182:185], v[44:47]
	v_mfma_f32_16x16x32_bf16 v[28:31], v[128:131], v[192:195], v[28:31]
	v_mfma_f32_16x16x32_bf16 v[24:27], v[136:139], v[192:195], v[24:27]
	v_mfma_f32_16x16x32_bf16 v[8:11], v[136:139], v[200:203], v[8:11]
	v_mfma_f32_16x16x32_bf16 v[12:15], v[128:131], v[200:203], v[12:15]
	v_mfma_f32_16x16x32_bf16 v[60:63], v[132:135], v[164:167], v[60:63]
	v_mfma_f32_16x16x32_bf16 v[56:59], v[140:143], v[164:167], v[56:59]
	v_mfma_f32_16x16x32_bf16 v[40:43], v[140:143], v[188:191], v[40:43]
	v_mfma_f32_16x16x32_bf16 v[44:47], v[132:135], v[188:191], v[44:47]
	v_mfma_f32_16x16x32_bf16 v[28:31], v[132:135], v[196:199], v[28:31]
	v_mfma_f32_16x16x32_bf16 v[24:27], v[140:143], v[196:199], v[24:27]
	v_mfma_f32_16x16x32_bf16 v[8:11], v[140:143], v[204:207], v[8:11]
	v_mfma_f32_16x16x32_bf16 v[12:15], v[132:135], v[204:207], v[12:15]
	v_mfma_f32_16x16x32_bf16 v[52:55], v[144:147], v[160:163], v[52:55]
	v_mfma_f32_16x16x32_bf16 v[48:51], v[152:155], v[160:163], v[48:51]
	v_mfma_f32_16x16x32_bf16 v[32:35], v[152:155], v[182:185], v[32:35]
	v_mfma_f32_16x16x32_bf16 v[36:39], v[144:147], v[182:185], v[36:39]
	v_mfma_f32_16x16x32_bf16 v[20:23], v[144:147], v[192:195], v[20:23]
	v_mfma_f32_16x16x32_bf16 v[16:19], v[152:155], v[192:195], v[16:19]
	v_mfma_f32_16x16x32_bf16 v[0:3], v[152:155], v[200:203], v[0:3]
	v_mfma_f32_16x16x32_bf16 v[4:7], v[144:147], v[200:203], v[4:7]
	v_mfma_f32_16x16x32_bf16 v[52:55], v[148:151], v[164:167], v[52:55]
	v_mfma_f32_16x16x32_bf16 v[48:51], v[156:159], v[164:167], v[48:51]
	v_mfma_f32_16x16x32_bf16 v[32:35], v[156:159], v[188:191], v[32:35]
	v_mfma_f32_16x16x32_bf16 v[36:39], v[148:151], v[188:191], v[36:39]
	v_mfma_f32_16x16x32_bf16 v[20:23], v[148:151], v[196:199], v[20:23]
	v_mfma_f32_16x16x32_bf16 v[16:19], v[156:159], v[196:199], v[16:19]
	v_mfma_f32_16x16x32_bf16 v[0:3], v[156:159], v[204:207], v[0:3]
	v_mfma_f32_16x16x32_bf16 v[4:7], v[148:151], v[204:207], v[4:7]
	s_barrier
	s_add_i32 s89, s89, 2
	s_add_u32 s80, s80, 0x100
	s_addc_u32 s81, s81, 0
	s_add_u32 s87, s87, 0x100
	s_addc_u32 s88, s88, 0
	s_cmp_gt_u32 s89, 29
	s_cbranch_scc0 .LBB0_385
	s_and_b64 vcc, exec, s[18:19]
	s_cbranch_vccz .LBB0_388
	s_barrier

.LBB0_594:
	s_ashr_i32 s81, s80, 31
	s_lshl_b64 s[84:85], s[80:81], 20
	s_add_u32 s84, s29, s84
	s_addc_u32 s85, s34, s85
	s_and_b64 s[86:87], s[82:83], exec
	s_cselect_b32 s81, s85, s95
	s_cselect_b32 vcc_lo, s84, s94
	s_ashr_i32 s79, s78, 31
	s_lshl_b64 s[86:87], s[78:79], 20
	s_add_u32 s86, s35, s86
	s_addc_u32 s87, s38, s87
	s_and_b64 s[2:3], s[82:83], exec
	s_cselect_b32 s79, s87, s93
	s_cselect_b32 vcc_hi, s86, s92
	s_lshl_b32 s88, s88, 8
	s_ashr_i32 s89, s88, 31
	s_lshl_b64 s[2:3], s[88:89], 2
	s_add_u32 s2, s90, s2
	s_addc_u32 s3, s91, s3
	s_add_i32 m0, s14, s41
	s_add_u32 s90, s94, 0x80080
	global_load_lds_dwordx4 v239, s[2:3]
	s_addc_u32 s91, s95, 0
	s_add_u32 s89, s92, 0x100
	s_addc_u32 s14, s93, 0
	s_mov_b32 s20, -2
	s_waitcnt vmcnt(0)
	s_add_u32 s2, s90, 0xfff80080
	s_addc_u32 s3, s91, -1
	s_add_i32 s67, 0, 0x10000
	s_cmp_eq_u32 s20, 28
	s_cselect_b32 s95, s81, s3
	s_cselect_b32 s94, vcc_lo, s2
	s_cselect_b32 s93, s79, s14
	s_cselect_b32 s92, vcc_hi, s89
	s_add_i32 s76, 0, 0x14000
	v_add_u32_e32 v96, s67, v238
	v_add_u32_e32 v140, s76, v238
	ds_read_b128 v[64:67], v96
	ds_read_b128 v[72:75], v96 offset:1024
	ds_read_b128 v[88:91], v96 offset:2048
	ds_read_b128 v[96:99], v96 offset:3072
	ds_read_b128 v[108:111], v140
	ds_read_b128 v[116:119], v140 offset:1024
	ds_read_b128 v[128:131], v140 offset:2048
	ds_read_b128 v[140:143], v140 offset:3072
	v_lshl_add_u64 v[192:193], s[90:91], 0, v[230:231]
	s_add_i32 m0, s39, 0xc000
	ds_read_b128 v[152:155], v240
	ds_read_b128 v[156:159], v240 offset:1024
	ds_read_b128 v[160:163], v240 offset:2048
	ds_read_b128 v[164:167], v240 offset:3072
	ds_read_b128 v[168:171], v240 offset:4096
	ds_read_b128 v[180:183], v240 offset:5120
	ds_read_b128 v[184:187], v240 offset:6144
	ds_read_b128 v[188:191], v240 offset:7168
	global_load_lds_dwordx4 v[192:193], off
	v_lshl_add_u64 v[192:193], s[90:91], 0, v[232:233]
	s_add_i32 m0, s39, 0xe000
	s_nop 0
	global_load_lds_dwordx4 v[192:193], off
	s_waitcnt vmcnt(8)
	s_waitcnt lgkmcnt(0)
	s_barrier
	s_waitcnt lgkmcnt(0)
	v_mfma_f32_16x16x32_bf16 v[176:179], v[64:67], v[152:155], 0
	v_mfma_f32_16x16x32_bf16 v[172:175], v[88:91], v[152:155], 0
	v_mfma_f32_16x16x32_bf16 v[132:135], v[88:91], v[160:163], 0
	v_mfma_f32_16x16x32_bf16 v[136:139], v[64:67], v[160:163], 0
	v_mfma_f32_16x16x32_bf16 v[112:115], v[64:67], v[168:171], 0
	v_mfma_f32_16x16x32_bf16 v[104:107], v[88:91], v[168:171], 0
	v_mfma_f32_16x16x32_bf16 v[80:83], v[88:91], v[184:187], 0
	v_mfma_f32_16x16x32_bf16 v[84:87], v[64:67], v[184:187], 0
	v_mfma_f32_16x16x32_bf16 v[176:179], v[72:75], v[156:159], v[176:179]
	v_mfma_f32_16x16x32_bf16 v[172:175], v[96:99], v[156:159], v[172:175]
	v_mfma_f32_16x16x32_bf16 v[132:135], v[96:99], v[164:167], v[132:135]
	v_mfma_f32_16x16x32_bf16 v[136:139], v[72:75], v[164:167], v[136:139]
	v_mfma_f32_16x16x32_bf16 v[112:115], v[72:75], v[180:183], v[112:115]
	v_mfma_f32_16x16x32_bf16 v[104:107], v[96:99], v[180:183], v[104:107]
	v_mfma_f32_16x16x32_bf16 v[80:83], v[96:99], v[188:191], v[80:83]
	v_mfma_f32_16x16x32_bf16 v[84:87], v[72:75], v[188:191], v[84:87]
	v_mfma_f32_16x16x32_bf16 v[148:151], v[108:111], v[152:155], 0
	v_mfma_f32_16x16x32_bf16 v[144:147], v[128:131], v[152:155], 0
	v_mfma_f32_16x16x32_bf16 v[120:123], v[128:131], v[160:163], 0
	v_mfma_f32_16x16x32_bf16 v[124:127], v[108:111], v[160:163], 0
	v_mfma_f32_16x16x32_bf16 v[100:103], v[108:111], v[168:171], 0
	v_mfma_f32_16x16x32_bf16 v[92:95], v[128:131], v[168:171], 0
	v_mfma_f32_16x16x32_bf16 v[68:71], v[128:131], v[184:187], 0
	v_mfma_f32_16x16x32_bf16 v[76:79], v[108:111], v[184:187], 0
	v_mfma_f32_16x16x32_bf16 v[148:151], v[116:119], v[156:159], v[148:151]
	v_mfma_f32_16x16x32_bf16 v[144:147], v[140:143], v[156:159], v[144:147]
	v_mfma_f32_16x16x32_bf16 v[120:123], v[140:143], v[164:167], v[120:123]
	v_mfma_f32_16x16x32_bf16 v[124:127], v[116:119], v[164:167], v[124:127]
	v_mfma_f32_16x16x32_bf16 v[100:103], v[116:119], v[180:183], v[100:103]
	v_mfma_f32_16x16x32_bf16 v[92:95], v[140:143], v[180:183], v[92:95]
	v_mfma_f32_16x16x32_bf16 v[68:71], v[140:143], v[188:191], v[68:71]
	v_mfma_f32_16x16x32_bf16 v[76:79], v[116:119], v[188:191], v[76:79]
	s_barrier
	s_add_i32 s2, s67, s28
	v_lshl_add_u64 v[192:193], s[92:93], 0, v[216:217]
	s_mov_b32 m0, s2
	ds_read_b128 v[152:155], v240 offset:16384
	ds_read_b128 v[156:159], v240 offset:17408
	ds_read_b128 v[160:163], v240 offset:18432
	ds_read_b128 v[164:167], v240 offset:19456
	ds_read_b128 v[168:171], v240 offset:20480
	ds_read_b128 v[180:183], v240 offset:21504
	ds_read_b128 v[184:187], v240 offset:22528
	ds_read_b128 v[188:191], v240 offset:23552
	global_load_lds_dwordx4 v[192:193], off
	s_add_i32 m0, s2, 0x2000
	s_add_u32 s2, s92, 0x80000
	v_lshl_add_u64 v[194:195], s[92:93], 0, v[228:229]
	s_addc_u32 s3, s93, 0
	s_add_i32 s67, s76, s28
	global_load_lds_dwordx4 v[194:195], off
	v_lshl_add_u64 v[196:197], s[2:3], 0, v[216:217]
	s_mov_b32 m0, s67
	v_lshl_add_u64 v[198:199], s[94:95], 0, v[226:227]
	global_load_lds_dwordx4 v[196:197], off
	v_lshl_add_u64 v[196:197], s[2:3], 0, v[228:229]
	s_add_i32 m0, s67, 0x2000
	s_nop 0
	global_load_lds_dwordx4 v[196:197], off
	v_lshl_add_u64 v[196:197], s[94:95], 0, v[224:225]
	s_mov_b32 m0, s39
	s_nop 0
	global_load_lds_dwordx4 v[196:197], off
	s_mov_b32 m0, s53
	s_nop 0
	global_load_lds_dwordx4 v[198:199], off
	s_waitcnt vmcnt(8)
	s_waitcnt lgkmcnt(0)
	s_barrier
	s_waitcnt lgkmcnt(0)
	v_mfma_f32_16x16x32_bf16 v[60:63], v[64:67], v[152:155], 0
	v_mfma_f32_16x16x32_bf16 v[56:59], v[88:91], v[152:155], 0
	v_mfma_f32_16x16x32_bf16 v[40:43], v[88:91], v[160:163], 0
	v_mfma_f32_16x16x32_bf16 v[44:47], v[64:67], v[160:163], 0
	v_mfma_f32_16x16x32_bf16 v[28:31], v[64:67], v[168:171], 0
	v_mfma_f32_16x16x32_bf16 v[24:27], v[88:91], v[168:171], 0
	v_mfma_f32_16x16x32_bf16 v[8:11], v[88:91], v[184:187], 0
	v_mfma_f32_16x16x32_bf16 v[12:15], v[64:67], v[184:187], 0
	v_mfma_f32_16x16x32_bf16 v[60:63], v[72:75], v[156:159], v[60:63]
	v_mfma_f32_16x16x32_bf16 v[56:59], v[96:99], v[156:159], v[56:59]
	v_mfma_f32_16x16x32_bf16 v[40:43], v[96:99], v[164:167], v[40:43]
	v_mfma_f32_16x16x32_bf16 v[44:47], v[72:75], v[164:167], v[44:47]
	v_mfma_f32_16x16x32_bf16 v[28:31], v[72:75], v[180:183], v[28:31]
	v_mfma_f32_16x16x32_bf16 v[24:27], v[96:99], v[180:183], v[24:27]
	v_mfma_f32_16x16x32_bf16 v[8:11], v[96:99], v[188:191], v[8:11]
	v_mfma_f32_16x16x32_bf16 v[12:15], v[72:75], v[188:191], v[12:15]
	v_mfma_f32_16x16x32_bf16 v[52:55], v[108:111], v[152:155], 0
	v_mfma_f32_16x16x32_bf16 v[48:51], v[128:131], v[152:155], 0
	v_mfma_f32_16x16x32_bf16 v[32:35], v[128:131], v[160:163], 0
	v_mfma_f32_16x16x32_bf16 v[36:39], v[108:111], v[160:163], 0
	v_mfma_f32_16x16x32_bf16 v[20:23], v[108:111], v[168:171], 0
	v_mfma_f32_16x16x32_bf16 v[16:19], v[128:131], v[168:171], 0
	v_mfma_f32_16x16x32_bf16 v[0:3], v[128:131], v[184:187], 0
	v_mfma_f32_16x16x32_bf16 v[4:7], v[108:111], v[184:187], 0
	v_mfma_f32_16x16x32_bf16 v[52:55], v[116:119], v[156:159], v[52:55]
	v_mfma_f32_16x16x32_bf16 v[48:51], v[140:143], v[156:159], v[48:51]
	v_mfma_f32_16x16x32_bf16 v[32:35], v[140:143], v[164:167], v[32:35]
	v_mfma_f32_16x16x32_bf16 v[36:39], v[116:119], v[164:167], v[36:39]
	v_mfma_f32_16x16x32_bf16 v[20:23], v[116:119], v[180:183], v[20:23]
	v_mfma_f32_16x16x32_bf16 v[16:19], v[140:143], v[180:183], v[16:19]
	v_mfma_f32_16x16x32_bf16 v[0:3], v[140:143], v[188:191], v[0:3]
	v_mfma_f32_16x16x32_bf16 v[4:7], v[116:119], v[188:191], v[4:7]
	s_barrier
	s_add_i32 s67, 0, 0x18000
	s_add_i32 s76, 0, 0x1c000
	v_add_u32_e32 v96, s67, v238
	v_add_u32_e32 v140, s76, v238
	ds_read_b128 v[64:67], v96
	ds_read_b128 v[72:75], v96 offset:1024
	ds_read_b128 v[88:91], v96 offset:2048
	ds_read_b128 v[96:99], v96 offset:3072
	ds_read_b128 v[108:111], v140
	ds_read_b128 v[116:119], v140 offset:1024
	ds_read_b128 v[128:131], v140 offset:2048
	ds_read_b128 v[140:143], v140 offset:3072
	s_add_u32 s2, s94, 0x80000
	s_addc_u32 s3, s95, 0
	s_mov_b32 m0, s55
	v_lshl_add_u64 v[200:201], s[2:3], 0, v[224:225]
	ds_read_b128 v[152:155], v240 offset:32768
	ds_read_b128 v[156:159], v240 offset:33792
	ds_read_b128 v[160:163], v240 offset:34816
	ds_read_b128 v[164:167], v240 offset:35840
	ds_read_b128 v[168:171], v240 offset:36864
	ds_read_b128 v[180:183], v240 offset:37888
	ds_read_b128 v[184:187], v240 offset:38912
	ds_read_b128 v[188:191], v240 offset:39936
	global_load_lds_dwordx4 v[200:201], off
	v_lshl_add_u64 v[200:201], s[2:3], 0, v[226:227]
	s_mov_b32 m0, s56
	s_nop 0
	global_load_lds_dwordx4 v[200:201], off
	s_waitcnt vmcnt(8)
	s_waitcnt lgkmcnt(0)
	s_barrier
	s_waitcnt lgkmcnt(0)
	v_mfma_f32_16x16x32_bf16 v[176:179], v[64:67], v[152:155], v[176:179]
	v_mfma_f32_16x16x32_bf16 v[172:175], v[88:91], v[152:155], v[172:175]
	v_mfma_f32_16x16x32_bf16 v[132:135], v[88:91], v[160:163], v[132:135]
	v_mfma_f32_16x16x32_bf16 v[136:139], v[64:67], v[160:163], v[136:139]
	v_mfma_f32_16x16x32_bf16 v[112:115], v[64:67], v[168:171], v[112:115]
	v_mfma_f32_16x16x32_bf16 v[104:107], v[88:91], v[168:171], v[104:107]
	v_mfma_f32_16x16x32_bf16 v[80:83], v[88:91], v[184:187], v[80:83]
	v_mfma_f32_16x16x32_bf16 v[84:87], v[64:67], v[184:187], v[84:87]
	v_mfma_f32_16x16x32_bf16 v[176:179], v[72:75], v[156:159], v[176:179]
	v_mfma_f32_16x16x32_bf16 v[172:175], v[96:99], v[156:159], v[172:175]
	v_mfma_f32_16x16x32_bf16 v[132:135], v[96:99], v[164:167], v[132:135]
	v_mfma_f32_16x16x32_bf16 v[136:139], v[72:75], v[164:167], v[136:139]
	v_mfma_f32_16x16x32_bf16 v[112:115], v[72:75], v[180:183], v[112:115]
	v_mfma_f32_16x16x32_bf16 v[104:107], v[96:99], v[180:183], v[104:107]
	v_mfma_f32_16x16x32_bf16 v[80:83], v[96:99], v[188:191], v[80:83]
	v_mfma_f32_16x16x32_bf16 v[84:87], v[72:75], v[188:191], v[84:87]
	v_mfma_f32_16x16x32_bf16 v[148:151], v[108:111], v[152:155], v[148:151]
	v_mfma_f32_16x16x32_bf16 v[144:147], v[128:131], v[152:155], v[144:147]
	v_mfma_f32_16x16x32_bf16 v[120:123], v[128:131], v[160:163], v[120:123]
	v_mfma_f32_16x16x32_bf16 v[124:127], v[108:111], v[160:163], v[124:127]
	v_mfma_f32_16x16x32_bf16 v[100:103], v[108:111], v[168:171], v[100:103]
	v_mfma_f32_16x16x32_bf16 v[92:95], v[128:131], v[168:171], v[92:95]
	v_mfma_f32_16x16x32_bf16 v[68:71], v[128:131], v[184:187], v[68:71]
	v_mfma_f32_16x16x32_bf16 v[76:79], v[108:111], v[184:187], v[76:79]
	v_mfma_f32_16x16x32_bf16 v[148:151], v[116:119], v[156:159], v[148:151]
	v_mfma_f32_16x16x32_bf16 v[144:147], v[140:143], v[156:159], v[144:147]
	v_mfma_f32_16x16x32_bf16 v[120:123], v[140:143], v[164:167], v[120:123]
	v_mfma_f32_16x16x32_bf16 v[124:127], v[116:119], v[164:167], v[124:127]
	v_mfma_f32_16x16x32_bf16 v[100:103], v[116:119], v[180:183], v[100:103]
	v_mfma_f32_16x16x32_bf16 v[92:95], v[140:143], v[180:183], v[92:95]
	v_mfma_f32_16x16x32_bf16 v[68:71], v[140:143], v[188:191], v[68:71]
	v_mfma_f32_16x16x32_bf16 v[76:79], v[116:119], v[188:191], v[76:79]
	s_barrier
	s_add_i32 s2, s67, s28
	v_lshl_add_u64 v[192:193], v[192:193], 0, s[30:31]
	s_mov_b32 m0, s2
	ds_read_b128 v[152:155], v240 offset:49152
	ds_read_b128 v[156:159], v240 offset:50176
	ds_read_b128 v[160:163], v240 offset:51200
	ds_read_b128 v[164:167], v240 offset:52224
	ds_read_b128 v[168:171], v240 offset:53248
	ds_read_b128 v[180:183], v240 offset:54272
	ds_read_b128 v[184:187], v240 offset:55296
	ds_read_b128 v[188:191], v240 offset:56320
	global_load_lds_dwordx4 v[192:193], off
	s_add_i32 m0, s2, 0x2000
	s_add_u32 s2, s92, 0x80080
	v_lshl_add_u64 v[192:193], v[194:195], 0, s[30:31]
	s_addc_u32 s3, s93, 0
	s_add_i32 s67, s76, s28
	global_load_lds_dwordx4 v[192:193], off
	v_lshl_add_u64 v[192:193], s[2:3], 0, v[216:217]
	s_mov_b32 m0, s67
	s_nop 0
	global_load_lds_dwordx4 v[192:193], off
	v_lshl_add_u64 v[192:193], s[2:3], 0, v[228:229]
	s_add_i32 m0, s67, 0x2000
	s_nop 0
	global_load_lds_dwordx4 v[192:193], off
	v_lshl_add_u64 v[192:193], v[196:197], 0, s[30:31]
	s_mov_b32 m0, s70
	s_nop 0
	global_load_lds_dwordx4 v[192:193], off
	v_lshl_add_u64 v[192:193], v[198:199], 0, s[30:31]
	s_mov_b32 m0, s71
	s_nop 0
	global_load_lds_dwordx4 v[192:193], off
	s_waitcnt vmcnt(8)
	s_waitcnt lgkmcnt(0)
	s_barrier
	s_waitcnt lgkmcnt(0)
	v_mfma_f32_16x16x32_bf16 v[60:63], v[64:67], v[152:155], v[60:63]
	v_mfma_f32_16x16x32_bf16 v[56:59], v[88:91], v[152:155], v[56:59]
	v_mfma_f32_16x16x32_bf16 v[40:43], v[88:91], v[160:163], v[40:43]
	v_mfma_f32_16x16x32_bf16 v[44:47], v[64:67], v[160:163], v[44:47]
	v_mfma_f32_16x16x32_bf16 v[28:31], v[64:67], v[168:171], v[28:31]
	v_mfma_f32_16x16x32_bf16 v[24:27], v[88:91], v[168:171], v[24:27]
	v_mfma_f32_16x16x32_bf16 v[8:11], v[88:91], v[184:187], v[8:11]
	v_mfma_f32_16x16x32_bf16 v[12:15], v[64:67], v[184:187], v[12:15]
	v_mfma_f32_16x16x32_bf16 v[60:63], v[72:75], v[156:159], v[60:63]
	v_mfma_f32_16x16x32_bf16 v[56:59], v[96:99], v[156:159], v[56:59]
	v_mfma_f32_16x16x32_bf16 v[40:43], v[96:99], v[164:167], v[40:43]
	v_mfma_f32_16x16x32_bf16 v[44:47], v[72:75], v[164:167], v[44:47]
	v_mfma_f32_16x16x32_bf16 v[28:31], v[72:75], v[180:183], v[28:31]
	v_mfma_f32_16x16x32_bf16 v[24:27], v[96:99], v[180:183], v[24:27]
	v_mfma_f32_16x16x32_bf16 v[8:11], v[96:99], v[188:191], v[8:11]
	v_mfma_f32_16x16x32_bf16 v[12:15], v[72:75], v[188:191], v[12:15]
	v_mfma_f32_16x16x32_bf16 v[52:55], v[108:111], v[152:155], v[52:55]
	v_mfma_f32_16x16x32_bf16 v[48:51], v[128:131], v[152:155], v[48:51]
	v_mfma_f32_16x16x32_bf16 v[32:35], v[128:131], v[160:163], v[32:35]
	v_mfma_f32_16x16x32_bf16 v[36:39], v[108:111], v[160:163], v[36:39]
	v_mfma_f32_16x16x32_bf16 v[20:23], v[108:111], v[168:171], v[20:23]
	v_mfma_f32_16x16x32_bf16 v[16:19], v[128:131], v[168:171], v[16:19]
	v_mfma_f32_16x16x32_bf16 v[0:3], v[128:131], v[184:187], v[0:3]
	v_mfma_f32_16x16x32_bf16 v[4:7], v[108:111], v[184:187], v[4:7]
	v_mfma_f32_16x16x32_bf16 v[52:55], v[116:119], v[156:159], v[52:55]
	v_mfma_f32_16x16x32_bf16 v[48:51], v[140:143], v[156:159], v[48:51]
	v_mfma_f32_16x16x32_bf16 v[32:35], v[140:143], v[164:167], v[32:35]
	v_mfma_f32_16x16x32_bf16 v[36:39], v[116:119], v[164:167], v[36:39]
	v_mfma_f32_16x16x32_bf16 v[20:23], v[116:119], v[180:183], v[20:23]
	v_mfma_f32_16x16x32_bf16 v[16:19], v[140:143], v[180:183], v[16:19]
	v_mfma_f32_16x16x32_bf16 v[0:3], v[140:143], v[188:191], v[0:3]
	v_mfma_f32_16x16x32_bf16 v[4:7], v[116:119], v[188:191], v[4:7]
	s_barrier
	s_add_i32 s20, s20, 2
	s_add_u32 s90, s90, 0x100
	s_addc_u32 s91, s91, 0
	s_add_u32 s89, s89, 0x100
	s_addc_u32 s14, s14, 0
.LBB0_595:
	s_add_u32 s2, s90, 0xfff80080
	s_addc_u32 s3, s91, -1
	s_add_i32 s67, 0, 0x10000
	s_cmp_eq_u32 s20, 28
	s_cselect_b32 s95, s81, s3
	s_cselect_b32 s94, vcc_lo, s2
	s_cselect_b32 s93, s79, s14
	s_cselect_b32 s92, vcc_hi, s89
	s_add_i32 s76, 0, 0x14000
	v_add_u32_e32 v96, s67, v238
	v_add_u32_e32 v140, s76, v238
	ds_read_b128 v[64:67], v96
	ds_read_b128 v[72:75], v96 offset:1024
	ds_read_b128 v[88:91], v96 offset:2048
	ds_read_b128 v[96:99], v96 offset:3072
	ds_read_b128 v[108:111], v140
	ds_read_b128 v[116:119], v140 offset:1024
	ds_read_b128 v[128:131], v140 offset:2048
	ds_read_b128 v[140:143], v140 offset:3072
	v_lshl_add_u64 v[192:193], s[90:91], 0, v[230:231]
	s_add_i32 m0, s39, 0xc000
	ds_read_b128 v[152:155], v240
	ds_read_b128 v[156:159], v240 offset:1024
	ds_read_b128 v[160:163], v240 offset:2048
	ds_read_b128 v[164:167], v240 offset:3072
	ds_read_b128 v[168:171], v240 offset:4096
	ds_read_b128 v[180:183], v240 offset:5120
	ds_read_b128 v[184:187], v240 offset:6144
	ds_read_b128 v[188:191], v240 offset:7168
	global_load_lds_dwordx4 v[192:193], off
	v_lshl_add_u64 v[192:193], s[90:91], 0, v[232:233]
	s_add_i32 m0, s39, 0xe000
	s_nop 0
	global_load_lds_dwordx4 v[192:193], off
	s_waitcnt vmcnt(8)
	s_waitcnt lgkmcnt(0)
	s_barrier
	s_waitcnt lgkmcnt(0)
	v_mfma_f32_16x16x32_bf16 v[176:179], v[64:67], v[152:155], v[176:179]
	v_mfma_f32_16x16x32_bf16 v[172:175], v[88:91], v[152:155], v[172:175]
	v_mfma_f32_16x16x32_bf16 v[132:135], v[88:91], v[160:163], v[132:135]
	v_mfma_f32_16x16x32_bf16 v[136:139], v[64:67], v[160:163], v[136:139]
	v_mfma_f32_16x16x32_bf16 v[112:115], v[64:67], v[168:171], v[112:115]
	v_mfma_f32_16x16x32_bf16 v[104:107], v[88:91], v[168:171], v[104:107]
	v_mfma_f32_16x16x32_bf16 v[80:83], v[88:91], v[184:187], v[80:83]
	v_mfma_f32_16x16x32_bf16 v[84:87], v[64:67], v[184:187], v[84:87]
	v_mfma_f32_16x16x32_bf16 v[176:179], v[72:75], v[156:159], v[176:179]
	v_mfma_f32_16x16x32_bf16 v[172:175], v[96:99], v[156:159], v[172:175]
	v_mfma_f32_16x16x32_bf16 v[132:135], v[96:99], v[164:167], v[132:135]
	v_mfma_f32_16x16x32_bf16 v[136:139], v[72:75], v[164:167], v[136:139]
	v_mfma_f32_16x16x32_bf16 v[112:115], v[72:75], v[180:183], v[112:115]
	v_mfma_f32_16x16x32_bf16 v[104:107], v[96:99], v[180:183], v[104:107]
	v_mfma_f32_16x16x32_bf16 v[80:83], v[96:99], v[188:191], v[80:83]
	v_mfma_f32_16x16x32_bf16 v[84:87], v[72:75], v[188:191], v[84:87]
	v_mfma_f32_16x16x32_bf16 v[148:151], v[108:111], v[152:155], v[148:151]
	v_mfma_f32_16x16x32_bf16 v[144:147], v[128:131], v[152:155], v[144:147]
	v_mfma_f32_16x16x32_bf16 v[120:123], v[128:131], v[160:163], v[120:123]
	v_mfma_f32_16x16x32_bf16 v[124:127], v[108:111], v[160:163], v[124:127]
	v_mfma_f32_16x16x32_bf16 v[100:103], v[108:111], v[168:171], v[100:103]
	v_mfma_f32_16x16x32_bf16 v[92:95], v[128:131], v[168:171], v[92:95]
	v_mfma_f32_16x16x32_bf16 v[68:71], v[128:131], v[184:187], v[68:71]
	v_mfma_f32_16x16x32_bf16 v[76:79], v[108:111], v[184:187], v[76:79]
	v_mfma_f32_16x16x32_bf16 v[148:151], v[116:119], v[156:159], v[148:151]
	v_mfma_f32_16x16x32_bf16 v[144:147], v[140:143], v[156:159], v[144:147]
	v_mfma_f32_16x16x32_bf16 v[120:123], v[140:143], v[164:167], v[120:123]
	v_mfma_f32_16x16x32_bf16 v[124:127], v[116:119], v[164:167], v[124:127]
	v_mfma_f32_16x16x32_bf16 v[100:103], v[116:119], v[180:183], v[100:103]
	v_mfma_f32_16x16x32_bf16 v[92:95], v[140:143], v[180:183], v[92:95]
	v_mfma_f32_16x16x32_bf16 v[68:71], v[140:143], v[188:191], v[68:71]
	v_mfma_f32_16x16x32_bf16 v[76:79], v[116:119], v[188:191], v[76:79]
	s_barrier
	s_add_i32 s2, s67, s28
	v_lshl_add_u64 v[192:193], s[92:93], 0, v[216:217]
	s_mov_b32 m0, s2
	ds_read_b128 v[152:155], v240 offset:16384
	ds_read_b128 v[156:159], v240 offset:17408
	ds_read_b128 v[160:163], v240 offset:18432
	ds_read_b128 v[164:167], v240 offset:19456
	ds_read_b128 v[168:171], v240 offset:20480
	ds_read_b128 v[180:183], v240 offset:21504
	ds_read_b128 v[184:187], v240 offset:22528
	ds_read_b128 v[188:191], v240 offset:23552
	global_load_lds_dwordx4 v[192:193], off
	s_add_i32 m0, s2, 0x2000
	s_add_u32 s2, s92, 0x80000
	v_lshl_add_u64 v[194:195], s[92:93], 0, v[228:229]
	s_addc_u32 s3, s93, 0
	s_add_i32 s67, s76, s28
	global_load_lds_dwordx4 v[194:195], off
	v_lshl_add_u64 v[196:197], s[2:3], 0, v[216:217]
	s_mov_b32 m0, s67
	v_lshl_add_u64 v[198:199], s[94:95], 0, v[226:227]
	global_load_lds_dwordx4 v[196:197], off
	v_lshl_add_u64 v[196:197], s[2:3], 0, v[228:229]
	s_add_i32 m0, s67, 0x2000
	s_nop 0
	global_load_lds_dwordx4 v[196:197], off
	v_lshl_add_u64 v[196:197], s[94:95], 0, v[224:225]
	s_mov_b32 m0, s39
	s_nop 0
	global_load_lds_dwordx4 v[196:197], off
	s_mov_b32 m0, s53
	s_nop 0
	global_load_lds_dwordx4 v[198:199], off
	s_waitcnt vmcnt(8)
	s_waitcnt lgkmcnt(0)
	s_barrier
	s_waitcnt lgkmcnt(0)
	v_mfma_f32_16x16x32_bf16 v[60:63], v[64:67], v[152:155], v[60:63]
	v_mfma_f32_16x16x32_bf16 v[56:59], v[88:91], v[152:155], v[56:59]
	v_mfma_f32_16x16x32_bf16 v[40:43], v[88:91], v[160:163], v[40:43]
	v_mfma_f32_16x16x32_bf16 v[44:47], v[64:67], v[160:163], v[44:47]
	v_mfma_f32_16x16x32_bf16 v[28:31], v[64:67], v[168:171], v[28:31]
	v_mfma_f32_16x16x32_bf16 v[24:27], v[88:91], v[168:171], v[24:27]
	v_mfma_f32_16x16x32_bf16 v[8:11], v[88:91], v[184:187], v[8:11]
	v_mfma_f32_16x16x32_bf16 v[12:15], v[64:67], v[184:187], v[12:15]
	v_mfma_f32_16x16x32_bf16 v[60:63], v[72:75], v[156:159], v[60:63]
	v_mfma_f32_16x16x32_bf16 v[56:59], v[96:99], v[156:159], v[56:59]
	v_mfma_f32_16x16x32_bf16 v[40:43], v[96:99], v[164:167], v[40:43]
	v_mfma_f32_16x16x32_bf16 v[44:47], v[72:75], v[164:167], v[44:47]
	v_mfma_f32_16x16x32_bf16 v[28:31], v[72:75], v[180:183], v[28:31]
	v_mfma_f32_16x16x32_bf16 v[24:27], v[96:99], v[180:183], v[24:27]
	v_mfma_f32_16x16x32_bf16 v[8:11], v[96:99], v[188:191], v[8:11]
	v_mfma_f32_16x16x32_bf16 v[12:15], v[72:75], v[188:191], v[12:15]
	v_mfma_f32_16x16x32_bf16 v[52:55], v[108:111], v[152:155], v[52:55]
	v_mfma_f32_16x16x32_bf16 v[48:51], v[128:131], v[152:155], v[48:51]
	v_mfma_f32_16x16x32_bf16 v[32:35], v[128:131], v[160:163], v[32:35]
	v_mfma_f32_16x16x32_bf16 v[36:39], v[108:111], v[160:163], v[36:39]
	v_mfma_f32_16x16x32_bf16 v[20:23], v[108:111], v[168:171], v[20:23]
	v_mfma_f32_16x16x32_bf16 v[16:19], v[128:131], v[168:171], v[16:19]
	v_mfma_f32_16x16x32_bf16 v[0:3], v[128:131], v[184:187], v[0:3]
	v_mfma_f32_16x16x32_bf16 v[4:7], v[108:111], v[184:187], v[4:7]
	v_mfma_f32_16x16x32_bf16 v[52:55], v[116:119], v[156:159], v[52:55]
	v_mfma_f32_16x16x32_bf16 v[48:51], v[140:143], v[156:159], v[48:51]
	v_mfma_f32_16x16x32_bf16 v[32:35], v[140:143], v[164:167], v[32:35]
	v_mfma_f32_16x16x32_bf16 v[36:39], v[116:119], v[164:167], v[36:39]
	v_mfma_f32_16x16x32_bf16 v[20:23], v[116:119], v[180:183], v[20:23]
	v_mfma_f32_16x16x32_bf16 v[16:19], v[140:143], v[180:183], v[16:19]
	v_mfma_f32_16x16x32_bf16 v[0:3], v[140:143], v[188:191], v[0:3]
	v_mfma_f32_16x16x32_bf16 v[4:7], v[116:119], v[188:191], v[4:7]
	s_barrier
	s_add_i32 s67, 0, 0x18000
	s_add_i32 s76, 0, 0x1c000
	v_add_u32_e32 v96, s67, v238
	v_add_u32_e32 v140, s76, v238
	ds_read_b128 v[64:67], v96
	ds_read_b128 v[72:75], v96 offset:1024
	ds_read_b128 v[88:91], v96 offset:2048
	ds_read_b128 v[96:99], v96 offset:3072
	ds_read_b128 v[108:111], v140
	ds_read_b128 v[116:119], v140 offset:1024
	ds_read_b128 v[128:131], v140 offset:2048
	ds_read_b128 v[140:143], v140 offset:3072
	s_add_u32 s2, s94, 0x80000
	s_addc_u32 s3, s95, 0
	s_mov_b32 m0, s55
	v_lshl_add_u64 v[200:201], s[2:3], 0, v[224:225]
	ds_read_b128 v[152:155], v240 offset:32768
	ds_read_b128 v[156:159], v240 offset:33792
	ds_read_b128 v[160:163], v240 offset:34816
	ds_read_b128 v[164:167], v240 offset:35840
	ds_read_b128 v[168:171], v240 offset:36864
	ds_read_b128 v[180:183], v240 offset:37888
	ds_read_b128 v[184:187], v240 offset:38912
	ds_read_b128 v[188:191], v240 offset:39936
	global_load_lds_dwordx4 v[200:201], off
	v_lshl_add_u64 v[200:201], s[2:3], 0, v[226:227]
	s_mov_b32 m0, s56
	s_nop 0
	global_load_lds_dwordx4 v[200:201], off
	s_waitcnt vmcnt(8)
	s_waitcnt lgkmcnt(0)
	s_barrier
	s_waitcnt lgkmcnt(0)
	v_mfma_f32_16x16x32_bf16 v[176:179], v[64:67], v[152:155], v[176:179]
	v_mfma_f32_16x16x32_bf16 v[172:175], v[88:91], v[152:155], v[172:175]
	v_mfma_f32_16x16x32_bf16 v[132:135], v[88:91], v[160:163], v[132:135]
	v_mfma_f32_16x16x32_bf16 v[136:139], v[64:67], v[160:163], v[136:139]
	v_mfma_f32_16x16x32_bf16 v[112:115], v[64:67], v[168:171], v[112:115]
	v_mfma_f32_16x16x32_bf16 v[104:107], v[88:91], v[168:171], v[104:107]
	v_mfma_f32_16x16x32_bf16 v[80:83], v[88:91], v[184:187], v[80:83]
	v_mfma_f32_16x16x32_bf16 v[84:87], v[64:67], v[184:187], v[84:87]
	v_mfma_f32_16x16x32_bf16 v[176:179], v[72:75], v[156:159], v[176:179]
	v_mfma_f32_16x16x32_bf16 v[172:175], v[96:99], v[156:159], v[172:175]
	v_mfma_f32_16x16x32_bf16 v[132:135], v[96:99], v[164:167], v[132:135]
	v_mfma_f32_16x16x32_bf16 v[136:139], v[72:75], v[164:167], v[136:139]
	v_mfma_f32_16x16x32_bf16 v[112:115], v[72:75], v[180:183], v[112:115]
	v_mfma_f32_16x16x32_bf16 v[104:107], v[96:99], v[180:183], v[104:107]
	v_mfma_f32_16x16x32_bf16 v[80:83], v[96:99], v[188:191], v[80:83]
	v_mfma_f32_16x16x32_bf16 v[84:87], v[72:75], v[188:191], v[84:87]
	v_mfma_f32_16x16x32_bf16 v[148:151], v[108:111], v[152:155], v[148:151]
	v_mfma_f32_16x16x32_bf16 v[144:147], v[128:131], v[152:155], v[144:147]
	v_mfma_f32_16x16x32_bf16 v[120:123], v[128:131], v[160:163], v[120:123]
	v_mfma_f32_16x16x32_bf16 v[124:127], v[108:111], v[160:163], v[124:127]
	v_mfma_f32_16x16x32_bf16 v[100:103], v[108:111], v[168:171], v[100:103]
	v_mfma_f32_16x16x32_bf16 v[92:95], v[128:131], v[168:171], v[92:95]
	v_mfma_f32_16x16x32_bf16 v[68:71], v[128:131], v[184:187], v[68:71]
	v_mfma_f32_16x16x32_bf16 v[76:79], v[108:111], v[184:187], v[76:79]
	v_mfma_f32_16x16x32_bf16 v[148:151], v[116:119], v[156:159], v[148:151]
	v_mfma_f32_16x16x32_bf16 v[144:147], v[140:143], v[156:159], v[144:147]
	v_mfma_f32_16x16x32_bf16 v[120:123], v[140:143], v[164:167], v[120:123]
	v_mfma_f32_16x16x32_bf16 v[124:127], v[116:119], v[164:167], v[124:127]
	v_mfma_f32_16x16x32_bf16 v[100:103], v[116:119], v[180:183], v[100:103]
	v_mfma_f32_16x16x32_bf16 v[92:95], v[140:143], v[180:183], v[92:95]
	v_mfma_f32_16x16x32_bf16 v[68:71], v[140:143], v[188:191], v[68:71]
	v_mfma_f32_16x16x32_bf16 v[76:79], v[116:119], v[188:191], v[76:79]
	s_barrier
	s_add_i32 s2, s67, s28
	v_lshl_add_u64 v[192:193], v[192:193], 0, s[30:31]
	s_mov_b32 m0, s2
	ds_read_b128 v[152:155], v240 offset:49152
	ds_read_b128 v[156:159], v240 offset:50176
	ds_read_b128 v[160:163], v240 offset:51200
	ds_read_b128 v[164:167], v240 offset:52224
	ds_read_b128 v[168:171], v240 offset:53248
	ds_read_b128 v[180:183], v240 offset:54272
	ds_read_b128 v[184:187], v240 offset:55296
	ds_read_b128 v[188:191], v240 offset:56320
	global_load_lds_dwordx4 v[192:193], off
	s_add_i32 m0, s2, 0x2000
	s_add_u32 s2, s92, 0x80080
	v_lshl_add_u64 v[192:193], v[194:195], 0, s[30:31]
	s_addc_u32 s3, s93, 0
	s_add_i32 s67, s76, s28
	global_load_lds_dwordx4 v[192:193], off
	v_lshl_add_u64 v[192:193], s[2:3], 0, v[216:217]
	s_mov_b32 m0, s67
	s_nop 0
	global_load_lds_dwordx4 v[192:193], off
	v_lshl_add_u64 v[192:193], s[2:3], 0, v[228:229]
	s_add_i32 m0, s67, 0x2000
	s_nop 0
	global_load_lds_dwordx4 v[192:193], off
	v_lshl_add_u64 v[192:193], v[196:197], 0, s[30:31]
	s_mov_b32 m0, s70
	s_nop 0
	global_load_lds_dwordx4 v[192:193], off
	v_lshl_add_u64 v[192:193], v[198:199], 0, s[30:31]
	s_mov_b32 m0, s71
	s_nop 0
	global_load_lds_dwordx4 v[192:193], off
	s_waitcnt vmcnt(8)
	s_waitcnt lgkmcnt(0)
	s_barrier
	s_waitcnt lgkmcnt(0)
	v_mfma_f32_16x16x32_bf16 v[60:63], v[64:67], v[152:155], v[60:63]
	v_mfma_f32_16x16x32_bf16 v[56:59], v[88:91], v[152:155], v[56:59]
	v_mfma_f32_16x16x32_bf16 v[40:43], v[88:91], v[160:163], v[40:43]
	v_mfma_f32_16x16x32_bf16 v[44:47], v[64:67], v[160:163], v[44:47]
	v_mfma_f32_16x16x32_bf16 v[28:31], v[64:67], v[168:171], v[28:31]
	v_mfma_f32_16x16x32_bf16 v[24:27], v[88:91], v[168:171], v[24:27]
	v_mfma_f32_16x16x32_bf16 v[8:11], v[88:91], v[184:187], v[8:11]
	v_mfma_f32_16x16x32_bf16 v[12:15], v[64:67], v[184:187], v[12:15]
	v_mfma_f32_16x16x32_bf16 v[60:63], v[72:75], v[156:159], v[60:63]
	v_mfma_f32_16x16x32_bf16 v[56:59], v[96:99], v[156:159], v[56:59]
	v_mfma_f32_16x16x32_bf16 v[40:43], v[96:99], v[164:167], v[40:43]
	v_mfma_f32_16x16x32_bf16 v[44:47], v[72:75], v[164:167], v[44:47]
	v_mfma_f32_16x16x32_bf16 v[28:31], v[72:75], v[180:183], v[28:31]
	v_mfma_f32_16x16x32_bf16 v[24:27], v[96:99], v[180:183], v[24:27]
	v_mfma_f32_16x16x32_bf16 v[8:11], v[96:99], v[188:191], v[8:11]
	v_mfma_f32_16x16x32_bf16 v[12:15], v[72:75], v[188:191], v[12:15]
	v_mfma_f32_16x16x32_bf16 v[52:55], v[108:111], v[152:155], v[52:55]
	v_mfma_f32_16x16x32_bf16 v[48:51], v[128:131], v[152:155], v[48:51]
	v_mfma_f32_16x16x32_bf16 v[32:35], v[128:131], v[160:163], v[32:35]
	v_mfma_f32_16x16x32_bf16 v[36:39], v[108:111], v[160:163], v[36:39]
	v_mfma_f32_16x16x32_bf16 v[20:23], v[108:111], v[168:171], v[20:23]
	v_mfma_f32_16x16x32_bf16 v[16:19], v[128:131], v[168:171], v[16:19]
	v_mfma_f32_16x16x32_bf16 v[0:3], v[128:131], v[184:187], v[0:3]
	v_mfma_f32_16x16x32_bf16 v[4:7], v[108:111], v[184:187], v[4:7]
	v_mfma_f32_16x16x32_bf16 v[52:55], v[116:119], v[156:159], v[52:55]
	v_mfma_f32_16x16x32_bf16 v[48:51], v[140:143], v[156:159], v[48:51]
	v_mfma_f32_16x16x32_bf16 v[32:35], v[140:143], v[164:167], v[32:35]
	v_mfma_f32_16x16x32_bf16 v[36:39], v[116:119], v[164:167], v[36:39]
	v_mfma_f32_16x16x32_bf16 v[20:23], v[116:119], v[180:183], v[20:23]
	v_mfma_f32_16x16x32_bf16 v[16:19], v[140:143], v[180:183], v[16:19]
	v_mfma_f32_16x16x32_bf16 v[0:3], v[140:143], v[188:191], v[0:3]
	v_mfma_f32_16x16x32_bf16 v[4:7], v[116:119], v[188:191], v[4:7]
	s_barrier
	s_add_i32 s20, s20, 2
	s_add_u32 s90, s90, 0x100
	s_addc_u32 s91, s91, 0
	s_add_u32 s89, s89, 0x100
	s_addc_u32 s14, s14, 0
	s_cmp_gt_u32 s20, 29
	s_cbranch_scc0 .LBB0_595
	s_and_b64 vcc, exec, s[74:75]
	s_cbranch_vccz .LBB0_598
	s_barrier

.LBB0_638:
	s_ashr_i32 s87, s86, 31
	s_lshl_b64 s[40:41], s[86:87], 20
	s_add_u32 s88, s14, s40
	s_addc_u32 s89, s15, s41
	s_and_b64 s[40:41], s[4:5], exec
	s_cselect_b32 s7, s89, s11
	s_cselect_b32 s9, s88, s10
	s_ashr_i32 s85, s84, 31
	s_lshl_b64 s[40:41], s[84:85], 20
	s_add_u32 s90, s24, s40
	s_addc_u32 s91, s26, s41
	s_and_b64 s[40:41], s[4:5], exec
	s_cselect_b32 s40, s91, s93
	s_cselect_b32 s41, s90, s92
	s_add_u32 s10, s10, 0x80080
	s_addc_u32 s11, s11, 0
	s_add_u32 s54, s92, 0x100
	s_addc_u32 s55, s93, 0
	s_mov_b32 s85, -2
	s_add_u32 s67, s10, 0xfff80080
	s_addc_u32 s87, s11, -1
	s_add_i32 s96, 0, 0x10000
	s_cmp_eq_u32 s85, 28
	s_cselect_b32 s95, s7, s87
	s_cselect_b32 s94, s9, s67
	s_cselect_b32 s93, s40, s55
	s_cselect_b32 s92, s41, s54
	s_add_i32 s67, 0, 0x14000
	v_add_u32_e32 v52, s96, v194
	v_add_u32_e32 v124, s67, v194
	ds_read_b128 v[40:43], v52
	ds_read_b128 v[44:47], v52 offset:1024
	ds_read_b128 v[48:51], v52 offset:2048
	ds_read_b128 v[52:55], v52 offset:3072
	ds_read_b128 v[64:67], v124
	ds_read_b128 v[100:103], v124 offset:1024
	ds_read_b128 v[120:123], v124 offset:2048
	ds_read_b128 v[124:127], v124 offset:3072
	v_lshl_add_u64 v[208:209], s[10:11], 0, v[186:187]
	s_add_i32 m0, s57, 0xc000
	ds_read_b128 v[136:139], v195
	ds_read_b128 v[140:143], v195 offset:1024
	ds_read_b128 v[144:147], v195 offset:2048
	ds_read_b128 v[172:175], v195 offset:3072
	ds_read_b128 v[190:193], v195 offset:4096
	ds_read_b128 v[196:199], v195 offset:5120
	ds_read_b128 v[200:203], v195 offset:6144
	ds_read_b128 v[204:207], v195 offset:7168
	global_load_lds_dwordx4 v[208:209], off
	v_lshl_add_u64 v[208:209], s[10:11], 0, v[188:189]
	s_add_i32 m0, s57, 0xe000
	s_nop 0
	global_load_lds_dwordx4 v[208:209], off
	s_waitcnt vmcnt(8)
	s_waitcnt lgkmcnt(0)
	s_barrier
	s_waitcnt lgkmcnt(0)
	v_mfma_f32_16x16x32_bf16 v[168:171], v[40:43], v[136:139], 0
	v_mfma_f32_16x16x32_bf16 v[164:167], v[48:51], v[136:139], 0
	v_mfma_f32_16x16x32_bf16 v[148:151], v[48:51], v[144:147], 0
	v_mfma_f32_16x16x32_bf16 v[152:155], v[40:43], v[144:147], 0
	v_mfma_f32_16x16x32_bf16 v[116:119], v[40:43], v[190:193], 0
	v_mfma_f32_16x16x32_bf16 v[112:115], v[48:51], v[190:193], 0
	v_mfma_f32_16x16x32_bf16 v[92:95], v[48:51], v[200:203], 0
	v_mfma_f32_16x16x32_bf16 v[96:99], v[40:43], v[200:203], 0
	v_mfma_f32_16x16x32_bf16 v[168:171], v[44:47], v[140:143], v[168:171]
	v_mfma_f32_16x16x32_bf16 v[164:167], v[52:55], v[140:143], v[164:167]
	v_mfma_f32_16x16x32_bf16 v[148:151], v[52:55], v[172:175], v[148:151]
	v_mfma_f32_16x16x32_bf16 v[152:155], v[44:47], v[172:175], v[152:155]
	v_mfma_f32_16x16x32_bf16 v[116:119], v[44:47], v[196:199], v[116:119]
	v_mfma_f32_16x16x32_bf16 v[112:115], v[52:55], v[196:199], v[112:115]
	v_mfma_f32_16x16x32_bf16 v[92:95], v[52:55], v[204:207], v[92:95]
	v_mfma_f32_16x16x32_bf16 v[96:99], v[44:47], v[204:207], v[96:99]
	v_mfma_f32_16x16x32_bf16 v[160:163], v[64:67], v[136:139], 0
	v_mfma_f32_16x16x32_bf16 v[132:135], v[64:67], v[144:147], 0
	v_mfma_f32_16x16x32_bf16 v[128:131], v[120:123], v[144:147], 0
	v_mfma_f32_16x16x32_bf16 v[108:111], v[64:67], v[190:193], 0
	v_mfma_f32_16x16x32_bf16 v[104:107], v[120:123], v[190:193], 0
	v_mfma_f32_16x16x32_bf16 v[88:91], v[64:67], v[200:203], 0
	v_mfma_f32_16x16x32_bf16 v[84:87], v[120:123], v[200:203], 0
	v_mfma_f32_16x16x32_bf16 v[160:163], v[100:103], v[140:143], v[160:163]
	v_mfma_f32_16x16x32_bf16 v[136:139], v[120:123], v[136:139], 0
	v_mfma_f32_16x16x32_bf16 v[132:135], v[100:103], v[172:175], v[132:135]
	v_mfma_f32_16x16x32_bf16 v[128:131], v[124:127], v[172:175], v[128:131]
	v_mfma_f32_16x16x32_bf16 v[108:111], v[100:103], v[196:199], v[108:111]
	v_mfma_f32_16x16x32_bf16 v[104:107], v[124:127], v[196:199], v[104:107]
	v_mfma_f32_16x16x32_bf16 v[88:91], v[100:103], v[204:207], v[88:91]
	v_mfma_f32_16x16x32_bf16 v[84:87], v[124:127], v[204:207], v[84:87]
	v_mfma_f32_16x16x32_bf16 v[136:139], v[124:127], v[140:143], v[136:139]
	s_barrier
	s_add_i32 s87, s96, s56
	v_lshl_add_u64 v[212:213], s[92:93], 0, v[178:179]
	s_mov_b32 m0, s87
	ds_read_b128 v[140:143], v195 offset:16384
	ds_read_b128 v[144:147], v195 offset:17408
	ds_read_b128 v[156:159], v195 offset:18432
	ds_read_b128 v[172:175], v195 offset:19456
	ds_read_b128 v[190:193], v195 offset:20480
	ds_read_b128 v[196:199], v195 offset:21504
	ds_read_b128 v[200:203], v195 offset:22528
	ds_read_b128 v[204:207], v195 offset:23552
	global_load_lds_dwordx4 v[212:213], off
	s_add_i32 m0, s87, 0x2000
	s_add_u32 vcc_lo, s92, 0x80000
	v_lshl_add_u64 v[214:215], s[92:93], 0, v[182:183]
	s_addc_u32 vcc_hi, s93, 0
	s_add_i32 s67, s67, s56
	global_load_lds_dwordx4 v[214:215], off
	v_lshl_add_u64 v[208:209], vcc, 0, v[178:179]
	s_mov_b32 m0, s67
	v_lshl_add_u64 v[224:225], s[94:95], 0, v[176:177]
	global_load_lds_dwordx4 v[208:209], off
	v_lshl_add_u64 v[208:209], vcc, 0, v[182:183]
	s_add_i32 m0, s67, 0x2000
	v_lshl_add_u64 v[226:227], s[94:95], 0, v[180:181]
	global_load_lds_dwordx4 v[208:209], off
	s_mov_b32 m0, s57
	s_nop 0
	global_load_lds_dwordx4 v[224:225], off
	s_mov_b32 m0, s61
	s_nop 0
	global_load_lds_dwordx4 v[226:227], off
	s_waitcnt vmcnt(8)
	s_waitcnt lgkmcnt(0)
	s_barrier
	s_waitcnt lgkmcnt(0)
	v_mfma_f32_16x16x32_bf16 v[80:83], v[40:43], v[140:143], 0
	v_mfma_f32_16x16x32_bf16 v[76:79], v[48:51], v[140:143], 0
	v_mfma_f32_16x16x32_bf16 v[56:59], v[48:51], v[156:159], 0
	v_mfma_f32_16x16x32_bf16 v[60:63], v[40:43], v[156:159], 0
	v_mfma_f32_16x16x32_bf16 v[28:31], v[40:43], v[190:193], 0
	v_mfma_f32_16x16x32_bf16 v[24:27], v[48:51], v[190:193], 0
	v_mfma_f32_16x16x32_bf16 v[8:11], v[48:51], v[200:203], 0
	v_mfma_f32_16x16x32_bf16 v[12:15], v[40:43], v[200:203], 0
	v_mfma_f32_16x16x32_bf16 v[80:83], v[44:47], v[144:147], v[80:83]
	v_mfma_f32_16x16x32_bf16 v[76:79], v[52:55], v[144:147], v[76:79]
	v_mfma_f32_16x16x32_bf16 v[56:59], v[52:55], v[172:175], v[56:59]
	v_mfma_f32_16x16x32_bf16 v[60:63], v[44:47], v[172:175], v[60:63]
	v_mfma_f32_16x16x32_bf16 v[28:31], v[44:47], v[196:199], v[28:31]
	v_mfma_f32_16x16x32_bf16 v[24:27], v[52:55], v[196:199], v[24:27]
	v_mfma_f32_16x16x32_bf16 v[8:11], v[52:55], v[204:207], v[8:11]
	v_mfma_f32_16x16x32_bf16 v[12:15], v[44:47], v[204:207], v[12:15]
	v_mfma_f32_16x16x32_bf16 v[36:39], v[64:67], v[156:159], 0
	v_mfma_f32_16x16x32_bf16 v[32:35], v[120:123], v[156:159], 0
	v_mfma_f32_16x16x32_bf16 v[16:19], v[120:123], v[190:193], 0
	v_mfma_f32_16x16x32_bf16 v[20:23], v[64:67], v[190:193], 0
	v_mfma_f32_16x16x32_bf16 v[4:7], v[64:67], v[200:203], 0
	v_mfma_f32_16x16x32_bf16 v[0:3], v[120:123], v[200:203], 0
	v_mfma_f32_16x16x32_bf16 v[44:47], v[120:123], v[140:143], 0
	v_mfma_f32_16x16x32_bf16 v[40:43], v[64:67], v[140:143], 0
	v_mfma_f32_16x16x32_bf16 v[36:39], v[100:103], v[172:175], v[36:39]
	v_mfma_f32_16x16x32_bf16 v[32:35], v[124:127], v[172:175], v[32:35]
	v_mfma_f32_16x16x32_bf16 v[16:19], v[124:127], v[196:199], v[16:19]
	v_mfma_f32_16x16x32_bf16 v[20:23], v[100:103], v[196:199], v[20:23]
	v_mfma_f32_16x16x32_bf16 v[4:7], v[100:103], v[204:207], v[4:7]
	v_mfma_f32_16x16x32_bf16 v[0:3], v[124:127], v[204:207], v[0:3]
	v_mfma_f32_16x16x32_bf16 v[44:47], v[124:127], v[144:147], v[44:47]
	v_mfma_f32_16x16x32_bf16 v[40:43], v[100:103], v[144:147], v[40:43]
	s_barrier
	s_add_i32 s67, 0, 0x18000
	s_add_i32 s87, 0, 0x1c000
	v_add_u32_e32 v68, s67, v194
	v_add_u32_e32 v72, s87, v194
	ds_read_b128 v[48:51], v68
	ds_read_b128 v[52:55], v68 offset:1024
	ds_read_b128 v[64:67], v68 offset:2048
	ds_read_b128 v[68:71], v68 offset:3072
	ds_read_b128 v[100:103], v72
	ds_read_b128 v[120:123], v72 offset:1024
	ds_read_b128 v[124:127], v72 offset:2048
	ds_read_b128 v[140:143], v72 offset:3072
	s_add_u32 s94, s94, 0x80000
	s_addc_u32 s95, s95, 0
	s_mov_b32 m0, s68
	v_lshl_add_u64 v[156:157], s[94:95], 0, v[176:177]
	ds_read_b128 v[72:75], v195 offset:32768
	ds_read_b128 v[144:147], v195 offset:33792
	ds_read_b128 v[172:175], v195 offset:34816
	ds_read_b128 v[190:193], v195 offset:35840
	ds_read_b128 v[196:199], v195 offset:36864
	ds_read_b128 v[200:203], v195 offset:37888
	ds_read_b128 v[204:207], v195 offset:38912
	ds_read_b128 v[208:211], v195 offset:39936
	global_load_lds_dwordx4 v[156:157], off
	v_lshl_add_u64 v[156:157], s[94:95], 0, v[180:181]
	s_mov_b32 m0, s69
	s_nop 0
	global_load_lds_dwordx4 v[156:157], off
	s_waitcnt vmcnt(8)
	s_waitcnt lgkmcnt(0)
	s_barrier
	s_waitcnt lgkmcnt(0)
	v_mfma_f32_16x16x32_bf16 v[156:159], v[48:51], v[72:75], v[168:171]
	v_mfma_f32_16x16x32_bf16 v[168:171], v[52:55], v[144:147], v[156:159]
	v_mfma_f32_16x16x32_bf16 v[156:159], v[64:67], v[72:75], v[164:167]
	v_mfma_f32_16x16x32_bf16 v[152:155], v[48:51], v[172:175], v[152:155]
	v_mfma_f32_16x16x32_bf16 v[148:151], v[64:67], v[172:175], v[148:151]
	v_mfma_f32_16x16x32_bf16 v[116:119], v[48:51], v[196:199], v[116:119]
	v_mfma_f32_16x16x32_bf16 v[112:115], v[64:67], v[196:199], v[112:115]
	v_mfma_f32_16x16x32_bf16 v[96:99], v[48:51], v[204:207], v[96:99]
	v_mfma_f32_16x16x32_bf16 v[92:95], v[64:67], v[204:207], v[92:95]
	v_mfma_f32_16x16x32_bf16 v[164:167], v[68:71], v[144:147], v[156:159]
	v_mfma_f32_16x16x32_bf16 v[152:155], v[52:55], v[190:193], v[152:155]
	v_mfma_f32_16x16x32_bf16 v[148:151], v[68:71], v[190:193], v[148:151]
	v_mfma_f32_16x16x32_bf16 v[116:119], v[52:55], v[200:203], v[116:119]
	v_mfma_f32_16x16x32_bf16 v[112:115], v[68:71], v[200:203], v[112:115]
	v_mfma_f32_16x16x32_bf16 v[96:99], v[52:55], v[208:211], v[96:99]
	v_mfma_f32_16x16x32_bf16 v[92:95], v[68:71], v[208:211], v[92:95]
	v_mfma_f32_16x16x32_bf16 v[156:159], v[100:103], v[72:75], v[160:163]
	v_mfma_f32_16x16x32_bf16 v[72:75], v[124:127], v[72:75], v[136:139]
	v_mfma_f32_16x16x32_bf16 v[160:163], v[120:123], v[144:147], v[156:159]
	v_mfma_f32_16x16x32_bf16 v[156:159], v[140:143], v[144:147], v[72:75]
	v_mfma_f32_16x16x32_bf16 v[72:75], v[100:103], v[172:175], v[132:135]
	v_mfma_f32_16x16x32_bf16 v[132:135], v[120:123], v[190:193], v[72:75]
	v_mfma_f32_16x16x32_bf16 v[72:75], v[124:127], v[172:175], v[128:131]
	v_mfma_f32_16x16x32_bf16 v[128:131], v[140:143], v[190:193], v[72:75]
	v_mfma_f32_16x16x32_bf16 v[72:75], v[100:103], v[196:199], v[108:111]
	v_mfma_f32_16x16x32_bf16 v[108:111], v[120:123], v[200:203], v[72:75]
	v_mfma_f32_16x16x32_bf16 v[72:75], v[124:127], v[196:199], v[104:107]
	v_mfma_f32_16x16x32_bf16 v[104:107], v[140:143], v[200:203], v[72:75]
	v_mfma_f32_16x16x32_bf16 v[72:75], v[100:103], v[204:207], v[88:91]
	v_mfma_f32_16x16x32_bf16 v[88:91], v[120:123], v[208:211], v[72:75]
	v_mfma_f32_16x16x32_bf16 v[72:75], v[124:127], v[204:207], v[84:87]
	v_mfma_f32_16x16x32_bf16 v[84:87], v[140:143], v[208:211], v[72:75]
	s_barrier
	s_add_i32 s67, s67, s56
	s_nop 3
	v_lshl_add_u64 v[72:73], v[212:213], 0, s[30:31]
	s_mov_b32 m0, s67
	ds_read_b128 v[136:139], v195 offset:49152
	ds_read_b128 v[144:147], v195 offset:50176
	ds_read_b128 v[172:175], v195 offset:51200
	ds_read_b128 v[190:193], v195 offset:52224
	ds_read_b128 v[196:199], v195 offset:53248
	ds_read_b128 v[200:203], v195 offset:54272
	ds_read_b128 v[204:207], v195 offset:55296
	ds_read_b128 v[208:211], v195 offset:56320
	global_load_lds_dwordx4 v[72:73], off
	s_add_i32 m0, s67, 0x2000
	s_add_u32 s92, s92, 0x80080
	v_lshl_add_u64 v[72:73], v[214:215], 0, s[30:31]
	s_addc_u32 s93, s93, 0
	s_add_i32 s67, s87, s56
	global_load_lds_dwordx4 v[72:73], off
	v_lshl_add_u64 v[72:73], s[92:93], 0, v[178:179]
	s_mov_b32 m0, s67
	s_nop 0
	global_load_lds_dwordx4 v[72:73], off
	v_lshl_add_u64 v[72:73], s[92:93], 0, v[182:183]
	s_add_i32 m0, s67, 0x2000
	s_nop 0
	global_load_lds_dwordx4 v[72:73], off
	v_lshl_add_u64 v[72:73], v[224:225], 0, s[30:31]
	s_mov_b32 m0, s2
	s_nop 0
	global_load_lds_dwordx4 v[72:73], off
	v_lshl_add_u64 v[72:73], v[226:227], 0, s[30:31]
	s_mov_b32 m0, s28
	s_nop 0
	global_load_lds_dwordx4 v[72:73], off
	s_waitcnt vmcnt(8)
	s_waitcnt lgkmcnt(0)
	s_barrier
	s_waitcnt lgkmcnt(0)
	v_mfma_f32_16x16x32_bf16 v[72:75], v[48:51], v[136:139], v[80:83]
	v_mfma_f32_16x16x32_bf16 v[80:83], v[52:55], v[144:147], v[72:75]
	v_mfma_f32_16x16x32_bf16 v[72:75], v[64:67], v[136:139], v[76:79]
	v_mfma_f32_16x16x32_bf16 v[60:63], v[48:51], v[172:175], v[60:63]
	v_mfma_f32_16x16x32_bf16 v[56:59], v[64:67], v[172:175], v[56:59]
	v_mfma_f32_16x16x32_bf16 v[28:31], v[48:51], v[196:199], v[28:31]
	v_mfma_f32_16x16x32_bf16 v[24:27], v[64:67], v[196:199], v[24:27]
	v_mfma_f32_16x16x32_bf16 v[12:15], v[48:51], v[204:207], v[12:15]
	v_mfma_f32_16x16x32_bf16 v[8:11], v[64:67], v[204:207], v[8:11]
	v_mfma_f32_16x16x32_bf16 v[76:79], v[68:71], v[144:147], v[72:75]
	v_mfma_f32_16x16x32_bf16 v[60:63], v[52:55], v[190:193], v[60:63]
	v_mfma_f32_16x16x32_bf16 v[56:59], v[68:71], v[190:193], v[56:59]
	v_mfma_f32_16x16x32_bf16 v[28:31], v[52:55], v[200:203], v[28:31]
	v_mfma_f32_16x16x32_bf16 v[24:27], v[68:71], v[200:203], v[24:27]
	v_mfma_f32_16x16x32_bf16 v[12:15], v[52:55], v[208:211], v[12:15]
	v_mfma_f32_16x16x32_bf16 v[8:11], v[68:71], v[208:211], v[8:11]
	v_mfma_f32_16x16x32_bf16 v[40:43], v[100:103], v[136:139], v[40:43]
	v_mfma_f32_16x16x32_bf16 v[72:75], v[120:123], v[144:147], v[40:43]
	v_mfma_f32_16x16x32_bf16 v[40:43], v[124:127], v[136:139], v[44:47]
	v_mfma_f32_16x16x32_bf16 v[36:39], v[100:103], v[172:175], v[36:39]
	v_mfma_f32_16x16x32_bf16 v[32:35], v[124:127], v[172:175], v[32:35]
	v_mfma_f32_16x16x32_bf16 v[20:23], v[100:103], v[196:199], v[20:23]
	v_mfma_f32_16x16x32_bf16 v[16:19], v[124:127], v[196:199], v[16:19]
	v_mfma_f32_16x16x32_bf16 v[4:7], v[100:103], v[204:207], v[4:7]
	v_mfma_f32_16x16x32_bf16 v[0:3], v[124:127], v[204:207], v[0:3]
	v_mfma_f32_16x16x32_bf16 v[68:71], v[140:143], v[144:147], v[40:43]
	v_mfma_f32_16x16x32_bf16 v[36:39], v[120:123], v[190:193], v[36:39]
	v_mfma_f32_16x16x32_bf16 v[32:35], v[140:143], v[190:193], v[32:35]
	v_mfma_f32_16x16x32_bf16 v[20:23], v[120:123], v[200:203], v[20:23]
	v_mfma_f32_16x16x32_bf16 v[16:19], v[140:143], v[200:203], v[16:19]
	v_mfma_f32_16x16x32_bf16 v[4:7], v[120:123], v[208:211], v[4:7]
	v_mfma_f32_16x16x32_bf16 v[0:3], v[140:143], v[208:211], v[0:3]
	s_barrier
	s_add_i32 s85, s85, 2
	s_add_u32 s10, s10, 0x100
	s_addc_u32 s11, s11, 0
	s_add_u32 s54, s54, 0x100
	s_addc_u32 s55, s55, 0
.LBB0_639:
	s_add_u32 s67, s10, 0xfff80080
	s_addc_u32 s87, s11, -1
	s_add_i32 s96, 0, 0x10000
	s_cmp_eq_u32 s85, 28
	s_cselect_b32 s95, s7, s87
	s_cselect_b32 s94, s9, s67
	s_cselect_b32 s93, s40, s55
	s_cselect_b32 s92, s41, s54
	s_add_i32 s67, 0, 0x14000
	v_add_u32_e32 v52, s96, v194
	v_add_u32_e32 v124, s67, v194
	ds_read_b128 v[40:43], v52
	ds_read_b128 v[44:47], v52 offset:1024
	ds_read_b128 v[48:51], v52 offset:2048
	ds_read_b128 v[52:55], v52 offset:3072
	ds_read_b128 v[64:67], v124
	ds_read_b128 v[100:103], v124 offset:1024
	ds_read_b128 v[120:123], v124 offset:2048
	ds_read_b128 v[124:127], v124 offset:3072
	v_lshl_add_u64 v[208:209], s[10:11], 0, v[186:187]
	s_add_i32 m0, s57, 0xc000
	ds_read_b128 v[136:139], v195
	ds_read_b128 v[140:143], v195 offset:1024
	ds_read_b128 v[144:147], v195 offset:2048
	ds_read_b128 v[172:175], v195 offset:3072
	ds_read_b128 v[190:193], v195 offset:4096
	ds_read_b128 v[196:199], v195 offset:5120
	ds_read_b128 v[200:203], v195 offset:6144
	ds_read_b128 v[204:207], v195 offset:7168
	global_load_lds_dwordx4 v[208:209], off
	v_lshl_add_u64 v[208:209], s[10:11], 0, v[188:189]
	s_add_i32 m0, s57, 0xe000
	s_nop 0
	global_load_lds_dwordx4 v[208:209], off
	s_waitcnt vmcnt(8)
	s_waitcnt lgkmcnt(0)
	s_barrier
	s_waitcnt lgkmcnt(0)
	v_mfma_f32_16x16x32_bf16 v[168:171], v[40:43], v[136:139], v[168:171]
	v_mfma_f32_16x16x32_bf16 v[164:167], v[48:51], v[136:139], v[164:167]
	v_mfma_f32_16x16x32_bf16 v[148:151], v[48:51], v[144:147], v[148:151]
	v_mfma_f32_16x16x32_bf16 v[152:155], v[40:43], v[144:147], v[152:155]
	v_mfma_f32_16x16x32_bf16 v[116:119], v[40:43], v[190:193], v[116:119]
	v_mfma_f32_16x16x32_bf16 v[112:115], v[48:51], v[190:193], v[112:115]
	v_mfma_f32_16x16x32_bf16 v[92:95], v[48:51], v[200:203], v[92:95]
	v_mfma_f32_16x16x32_bf16 v[96:99], v[40:43], v[200:203], v[96:99]
	v_mfma_f32_16x16x32_bf16 v[168:171], v[44:47], v[140:143], v[168:171]
	v_mfma_f32_16x16x32_bf16 v[164:167], v[52:55], v[140:143], v[164:167]
	v_mfma_f32_16x16x32_bf16 v[148:151], v[52:55], v[172:175], v[148:151]
	v_mfma_f32_16x16x32_bf16 v[152:155], v[44:47], v[172:175], v[152:155]
	v_mfma_f32_16x16x32_bf16 v[116:119], v[44:47], v[196:199], v[116:119]
	v_mfma_f32_16x16x32_bf16 v[112:115], v[52:55], v[196:199], v[112:115]
	v_mfma_f32_16x16x32_bf16 v[92:95], v[52:55], v[204:207], v[92:95]
	v_mfma_f32_16x16x32_bf16 v[96:99], v[44:47], v[204:207], v[96:99]
	v_mfma_f32_16x16x32_bf16 v[160:163], v[64:67], v[136:139], v[160:163]
	v_mfma_f32_16x16x32_bf16 v[132:135], v[64:67], v[144:147], v[132:135]
	v_mfma_f32_16x16x32_bf16 v[128:131], v[120:123], v[144:147], v[128:131]
	v_mfma_f32_16x16x32_bf16 v[108:111], v[64:67], v[190:193], v[108:111]
	v_mfma_f32_16x16x32_bf16 v[104:107], v[120:123], v[190:193], v[104:107]
	v_mfma_f32_16x16x32_bf16 v[88:91], v[64:67], v[200:203], v[88:91]
	v_mfma_f32_16x16x32_bf16 v[84:87], v[120:123], v[200:203], v[84:87]
	v_mfma_f32_16x16x32_bf16 v[160:163], v[100:103], v[140:143], v[160:163]
	v_mfma_f32_16x16x32_bf16 v[136:139], v[120:123], v[136:139], v[156:159]
	v_mfma_f32_16x16x32_bf16 v[132:135], v[100:103], v[172:175], v[132:135]
	v_mfma_f32_16x16x32_bf16 v[128:131], v[124:127], v[172:175], v[128:131]
	v_mfma_f32_16x16x32_bf16 v[108:111], v[100:103], v[196:199], v[108:111]
	v_mfma_f32_16x16x32_bf16 v[104:107], v[124:127], v[196:199], v[104:107]
	v_mfma_f32_16x16x32_bf16 v[88:91], v[100:103], v[204:207], v[88:91]
	v_mfma_f32_16x16x32_bf16 v[84:87], v[124:127], v[204:207], v[84:87]
	v_mfma_f32_16x16x32_bf16 v[136:139], v[124:127], v[140:143], v[136:139]
	s_barrier
	s_add_i32 s87, s96, s56
	v_lshl_add_u64 v[212:213], s[92:93], 0, v[178:179]
	s_mov_b32 m0, s87
	ds_read_b128 v[140:143], v195 offset:16384
	ds_read_b128 v[144:147], v195 offset:17408
	ds_read_b128 v[156:159], v195 offset:18432
	ds_read_b128 v[172:175], v195 offset:19456
	ds_read_b128 v[190:193], v195 offset:20480
	ds_read_b128 v[196:199], v195 offset:21504
	ds_read_b128 v[200:203], v195 offset:22528
	ds_read_b128 v[204:207], v195 offset:23552
	global_load_lds_dwordx4 v[212:213], off
	s_add_i32 m0, s87, 0x2000
	s_add_u32 vcc_lo, s92, 0x80000
	v_lshl_add_u64 v[214:215], s[92:93], 0, v[182:183]
	s_addc_u32 vcc_hi, s93, 0
	s_add_i32 s67, s67, s56
	global_load_lds_dwordx4 v[214:215], off
	v_lshl_add_u64 v[208:209], vcc, 0, v[178:179]
	s_mov_b32 m0, s67
	v_lshl_add_u64 v[224:225], s[94:95], 0, v[176:177]
	global_load_lds_dwordx4 v[208:209], off
	v_lshl_add_u64 v[208:209], vcc, 0, v[182:183]
	s_add_i32 m0, s67, 0x2000
	v_lshl_add_u64 v[226:227], s[94:95], 0, v[180:181]
	global_load_lds_dwordx4 v[208:209], off
	s_mov_b32 m0, s57
	s_nop 0
	global_load_lds_dwordx4 v[224:225], off
	s_mov_b32 m0, s61
	s_nop 0
	global_load_lds_dwordx4 v[226:227], off
	s_waitcnt vmcnt(8)
	s_waitcnt lgkmcnt(0)
	s_barrier
	s_waitcnt lgkmcnt(0)
	v_mfma_f32_16x16x32_bf16 v[80:83], v[40:43], v[140:143], v[80:83]
	v_mfma_f32_16x16x32_bf16 v[76:79], v[48:51], v[140:143], v[76:79]
	v_mfma_f32_16x16x32_bf16 v[56:59], v[48:51], v[156:159], v[56:59]
	v_mfma_f32_16x16x32_bf16 v[60:63], v[40:43], v[156:159], v[60:63]
	v_mfma_f32_16x16x32_bf16 v[28:31], v[40:43], v[190:193], v[28:31]
	v_mfma_f32_16x16x32_bf16 v[24:27], v[48:51], v[190:193], v[24:27]
	v_mfma_f32_16x16x32_bf16 v[8:11], v[48:51], v[200:203], v[8:11]
	v_mfma_f32_16x16x32_bf16 v[12:15], v[40:43], v[200:203], v[12:15]
	v_mfma_f32_16x16x32_bf16 v[80:83], v[44:47], v[144:147], v[80:83]
	v_mfma_f32_16x16x32_bf16 v[76:79], v[52:55], v[144:147], v[76:79]
	v_mfma_f32_16x16x32_bf16 v[56:59], v[52:55], v[172:175], v[56:59]
	v_mfma_f32_16x16x32_bf16 v[60:63], v[44:47], v[172:175], v[60:63]
	v_mfma_f32_16x16x32_bf16 v[28:31], v[44:47], v[196:199], v[28:31]
	v_mfma_f32_16x16x32_bf16 v[24:27], v[52:55], v[196:199], v[24:27]
	v_mfma_f32_16x16x32_bf16 v[8:11], v[52:55], v[204:207], v[8:11]
	v_mfma_f32_16x16x32_bf16 v[12:15], v[44:47], v[204:207], v[12:15]
	v_mfma_f32_16x16x32_bf16 v[36:39], v[64:67], v[156:159], v[36:39]
	v_mfma_f32_16x16x32_bf16 v[32:35], v[120:123], v[156:159], v[32:35]
	v_mfma_f32_16x16x32_bf16 v[16:19], v[120:123], v[190:193], v[16:19]
	v_mfma_f32_16x16x32_bf16 v[20:23], v[64:67], v[190:193], v[20:23]
	v_mfma_f32_16x16x32_bf16 v[4:7], v[64:67], v[200:203], v[4:7]
	v_mfma_f32_16x16x32_bf16 v[0:3], v[120:123], v[200:203], v[0:3]
	v_mfma_f32_16x16x32_bf16 v[44:47], v[120:123], v[140:143], v[68:71]
	v_mfma_f32_16x16x32_bf16 v[40:43], v[64:67], v[140:143], v[72:75]
	v_mfma_f32_16x16x32_bf16 v[36:39], v[100:103], v[172:175], v[36:39]
	v_mfma_f32_16x16x32_bf16 v[32:35], v[124:127], v[172:175], v[32:35]
	v_mfma_f32_16x16x32_bf16 v[16:19], v[124:127], v[196:199], v[16:19]
	v_mfma_f32_16x16x32_bf16 v[20:23], v[100:103], v[196:199], v[20:23]
	v_mfma_f32_16x16x32_bf16 v[4:7], v[100:103], v[204:207], v[4:7]
	v_mfma_f32_16x16x32_bf16 v[0:3], v[124:127], v[204:207], v[0:3]
	v_mfma_f32_16x16x32_bf16 v[44:47], v[124:127], v[144:147], v[44:47]
	v_mfma_f32_16x16x32_bf16 v[40:43], v[100:103], v[144:147], v[40:43]
	s_barrier
	s_add_i32 s67, 0, 0x18000
	s_add_i32 s87, 0, 0x1c000
	v_add_u32_e32 v68, s67, v194
	v_add_u32_e32 v72, s87, v194
	ds_read_b128 v[48:51], v68
	ds_read_b128 v[52:55], v68 offset:1024
	ds_read_b128 v[64:67], v68 offset:2048
	ds_read_b128 v[68:71], v68 offset:3072
	ds_read_b128 v[100:103], v72
	ds_read_b128 v[120:123], v72 offset:1024
	ds_read_b128 v[124:127], v72 offset:2048
	ds_read_b128 v[140:143], v72 offset:3072
	s_add_u32 s94, s94, 0x80000
	s_addc_u32 s95, s95, 0
	s_mov_b32 m0, s68
	v_lshl_add_u64 v[156:157], s[94:95], 0, v[176:177]
	ds_read_b128 v[72:75], v195 offset:32768
	ds_read_b128 v[144:147], v195 offset:33792
	ds_read_b128 v[172:175], v195 offset:34816
	ds_read_b128 v[190:193], v195 offset:35840
	ds_read_b128 v[196:199], v195 offset:36864
	ds_read_b128 v[200:203], v195 offset:37888
	ds_read_b128 v[204:207], v195 offset:38912
	ds_read_b128 v[208:211], v195 offset:39936
	global_load_lds_dwordx4 v[156:157], off
	v_lshl_add_u64 v[156:157], s[94:95], 0, v[180:181]
	s_mov_b32 m0, s69
	s_nop 0
	global_load_lds_dwordx4 v[156:157], off
	s_waitcnt vmcnt(8)
	s_waitcnt lgkmcnt(0)
	s_barrier
	s_waitcnt lgkmcnt(0)
	v_mfma_f32_16x16x32_bf16 v[156:159], v[48:51], v[72:75], v[168:171]
	v_mfma_f32_16x16x32_bf16 v[168:171], v[52:55], v[144:147], v[156:159]
	v_mfma_f32_16x16x32_bf16 v[156:159], v[64:67], v[72:75], v[164:167]
	v_mfma_f32_16x16x32_bf16 v[152:155], v[48:51], v[172:175], v[152:155]
	v_mfma_f32_16x16x32_bf16 v[148:151], v[64:67], v[172:175], v[148:151]
	v_mfma_f32_16x16x32_bf16 v[116:119], v[48:51], v[196:199], v[116:119]
	v_mfma_f32_16x16x32_bf16 v[112:115], v[64:67], v[196:199], v[112:115]
	v_mfma_f32_16x16x32_bf16 v[96:99], v[48:51], v[204:207], v[96:99]
	v_mfma_f32_16x16x32_bf16 v[92:95], v[64:67], v[204:207], v[92:95]
	v_mfma_f32_16x16x32_bf16 v[164:167], v[68:71], v[144:147], v[156:159]
	v_mfma_f32_16x16x32_bf16 v[152:155], v[52:55], v[190:193], v[152:155]
	v_mfma_f32_16x16x32_bf16 v[148:151], v[68:71], v[190:193], v[148:151]
	v_mfma_f32_16x16x32_bf16 v[116:119], v[52:55], v[200:203], v[116:119]
	v_mfma_f32_16x16x32_bf16 v[112:115], v[68:71], v[200:203], v[112:115]
	v_mfma_f32_16x16x32_bf16 v[96:99], v[52:55], v[208:211], v[96:99]
	v_mfma_f32_16x16x32_bf16 v[92:95], v[68:71], v[208:211], v[92:95]
	v_mfma_f32_16x16x32_bf16 v[156:159], v[100:103], v[72:75], v[160:163]
	v_mfma_f32_16x16x32_bf16 v[72:75], v[124:127], v[72:75], v[136:139]
	v_mfma_f32_16x16x32_bf16 v[160:163], v[120:123], v[144:147], v[156:159]
	v_mfma_f32_16x16x32_bf16 v[156:159], v[140:143], v[144:147], v[72:75]
	v_mfma_f32_16x16x32_bf16 v[72:75], v[100:103], v[172:175], v[132:135]
	v_mfma_f32_16x16x32_bf16 v[132:135], v[120:123], v[190:193], v[72:75]
	v_mfma_f32_16x16x32_bf16 v[72:75], v[124:127], v[172:175], v[128:131]
	v_mfma_f32_16x16x32_bf16 v[128:131], v[140:143], v[190:193], v[72:75]
	v_mfma_f32_16x16x32_bf16 v[72:75], v[100:103], v[196:199], v[108:111]
	v_mfma_f32_16x16x32_bf16 v[108:111], v[120:123], v[200:203], v[72:75]
	v_mfma_f32_16x16x32_bf16 v[72:75], v[124:127], v[196:199], v[104:107]
	v_mfma_f32_16x16x32_bf16 v[104:107], v[140:143], v[200:203], v[72:75]
	v_mfma_f32_16x16x32_bf16 v[72:75], v[100:103], v[204:207], v[88:91]
	v_mfma_f32_16x16x32_bf16 v[88:91], v[120:123], v[208:211], v[72:75]
	v_mfma_f32_16x16x32_bf16 v[72:75], v[124:127], v[204:207], v[84:87]
	v_mfma_f32_16x16x32_bf16 v[84:87], v[140:143], v[208:211], v[72:75]
	s_barrier
	s_add_i32 s67, s67, s56
	s_nop 3
	v_lshl_add_u64 v[72:73], v[212:213], 0, s[30:31]
	s_mov_b32 m0, s67
	ds_read_b128 v[136:139], v195 offset:49152
	ds_read_b128 v[144:147], v195 offset:50176
	ds_read_b128 v[172:175], v195 offset:51200
	ds_read_b128 v[190:193], v195 offset:52224
	ds_read_b128 v[196:199], v195 offset:53248
	ds_read_b128 v[200:203], v195 offset:54272
	ds_read_b128 v[204:207], v195 offset:55296
	ds_read_b128 v[208:211], v195 offset:56320
	global_load_lds_dwordx4 v[72:73], off
	s_add_i32 m0, s67, 0x2000
	s_add_u32 s92, s92, 0x80080
	v_lshl_add_u64 v[72:73], v[214:215], 0, s[30:31]
	s_addc_u32 s93, s93, 0
	s_add_i32 s67, s87, s56
	global_load_lds_dwordx4 v[72:73], off
	v_lshl_add_u64 v[72:73], s[92:93], 0, v[178:179]
	s_mov_b32 m0, s67
	s_nop 0
	global_load_lds_dwordx4 v[72:73], off
	v_lshl_add_u64 v[72:73], s[92:93], 0, v[182:183]
	s_add_i32 m0, s67, 0x2000
	s_nop 0
	global_load_lds_dwordx4 v[72:73], off
	v_lshl_add_u64 v[72:73], v[224:225], 0, s[30:31]
	s_mov_b32 m0, s2
	s_nop 0
	global_load_lds_dwordx4 v[72:73], off
	v_lshl_add_u64 v[72:73], v[226:227], 0, s[30:31]
	s_mov_b32 m0, s28
	s_nop 0
	global_load_lds_dwordx4 v[72:73], off
	s_waitcnt vmcnt(8)
	s_waitcnt lgkmcnt(0)
	s_barrier
	s_waitcnt lgkmcnt(0)
	v_mfma_f32_16x16x32_bf16 v[72:75], v[48:51], v[136:139], v[80:83]
	v_mfma_f32_16x16x32_bf16 v[80:83], v[52:55], v[144:147], v[72:75]
	v_mfma_f32_16x16x32_bf16 v[72:75], v[64:67], v[136:139], v[76:79]
	v_mfma_f32_16x16x32_bf16 v[60:63], v[48:51], v[172:175], v[60:63]
	v_mfma_f32_16x16x32_bf16 v[56:59], v[64:67], v[172:175], v[56:59]
	v_mfma_f32_16x16x32_bf16 v[28:31], v[48:51], v[196:199], v[28:31]
	v_mfma_f32_16x16x32_bf16 v[24:27], v[64:67], v[196:199], v[24:27]
	v_mfma_f32_16x16x32_bf16 v[12:15], v[48:51], v[204:207], v[12:15]
	v_mfma_f32_16x16x32_bf16 v[8:11], v[64:67], v[204:207], v[8:11]
	v_mfma_f32_16x16x32_bf16 v[76:79], v[68:71], v[144:147], v[72:75]
	v_mfma_f32_16x16x32_bf16 v[60:63], v[52:55], v[190:193], v[60:63]
	v_mfma_f32_16x16x32_bf16 v[56:59], v[68:71], v[190:193], v[56:59]
	v_mfma_f32_16x16x32_bf16 v[28:31], v[52:55], v[200:203], v[28:31]
	v_mfma_f32_16x16x32_bf16 v[24:27], v[68:71], v[200:203], v[24:27]
	v_mfma_f32_16x16x32_bf16 v[12:15], v[52:55], v[208:211], v[12:15]
	v_mfma_f32_16x16x32_bf16 v[8:11], v[68:71], v[208:211], v[8:11]
	v_mfma_f32_16x16x32_bf16 v[40:43], v[100:103], v[136:139], v[40:43]
	v_mfma_f32_16x16x32_bf16 v[72:75], v[120:123], v[144:147], v[40:43]
	v_mfma_f32_16x16x32_bf16 v[40:43], v[124:127], v[136:139], v[44:47]
	v_mfma_f32_16x16x32_bf16 v[36:39], v[100:103], v[172:175], v[36:39]
	v_mfma_f32_16x16x32_bf16 v[32:35], v[124:127], v[172:175], v[32:35]
	v_mfma_f32_16x16x32_bf16 v[20:23], v[100:103], v[196:199], v[20:23]
	v_mfma_f32_16x16x32_bf16 v[16:19], v[124:127], v[196:199], v[16:19]
	v_mfma_f32_16x16x32_bf16 v[4:7], v[100:103], v[204:207], v[4:7]
	v_mfma_f32_16x16x32_bf16 v[0:3], v[124:127], v[204:207], v[0:3]
	v_mfma_f32_16x16x32_bf16 v[68:71], v[140:143], v[144:147], v[40:43]
	v_mfma_f32_16x16x32_bf16 v[36:39], v[120:123], v[190:193], v[36:39]
	v_mfma_f32_16x16x32_bf16 v[32:35], v[140:143], v[190:193], v[32:35]
	v_mfma_f32_16x16x32_bf16 v[20:23], v[120:123], v[200:203], v[20:23]
	v_mfma_f32_16x16x32_bf16 v[16:19], v[140:143], v[200:203], v[16:19]
	v_mfma_f32_16x16x32_bf16 v[4:7], v[120:123], v[208:211], v[4:7]
	v_mfma_f32_16x16x32_bf16 v[0:3], v[140:143], v[208:211], v[0:3]
	s_barrier
	s_add_i32 s85, s85, 2
	s_add_u32 s10, s10, 0x100
	s_addc_u32 s11, s11, 0
	s_add_u32 s54, s54, 0x100
	s_addc_u32 s55, s55, 0
	s_cmp_gt_u32 s85, 29
	s_cbranch_scc0 .LBB0_639
	s_and_b64 vcc, exec, s[80:81]
	s_cbranch_vccz .LBB0_642
	s_barrier

.LBB0_964:
	s_ashr_i32 s79, s78, 31
	s_lshl_b64 s[82:83], s[78:79], 20
	s_add_u32 s82, s14, s82
	s_addc_u32 s83, s15, s83
	s_and_b64 s[84:85], s[80:81], exec
	s_cselect_b32 s79, s83, s93
	s_cselect_b32 s96, s82, s92
	s_ashr_i32 s77, s76, 31
	s_lshl_b64 s[84:85], s[76:77], 20
	s_add_u32 s84, s24, s84
	s_addc_u32 s85, s26, s85
	s_and_b64 vcc, s[80:81], exec
	s_cselect_b32 s77, s85, s91
	s_cselect_b32 vcc_lo, s84, s90
	s_lshl_b32 s86, s86, 8
	s_ashr_i32 s87, s86, 31
	s_lshl_b64 s[74:75], s[86:87], 2
	s_add_u32 s74, s88, s74
	s_addc_u32 s75, s89, s75
	s_add_i32 m0, s71, s40
	s_add_u32 s88, s92, 0x80080
	global_load_lds_dwordx4 v239, s[74:75]
	s_addc_u32 s89, s93, 0
	s_add_u32 s87, s90, 0x100
	s_addc_u32 vcc_hi, s91, 0
	s_mov_b32 s71, -2
	s_waitcnt vmcnt(0)
	s_add_u32 s67, s88, 0xfff80080
	s_addc_u32 s74, s89, -1
	s_add_i32 s75, 0, 0x10000
	s_cmp_eq_u32 s71, 28
	s_cselect_b32 s93, s79, s74
	s_cselect_b32 s92, s96, s67
	s_cselect_b32 s91, s77, vcc_hi
	s_cselect_b32 s90, vcc_lo, s87
	s_add_i32 s67, 0, 0x14000
	v_add_u32_e32 v96, s75, v238
	v_add_u32_e32 v140, s67, v238
	ds_read_b128 v[64:67], v96
	ds_read_b128 v[72:75], v96 offset:1024
	ds_read_b128 v[88:91], v96 offset:2048
	ds_read_b128 v[96:99], v96 offset:3072
	ds_read_b128 v[108:111], v140
	ds_read_b128 v[116:119], v140 offset:1024
	ds_read_b128 v[128:131], v140 offset:2048
	ds_read_b128 v[140:143], v140 offset:3072
	v_lshl_add_u64 v[192:193], s[88:89], 0, v[230:231]
	s_add_i32 m0, s28, 0xc000
	ds_read_b128 v[152:155], v240
	ds_read_b128 v[156:159], v240 offset:1024
	ds_read_b128 v[160:163], v240 offset:2048
	ds_read_b128 v[164:167], v240 offset:3072
	ds_read_b128 v[168:171], v240 offset:4096
	ds_read_b128 v[180:183], v240 offset:5120
	ds_read_b128 v[184:187], v240 offset:6144
	ds_read_b128 v[188:191], v240 offset:7168
	global_load_lds_dwordx4 v[192:193], off
	v_lshl_add_u64 v[192:193], s[88:89], 0, v[232:233]
	s_add_i32 m0, s28, 0xe000
	s_nop 0
	global_load_lds_dwordx4 v[192:193], off
	s_waitcnt vmcnt(8)
	s_waitcnt lgkmcnt(0)
	s_barrier
	s_waitcnt lgkmcnt(0)
	v_mfma_f32_16x16x32_bf16 v[176:179], v[64:67], v[152:155], 0
	v_mfma_f32_16x16x32_bf16 v[172:175], v[88:91], v[152:155], 0
	v_mfma_f32_16x16x32_bf16 v[132:135], v[88:91], v[160:163], 0
	v_mfma_f32_16x16x32_bf16 v[136:139], v[64:67], v[160:163], 0
	v_mfma_f32_16x16x32_bf16 v[112:115], v[64:67], v[168:171], 0
	v_mfma_f32_16x16x32_bf16 v[104:107], v[88:91], v[168:171], 0
	v_mfma_f32_16x16x32_bf16 v[80:83], v[88:91], v[184:187], 0
	v_mfma_f32_16x16x32_bf16 v[84:87], v[64:67], v[184:187], 0
	v_mfma_f32_16x16x32_bf16 v[176:179], v[72:75], v[156:159], v[176:179]
	v_mfma_f32_16x16x32_bf16 v[172:175], v[96:99], v[156:159], v[172:175]
	v_mfma_f32_16x16x32_bf16 v[132:135], v[96:99], v[164:167], v[132:135]
	v_mfma_f32_16x16x32_bf16 v[136:139], v[72:75], v[164:167], v[136:139]
	v_mfma_f32_16x16x32_bf16 v[112:115], v[72:75], v[180:183], v[112:115]
	v_mfma_f32_16x16x32_bf16 v[104:107], v[96:99], v[180:183], v[104:107]
	v_mfma_f32_16x16x32_bf16 v[80:83], v[96:99], v[188:191], v[80:83]
	v_mfma_f32_16x16x32_bf16 v[84:87], v[72:75], v[188:191], v[84:87]
	v_mfma_f32_16x16x32_bf16 v[148:151], v[108:111], v[152:155], 0
	v_mfma_f32_16x16x32_bf16 v[144:147], v[128:131], v[152:155], 0
	v_mfma_f32_16x16x32_bf16 v[120:123], v[128:131], v[160:163], 0
	v_mfma_f32_16x16x32_bf16 v[124:127], v[108:111], v[160:163], 0
	v_mfma_f32_16x16x32_bf16 v[100:103], v[108:111], v[168:171], 0
	v_mfma_f32_16x16x32_bf16 v[92:95], v[128:131], v[168:171], 0
	v_mfma_f32_16x16x32_bf16 v[68:71], v[128:131], v[184:187], 0
	v_mfma_f32_16x16x32_bf16 v[76:79], v[108:111], v[184:187], 0
	v_mfma_f32_16x16x32_bf16 v[148:151], v[116:119], v[156:159], v[148:151]
	v_mfma_f32_16x16x32_bf16 v[144:147], v[140:143], v[156:159], v[144:147]
	v_mfma_f32_16x16x32_bf16 v[120:123], v[140:143], v[164:167], v[120:123]
	v_mfma_f32_16x16x32_bf16 v[124:127], v[116:119], v[164:167], v[124:127]
	v_mfma_f32_16x16x32_bf16 v[100:103], v[116:119], v[180:183], v[100:103]
	v_mfma_f32_16x16x32_bf16 v[92:95], v[140:143], v[180:183], v[92:95]
	v_mfma_f32_16x16x32_bf16 v[68:71], v[140:143], v[188:191], v[68:71]
	v_mfma_f32_16x16x32_bf16 v[76:79], v[116:119], v[188:191], v[76:79]
	s_barrier
	s_add_i32 s74, s75, s2
	v_lshl_add_u64 v[192:193], s[90:91], 0, v[216:217]
	s_mov_b32 m0, s74
	ds_read_b128 v[152:155], v240 offset:16384
	ds_read_b128 v[156:159], v240 offset:17408
	ds_read_b128 v[160:163], v240 offset:18432
	ds_read_b128 v[164:167], v240 offset:19456
	ds_read_b128 v[168:171], v240 offset:20480
	ds_read_b128 v[180:183], v240 offset:21504
	ds_read_b128 v[184:187], v240 offset:22528
	ds_read_b128 v[188:191], v240 offset:23552
	global_load_lds_dwordx4 v[192:193], off
	s_add_i32 m0, s74, 0x2000
	s_add_u32 s74, s90, 0x80000
	v_lshl_add_u64 v[194:195], s[90:91], 0, v[228:229]
	s_addc_u32 s75, s91, 0
	s_add_i32 s67, s67, s2
	global_load_lds_dwordx4 v[194:195], off
	v_lshl_add_u64 v[196:197], s[74:75], 0, v[216:217]
	s_mov_b32 m0, s67
	v_lshl_add_u64 v[198:199], s[92:93], 0, v[226:227]
	global_load_lds_dwordx4 v[196:197], off
	v_lshl_add_u64 v[196:197], s[74:75], 0, v[228:229]
	s_add_i32 m0, s67, 0x2000
	s_nop 0
	global_load_lds_dwordx4 v[196:197], off
	v_lshl_add_u64 v[196:197], s[92:93], 0, v[224:225]
	s_mov_b32 m0, s28
	s_nop 0
	global_load_lds_dwordx4 v[196:197], off
	s_mov_b32 m0, s29
	s_nop 0
	global_load_lds_dwordx4 v[198:199], off
	s_waitcnt vmcnt(8)
	s_waitcnt lgkmcnt(0)
	s_barrier
	s_waitcnt lgkmcnt(0)
	v_mfma_f32_16x16x32_bf16 v[60:63], v[64:67], v[152:155], 0
	v_mfma_f32_16x16x32_bf16 v[56:59], v[88:91], v[152:155], 0
	v_mfma_f32_16x16x32_bf16 v[40:43], v[88:91], v[160:163], 0
	v_mfma_f32_16x16x32_bf16 v[44:47], v[64:67], v[160:163], 0
	v_mfma_f32_16x16x32_bf16 v[28:31], v[64:67], v[168:171], 0
	v_mfma_f32_16x16x32_bf16 v[24:27], v[88:91], v[168:171], 0
	v_mfma_f32_16x16x32_bf16 v[8:11], v[88:91], v[184:187], 0
	v_mfma_f32_16x16x32_bf16 v[12:15], v[64:67], v[184:187], 0
	v_mfma_f32_16x16x32_bf16 v[60:63], v[72:75], v[156:159], v[60:63]
	v_mfma_f32_16x16x32_bf16 v[56:59], v[96:99], v[156:159], v[56:59]
	v_mfma_f32_16x16x32_bf16 v[40:43], v[96:99], v[164:167], v[40:43]
	v_mfma_f32_16x16x32_bf16 v[44:47], v[72:75], v[164:167], v[44:47]
	v_mfma_f32_16x16x32_bf16 v[28:31], v[72:75], v[180:183], v[28:31]
	v_mfma_f32_16x16x32_bf16 v[24:27], v[96:99], v[180:183], v[24:27]
	v_mfma_f32_16x16x32_bf16 v[8:11], v[96:99], v[188:191], v[8:11]
	v_mfma_f32_16x16x32_bf16 v[12:15], v[72:75], v[188:191], v[12:15]
	v_mfma_f32_16x16x32_bf16 v[52:55], v[108:111], v[152:155], 0
	v_mfma_f32_16x16x32_bf16 v[48:51], v[128:131], v[152:155], 0
	v_mfma_f32_16x16x32_bf16 v[32:35], v[128:131], v[160:163], 0
	v_mfma_f32_16x16x32_bf16 v[36:39], v[108:111], v[160:163], 0
	v_mfma_f32_16x16x32_bf16 v[20:23], v[108:111], v[168:171], 0
	v_mfma_f32_16x16x32_bf16 v[16:19], v[128:131], v[168:171], 0
	v_mfma_f32_16x16x32_bf16 v[0:3], v[128:131], v[184:187], 0
	v_mfma_f32_16x16x32_bf16 v[4:7], v[108:111], v[184:187], 0
	v_mfma_f32_16x16x32_bf16 v[52:55], v[116:119], v[156:159], v[52:55]
	v_mfma_f32_16x16x32_bf16 v[48:51], v[140:143], v[156:159], v[48:51]
	v_mfma_f32_16x16x32_bf16 v[32:35], v[140:143], v[164:167], v[32:35]
	v_mfma_f32_16x16x32_bf16 v[36:39], v[116:119], v[164:167], v[36:39]
	v_mfma_f32_16x16x32_bf16 v[20:23], v[116:119], v[180:183], v[20:23]
	v_mfma_f32_16x16x32_bf16 v[16:19], v[140:143], v[180:183], v[16:19]
	v_mfma_f32_16x16x32_bf16 v[0:3], v[140:143], v[188:191], v[0:3]
	v_mfma_f32_16x16x32_bf16 v[4:7], v[116:119], v[188:191], v[4:7]
	s_barrier
	s_add_i32 s67, 0, 0x18000
	s_add_i32 s3, 0, 0x1c000
	v_add_u32_e32 v96, s67, v238
	v_add_u32_e32 v140, s3, v238
	ds_read_b128 v[64:67], v96
	ds_read_b128 v[72:75], v96 offset:1024
	ds_read_b128 v[88:91], v96 offset:2048
	ds_read_b128 v[96:99], v96 offset:3072
	ds_read_b128 v[108:111], v140
	ds_read_b128 v[116:119], v140 offset:1024
	ds_read_b128 v[128:131], v140 offset:2048
	ds_read_b128 v[140:143], v140 offset:3072
	s_add_u32 s74, s92, 0x80000
	s_addc_u32 s75, s93, 0
	s_mov_b32 m0, s34
	v_lshl_add_u64 v[200:201], s[74:75], 0, v[224:225]
	ds_read_b128 v[152:155], v240 offset:32768
	ds_read_b128 v[156:159], v240 offset:33792
	ds_read_b128 v[160:163], v240 offset:34816
	ds_read_b128 v[164:167], v240 offset:35840
	ds_read_b128 v[168:171], v240 offset:36864
	ds_read_b128 v[180:183], v240 offset:37888
	ds_read_b128 v[184:187], v240 offset:38912
	ds_read_b128 v[188:191], v240 offset:39936
	global_load_lds_dwordx4 v[200:201], off
	v_lshl_add_u64 v[200:201], s[74:75], 0, v[226:227]
	s_mov_b32 m0, s35
	s_nop 0
	global_load_lds_dwordx4 v[200:201], off
	s_waitcnt vmcnt(8)
	s_waitcnt lgkmcnt(0)
	s_barrier
	s_waitcnt lgkmcnt(0)
	v_mfma_f32_16x16x32_bf16 v[176:179], v[64:67], v[152:155], v[176:179]
	v_mfma_f32_16x16x32_bf16 v[172:175], v[88:91], v[152:155], v[172:175]
	v_mfma_f32_16x16x32_bf16 v[132:135], v[88:91], v[160:163], v[132:135]
	v_mfma_f32_16x16x32_bf16 v[136:139], v[64:67], v[160:163], v[136:139]
	v_mfma_f32_16x16x32_bf16 v[112:115], v[64:67], v[168:171], v[112:115]
	v_mfma_f32_16x16x32_bf16 v[104:107], v[88:91], v[168:171], v[104:107]
	v_mfma_f32_16x16x32_bf16 v[80:83], v[88:91], v[184:187], v[80:83]
	v_mfma_f32_16x16x32_bf16 v[84:87], v[64:67], v[184:187], v[84:87]
	v_mfma_f32_16x16x32_bf16 v[176:179], v[72:75], v[156:159], v[176:179]
	v_mfma_f32_16x16x32_bf16 v[172:175], v[96:99], v[156:159], v[172:175]
	v_mfma_f32_16x16x32_bf16 v[132:135], v[96:99], v[164:167], v[132:135]
	v_mfma_f32_16x16x32_bf16 v[136:139], v[72:75], v[164:167], v[136:139]
	v_mfma_f32_16x16x32_bf16 v[112:115], v[72:75], v[180:183], v[112:115]
	v_mfma_f32_16x16x32_bf16 v[104:107], v[96:99], v[180:183], v[104:107]
	v_mfma_f32_16x16x32_bf16 v[80:83], v[96:99], v[188:191], v[80:83]
	v_mfma_f32_16x16x32_bf16 v[84:87], v[72:75], v[188:191], v[84:87]
	v_mfma_f32_16x16x32_bf16 v[148:151], v[108:111], v[152:155], v[148:151]
	v_mfma_f32_16x16x32_bf16 v[144:147], v[128:131], v[152:155], v[144:147]
	v_mfma_f32_16x16x32_bf16 v[120:123], v[128:131], v[160:163], v[120:123]
	v_mfma_f32_16x16x32_bf16 v[124:127], v[108:111], v[160:163], v[124:127]
	v_mfma_f32_16x16x32_bf16 v[100:103], v[108:111], v[168:171], v[100:103]
	v_mfma_f32_16x16x32_bf16 v[92:95], v[128:131], v[168:171], v[92:95]
	v_mfma_f32_16x16x32_bf16 v[68:71], v[128:131], v[184:187], v[68:71]
	v_mfma_f32_16x16x32_bf16 v[76:79], v[108:111], v[184:187], v[76:79]
	v_mfma_f32_16x16x32_bf16 v[148:151], v[116:119], v[156:159], v[148:151]
	v_mfma_f32_16x16x32_bf16 v[144:147], v[140:143], v[156:159], v[144:147]
	v_mfma_f32_16x16x32_bf16 v[120:123], v[140:143], v[164:167], v[120:123]
	v_mfma_f32_16x16x32_bf16 v[124:127], v[116:119], v[164:167], v[124:127]
	v_mfma_f32_16x16x32_bf16 v[100:103], v[116:119], v[180:183], v[100:103]
	v_mfma_f32_16x16x32_bf16 v[92:95], v[140:143], v[180:183], v[92:95]
	v_mfma_f32_16x16x32_bf16 v[68:71], v[140:143], v[188:191], v[68:71]
	v_mfma_f32_16x16x32_bf16 v[76:79], v[116:119], v[188:191], v[76:79]
	s_barrier
	s_add_i32 s67, s67, s2
	v_lshl_add_u64 v[192:193], v[192:193], 0, s[30:31]
	s_mov_b32 m0, s67
	ds_read_b128 v[152:155], v240 offset:49152
	ds_read_b128 v[156:159], v240 offset:50176
	ds_read_b128 v[160:163], v240 offset:51200
	ds_read_b128 v[164:167], v240 offset:52224
	ds_read_b128 v[168:171], v240 offset:53248
	ds_read_b128 v[180:183], v240 offset:54272
	ds_read_b128 v[184:187], v240 offset:55296
	ds_read_b128 v[188:191], v240 offset:56320
	global_load_lds_dwordx4 v[192:193], off
	s_add_i32 m0, s67, 0x2000
	s_add_u32 s74, s90, 0x80080
	v_lshl_add_u64 v[192:193], v[194:195], 0, s[30:31]
	s_addc_u32 s75, s91, 0
	s_add_i32 s3, s3, s2
	global_load_lds_dwordx4 v[192:193], off
	v_lshl_add_u64 v[192:193], s[74:75], 0, v[216:217]
	s_mov_b32 m0, s3
	s_nop 0
	global_load_lds_dwordx4 v[192:193], off
	v_lshl_add_u64 v[192:193], s[74:75], 0, v[228:229]
	s_add_i32 m0, s3, 0x2000
	s_nop 0
	global_load_lds_dwordx4 v[192:193], off
	v_lshl_add_u64 v[192:193], v[196:197], 0, s[30:31]
	s_mov_b32 m0, s60
	s_nop 0
	global_load_lds_dwordx4 v[192:193], off
	v_lshl_add_u64 v[192:193], v[198:199], 0, s[30:31]
	s_mov_b32 m0, s61
	s_nop 0
	global_load_lds_dwordx4 v[192:193], off
	s_waitcnt vmcnt(8)
	s_waitcnt lgkmcnt(0)
	s_barrier
	s_waitcnt lgkmcnt(0)
	v_mfma_f32_16x16x32_bf16 v[60:63], v[64:67], v[152:155], v[60:63]
	v_mfma_f32_16x16x32_bf16 v[56:59], v[88:91], v[152:155], v[56:59]
	v_mfma_f32_16x16x32_bf16 v[40:43], v[88:91], v[160:163], v[40:43]
	v_mfma_f32_16x16x32_bf16 v[44:47], v[64:67], v[160:163], v[44:47]
	v_mfma_f32_16x16x32_bf16 v[28:31], v[64:67], v[168:171], v[28:31]
	v_mfma_f32_16x16x32_bf16 v[24:27], v[88:91], v[168:171], v[24:27]
	v_mfma_f32_16x16x32_bf16 v[8:11], v[88:91], v[184:187], v[8:11]
	v_mfma_f32_16x16x32_bf16 v[12:15], v[64:67], v[184:187], v[12:15]
	v_mfma_f32_16x16x32_bf16 v[60:63], v[72:75], v[156:159], v[60:63]
	v_mfma_f32_16x16x32_bf16 v[56:59], v[96:99], v[156:159], v[56:59]
	v_mfma_f32_16x16x32_bf16 v[40:43], v[96:99], v[164:167], v[40:43]
	v_mfma_f32_16x16x32_bf16 v[44:47], v[72:75], v[164:167], v[44:47]
	v_mfma_f32_16x16x32_bf16 v[28:31], v[72:75], v[180:183], v[28:31]
	v_mfma_f32_16x16x32_bf16 v[24:27], v[96:99], v[180:183], v[24:27]
	v_mfma_f32_16x16x32_bf16 v[8:11], v[96:99], v[188:191], v[8:11]
	v_mfma_f32_16x16x32_bf16 v[12:15], v[72:75], v[188:191], v[12:15]
	v_mfma_f32_16x16x32_bf16 v[52:55], v[108:111], v[152:155], v[52:55]
	v_mfma_f32_16x16x32_bf16 v[48:51], v[128:131], v[152:155], v[48:51]
	v_mfma_f32_16x16x32_bf16 v[32:35], v[128:131], v[160:163], v[32:35]
	v_mfma_f32_16x16x32_bf16 v[36:39], v[108:111], v[160:163], v[36:39]
	v_mfma_f32_16x16x32_bf16 v[20:23], v[108:111], v[168:171], v[20:23]
	v_mfma_f32_16x16x32_bf16 v[16:19], v[128:131], v[168:171], v[16:19]
	v_mfma_f32_16x16x32_bf16 v[0:3], v[128:131], v[184:187], v[0:3]
	v_mfma_f32_16x16x32_bf16 v[4:7], v[108:111], v[184:187], v[4:7]
	v_mfma_f32_16x16x32_bf16 v[52:55], v[116:119], v[156:159], v[52:55]
	v_mfma_f32_16x16x32_bf16 v[48:51], v[140:143], v[156:159], v[48:51]
	v_mfma_f32_16x16x32_bf16 v[32:35], v[140:143], v[164:167], v[32:35]
	v_mfma_f32_16x16x32_bf16 v[36:39], v[116:119], v[164:167], v[36:39]
	v_mfma_f32_16x16x32_bf16 v[20:23], v[116:119], v[180:183], v[20:23]
	v_mfma_f32_16x16x32_bf16 v[16:19], v[140:143], v[180:183], v[16:19]
	v_mfma_f32_16x16x32_bf16 v[0:3], v[140:143], v[188:191], v[0:3]
	v_mfma_f32_16x16x32_bf16 v[4:7], v[116:119], v[188:191], v[4:7]
	s_barrier
	s_add_i32 s71, s71, 2
	s_add_u32 s88, s88, 0x100
	s_addc_u32 s89, s89, 0
	s_add_u32 s87, s87, 0x100
	s_addc_u32 vcc_hi, vcc_hi, 0
.LBB0_965:
	s_add_u32 s67, s88, 0xfff80080
	s_addc_u32 s74, s89, -1
	s_add_i32 s75, 0, 0x10000
	s_cmp_eq_u32 s71, 28
	s_cselect_b32 s93, s79, s74
	s_cselect_b32 s92, s96, s67
	s_cselect_b32 s91, s77, vcc_hi
	s_cselect_b32 s90, vcc_lo, s87
	s_add_i32 s67, 0, 0x14000
	v_add_u32_e32 v96, s75, v238
	v_add_u32_e32 v140, s67, v238
	ds_read_b128 v[64:67], v96
	ds_read_b128 v[72:75], v96 offset:1024
	ds_read_b128 v[88:91], v96 offset:2048
	ds_read_b128 v[96:99], v96 offset:3072
	ds_read_b128 v[108:111], v140
	ds_read_b128 v[116:119], v140 offset:1024
	ds_read_b128 v[128:131], v140 offset:2048
	ds_read_b128 v[140:143], v140 offset:3072
	v_lshl_add_u64 v[192:193], s[88:89], 0, v[230:231]
	s_add_i32 m0, s28, 0xc000
	ds_read_b128 v[152:155], v240
	ds_read_b128 v[156:159], v240 offset:1024
	ds_read_b128 v[160:163], v240 offset:2048
	ds_read_b128 v[164:167], v240 offset:3072
	ds_read_b128 v[168:171], v240 offset:4096
	ds_read_b128 v[180:183], v240 offset:5120
	ds_read_b128 v[184:187], v240 offset:6144
	ds_read_b128 v[188:191], v240 offset:7168
	global_load_lds_dwordx4 v[192:193], off
	v_lshl_add_u64 v[192:193], s[88:89], 0, v[232:233]
	s_add_i32 m0, s28, 0xe000
	s_nop 0
	global_load_lds_dwordx4 v[192:193], off
	s_waitcnt vmcnt(8)
	s_waitcnt lgkmcnt(0)
	s_barrier
	s_waitcnt lgkmcnt(0)
	v_mfma_f32_16x16x32_bf16 v[176:179], v[64:67], v[152:155], v[176:179]
	v_mfma_f32_16x16x32_bf16 v[172:175], v[88:91], v[152:155], v[172:175]
	v_mfma_f32_16x16x32_bf16 v[132:135], v[88:91], v[160:163], v[132:135]
	v_mfma_f32_16x16x32_bf16 v[136:139], v[64:67], v[160:163], v[136:139]
	v_mfma_f32_16x16x32_bf16 v[112:115], v[64:67], v[168:171], v[112:115]
	v_mfma_f32_16x16x32_bf16 v[104:107], v[88:91], v[168:171], v[104:107]
	v_mfma_f32_16x16x32_bf16 v[80:83], v[88:91], v[184:187], v[80:83]
	v_mfma_f32_16x16x32_bf16 v[84:87], v[64:67], v[184:187], v[84:87]
	v_mfma_f32_16x16x32_bf16 v[176:179], v[72:75], v[156:159], v[176:179]
	v_mfma_f32_16x16x32_bf16 v[172:175], v[96:99], v[156:159], v[172:175]
	v_mfma_f32_16x16x32_bf16 v[132:135], v[96:99], v[164:167], v[132:135]
	v_mfma_f32_16x16x32_bf16 v[136:139], v[72:75], v[164:167], v[136:139]
	v_mfma_f32_16x16x32_bf16 v[112:115], v[72:75], v[180:183], v[112:115]
	v_mfma_f32_16x16x32_bf16 v[104:107], v[96:99], v[180:183], v[104:107]
	v_mfma_f32_16x16x32_bf16 v[80:83], v[96:99], v[188:191], v[80:83]
	v_mfma_f32_16x16x32_bf16 v[84:87], v[72:75], v[188:191], v[84:87]
	v_mfma_f32_16x16x32_bf16 v[148:151], v[108:111], v[152:155], v[148:151]
	v_mfma_f32_16x16x32_bf16 v[144:147], v[128:131], v[152:155], v[144:147]
	v_mfma_f32_16x16x32_bf16 v[120:123], v[128:131], v[160:163], v[120:123]
	v_mfma_f32_16x16x32_bf16 v[124:127], v[108:111], v[160:163], v[124:127]
	v_mfma_f32_16x16x32_bf16 v[100:103], v[108:111], v[168:171], v[100:103]
	v_mfma_f32_16x16x32_bf16 v[92:95], v[128:131], v[168:171], v[92:95]
	v_mfma_f32_16x16x32_bf16 v[68:71], v[128:131], v[184:187], v[68:71]
	v_mfma_f32_16x16x32_bf16 v[76:79], v[108:111], v[184:187], v[76:79]
	v_mfma_f32_16x16x32_bf16 v[148:151], v[116:119], v[156:159], v[148:151]
	v_mfma_f32_16x16x32_bf16 v[144:147], v[140:143], v[156:159], v[144:147]
	v_mfma_f32_16x16x32_bf16 v[120:123], v[140:143], v[164:167], v[120:123]
	v_mfma_f32_16x16x32_bf16 v[124:127], v[116:119], v[164:167], v[124:127]
	v_mfma_f32_16x16x32_bf16 v[100:103], v[116:119], v[180:183], v[100:103]
	v_mfma_f32_16x16x32_bf16 v[92:95], v[140:143], v[180:183], v[92:95]
	v_mfma_f32_16x16x32_bf16 v[68:71], v[140:143], v[188:191], v[68:71]
	v_mfma_f32_16x16x32_bf16 v[76:79], v[116:119], v[188:191], v[76:79]
	s_barrier
	s_add_i32 s74, s75, s2
	v_lshl_add_u64 v[192:193], s[90:91], 0, v[216:217]
	s_mov_b32 m0, s74
	ds_read_b128 v[152:155], v240 offset:16384
	ds_read_b128 v[156:159], v240 offset:17408
	ds_read_b128 v[160:163], v240 offset:18432
	ds_read_b128 v[164:167], v240 offset:19456
	ds_read_b128 v[168:171], v240 offset:20480
	ds_read_b128 v[180:183], v240 offset:21504
	ds_read_b128 v[184:187], v240 offset:22528
	ds_read_b128 v[188:191], v240 offset:23552
	global_load_lds_dwordx4 v[192:193], off
	s_add_i32 m0, s74, 0x2000
	s_add_u32 s74, s90, 0x80000
	v_lshl_add_u64 v[194:195], s[90:91], 0, v[228:229]
	s_addc_u32 s75, s91, 0
	s_add_i32 s67, s67, s2
	global_load_lds_dwordx4 v[194:195], off
	v_lshl_add_u64 v[196:197], s[74:75], 0, v[216:217]
	s_mov_b32 m0, s67
	v_lshl_add_u64 v[198:199], s[92:93], 0, v[226:227]
	global_load_lds_dwordx4 v[196:197], off
	v_lshl_add_u64 v[196:197], s[74:75], 0, v[228:229]
	s_add_i32 m0, s67, 0x2000
	s_nop 0
	global_load_lds_dwordx4 v[196:197], off
	v_lshl_add_u64 v[196:197], s[92:93], 0, v[224:225]
	s_mov_b32 m0, s28
	s_nop 0
	global_load_lds_dwordx4 v[196:197], off
	s_mov_b32 m0, s29
	s_nop 0
	global_load_lds_dwordx4 v[198:199], off
	s_waitcnt vmcnt(8)
	s_waitcnt lgkmcnt(0)
	s_barrier
	s_waitcnt lgkmcnt(0)
	v_mfma_f32_16x16x32_bf16 v[60:63], v[64:67], v[152:155], v[60:63]
	v_mfma_f32_16x16x32_bf16 v[56:59], v[88:91], v[152:155], v[56:59]
	v_mfma_f32_16x16x32_bf16 v[40:43], v[88:91], v[160:163], v[40:43]
	v_mfma_f32_16x16x32_bf16 v[44:47], v[64:67], v[160:163], v[44:47]
	v_mfma_f32_16x16x32_bf16 v[28:31], v[64:67], v[168:171], v[28:31]
	v_mfma_f32_16x16x32_bf16 v[24:27], v[88:91], v[168:171], v[24:27]
	v_mfma_f32_16x16x32_bf16 v[8:11], v[88:91], v[184:187], v[8:11]
	v_mfma_f32_16x16x32_bf16 v[12:15], v[64:67], v[184:187], v[12:15]
	v_mfma_f32_16x16x32_bf16 v[60:63], v[72:75], v[156:159], v[60:63]
	v_mfma_f32_16x16x32_bf16 v[56:59], v[96:99], v[156:159], v[56:59]
	v_mfma_f32_16x16x32_bf16 v[40:43], v[96:99], v[164:167], v[40:43]
	v_mfma_f32_16x16x32_bf16 v[44:47], v[72:75], v[164:167], v[44:47]
	v_mfma_f32_16x16x32_bf16 v[28:31], v[72:75], v[180:183], v[28:31]
	v_mfma_f32_16x16x32_bf16 v[24:27], v[96:99], v[180:183], v[24:27]
	v_mfma_f32_16x16x32_bf16 v[8:11], v[96:99], v[188:191], v[8:11]
	v_mfma_f32_16x16x32_bf16 v[12:15], v[72:75], v[188:191], v[12:15]
	v_mfma_f32_16x16x32_bf16 v[52:55], v[108:111], v[152:155], v[52:55]
	v_mfma_f32_16x16x32_bf16 v[48:51], v[128:131], v[152:155], v[48:51]
	v_mfma_f32_16x16x32_bf16 v[32:35], v[128:131], v[160:163], v[32:35]
	v_mfma_f32_16x16x32_bf16 v[36:39], v[108:111], v[160:163], v[36:39]
	v_mfma_f32_16x16x32_bf16 v[20:23], v[108:111], v[168:171], v[20:23]
	v_mfma_f32_16x16x32_bf16 v[16:19], v[128:131], v[168:171], v[16:19]
	v_mfma_f32_16x16x32_bf16 v[0:3], v[128:131], v[184:187], v[0:3]
	v_mfma_f32_16x16x32_bf16 v[4:7], v[108:111], v[184:187], v[4:7]
	v_mfma_f32_16x16x32_bf16 v[52:55], v[116:119], v[156:159], v[52:55]
	v_mfma_f32_16x16x32_bf16 v[48:51], v[140:143], v[156:159], v[48:51]
	v_mfma_f32_16x16x32_bf16 v[32:35], v[140:143], v[164:167], v[32:35]
	v_mfma_f32_16x16x32_bf16 v[36:39], v[116:119], v[164:167], v[36:39]
	v_mfma_f32_16x16x32_bf16 v[20:23], v[116:119], v[180:183], v[20:23]
	v_mfma_f32_16x16x32_bf16 v[16:19], v[140:143], v[180:183], v[16:19]
	v_mfma_f32_16x16x32_bf16 v[0:3], v[140:143], v[188:191], v[0:3]
	v_mfma_f32_16x16x32_bf16 v[4:7], v[116:119], v[188:191], v[4:7]
	s_barrier
	s_add_i32 s67, 0, 0x18000
	s_add_i32 s3, 0, 0x1c000
	v_add_u32_e32 v96, s67, v238
	v_add_u32_e32 v140, s3, v238
	ds_read_b128 v[64:67], v96
	ds_read_b128 v[72:75], v96 offset:1024
	ds_read_b128 v[88:91], v96 offset:2048
	ds_read_b128 v[96:99], v96 offset:3072
	ds_read_b128 v[108:111], v140
	ds_read_b128 v[116:119], v140 offset:1024
	ds_read_b128 v[128:131], v140 offset:2048
	ds_read_b128 v[140:143], v140 offset:3072
	s_add_u32 s74, s92, 0x80000
	s_addc_u32 s75, s93, 0
	s_mov_b32 m0, s34
	v_lshl_add_u64 v[200:201], s[74:75], 0, v[224:225]
	ds_read_b128 v[152:155], v240 offset:32768
	ds_read_b128 v[156:159], v240 offset:33792
	ds_read_b128 v[160:163], v240 offset:34816
	ds_read_b128 v[164:167], v240 offset:35840
	ds_read_b128 v[168:171], v240 offset:36864
	ds_read_b128 v[180:183], v240 offset:37888
	ds_read_b128 v[184:187], v240 offset:38912
	ds_read_b128 v[188:191], v240 offset:39936
	global_load_lds_dwordx4 v[200:201], off
	v_lshl_add_u64 v[200:201], s[74:75], 0, v[226:227]
	s_mov_b32 m0, s35
	s_nop 0
	global_load_lds_dwordx4 v[200:201], off
	s_waitcnt vmcnt(8)
	s_waitcnt lgkmcnt(0)
	s_barrier
	s_waitcnt lgkmcnt(0)
	v_mfma_f32_16x16x32_bf16 v[176:179], v[64:67], v[152:155], v[176:179]
	v_mfma_f32_16x16x32_bf16 v[172:175], v[88:91], v[152:155], v[172:175]
	v_mfma_f32_16x16x32_bf16 v[132:135], v[88:91], v[160:163], v[132:135]
	v_mfma_f32_16x16x32_bf16 v[136:139], v[64:67], v[160:163], v[136:139]
	v_mfma_f32_16x16x32_bf16 v[112:115], v[64:67], v[168:171], v[112:115]
	v_mfma_f32_16x16x32_bf16 v[104:107], v[88:91], v[168:171], v[104:107]
	v_mfma_f32_16x16x32_bf16 v[80:83], v[88:91], v[184:187], v[80:83]
	v_mfma_f32_16x16x32_bf16 v[84:87], v[64:67], v[184:187], v[84:87]
	v_mfma_f32_16x16x32_bf16 v[176:179], v[72:75], v[156:159], v[176:179]
	v_mfma_f32_16x16x32_bf16 v[172:175], v[96:99], v[156:159], v[172:175]
	v_mfma_f32_16x16x32_bf16 v[132:135], v[96:99], v[164:167], v[132:135]
	v_mfma_f32_16x16x32_bf16 v[136:139], v[72:75], v[164:167], v[136:139]
	v_mfma_f32_16x16x32_bf16 v[112:115], v[72:75], v[180:183], v[112:115]
	v_mfma_f32_16x16x32_bf16 v[104:107], v[96:99], v[180:183], v[104:107]
	v_mfma_f32_16x16x32_bf16 v[80:83], v[96:99], v[188:191], v[80:83]
	v_mfma_f32_16x16x32_bf16 v[84:87], v[72:75], v[188:191], v[84:87]
	v_mfma_f32_16x16x32_bf16 v[148:151], v[108:111], v[152:155], v[148:151]
	v_mfma_f32_16x16x32_bf16 v[144:147], v[128:131], v[152:155], v[144:147]
	v_mfma_f32_16x16x32_bf16 v[120:123], v[128:131], v[160:163], v[120:123]
	v_mfma_f32_16x16x32_bf16 v[124:127], v[108:111], v[160:163], v[124:127]
	v_mfma_f32_16x16x32_bf16 v[100:103], v[108:111], v[168:171], v[100:103]
	v_mfma_f32_16x16x32_bf16 v[92:95], v[128:131], v[168:171], v[92:95]
	v_mfma_f32_16x16x32_bf16 v[68:71], v[128:131], v[184:187], v[68:71]
	v_mfma_f32_16x16x32_bf16 v[76:79], v[108:111], v[184:187], v[76:79]
	v_mfma_f32_16x16x32_bf16 v[148:151], v[116:119], v[156:159], v[148:151]
	v_mfma_f32_16x16x32_bf16 v[144:147], v[140:143], v[156:159], v[144:147]
	v_mfma_f32_16x16x32_bf16 v[120:123], v[140:143], v[164:167], v[120:123]
	v_mfma_f32_16x16x32_bf16 v[124:127], v[116:119], v[164:167], v[124:127]
	v_mfma_f32_16x16x32_bf16 v[100:103], v[116:119], v[180:183], v[100:103]
	v_mfma_f32_16x16x32_bf16 v[92:95], v[140:143], v[180:183], v[92:95]
	v_mfma_f32_16x16x32_bf16 v[68:71], v[140:143], v[188:191], v[68:71]
	v_mfma_f32_16x16x32_bf16 v[76:79], v[116:119], v[188:191], v[76:79]
	s_barrier
	s_add_i32 s67, s67, s2
	v_lshl_add_u64 v[192:193], v[192:193], 0, s[30:31]
	s_mov_b32 m0, s67
	ds_read_b128 v[152:155], v240 offset:49152
	ds_read_b128 v[156:159], v240 offset:50176
	ds_read_b128 v[160:163], v240 offset:51200
	ds_read_b128 v[164:167], v240 offset:52224
	ds_read_b128 v[168:171], v240 offset:53248
	ds_read_b128 v[180:183], v240 offset:54272
	ds_read_b128 v[184:187], v240 offset:55296
	ds_read_b128 v[188:191], v240 offset:56320
	global_load_lds_dwordx4 v[192:193], off
	s_add_i32 m0, s67, 0x2000
	s_add_u32 s74, s90, 0x80080
	v_lshl_add_u64 v[192:193], v[194:195], 0, s[30:31]
	s_addc_u32 s75, s91, 0
	s_add_i32 s3, s3, s2
	global_load_lds_dwordx4 v[192:193], off
	v_lshl_add_u64 v[192:193], s[74:75], 0, v[216:217]
	s_mov_b32 m0, s3
	s_nop 0
	global_load_lds_dwordx4 v[192:193], off
	v_lshl_add_u64 v[192:193], s[74:75], 0, v[228:229]
	s_add_i32 m0, s3, 0x2000
	s_nop 0
	global_load_lds_dwordx4 v[192:193], off
	v_lshl_add_u64 v[192:193], v[196:197], 0, s[30:31]
	s_mov_b32 m0, s60
	s_nop 0
	global_load_lds_dwordx4 v[192:193], off
	v_lshl_add_u64 v[192:193], v[198:199], 0, s[30:31]
	s_mov_b32 m0, s61
	s_nop 0
	global_load_lds_dwordx4 v[192:193], off
	s_waitcnt vmcnt(8)
	s_waitcnt lgkmcnt(0)
	s_barrier
	s_waitcnt lgkmcnt(0)
	v_mfma_f32_16x16x32_bf16 v[60:63], v[64:67], v[152:155], v[60:63]
	v_mfma_f32_16x16x32_bf16 v[56:59], v[88:91], v[152:155], v[56:59]
	v_mfma_f32_16x16x32_bf16 v[40:43], v[88:91], v[160:163], v[40:43]
	v_mfma_f32_16x16x32_bf16 v[44:47], v[64:67], v[160:163], v[44:47]
	v_mfma_f32_16x16x32_bf16 v[28:31], v[64:67], v[168:171], v[28:31]
	v_mfma_f32_16x16x32_bf16 v[24:27], v[88:91], v[168:171], v[24:27]
	v_mfma_f32_16x16x32_bf16 v[8:11], v[88:91], v[184:187], v[8:11]
	v_mfma_f32_16x16x32_bf16 v[12:15], v[64:67], v[184:187], v[12:15]
	v_mfma_f32_16x16x32_bf16 v[60:63], v[72:75], v[156:159], v[60:63]
	v_mfma_f32_16x16x32_bf16 v[56:59], v[96:99], v[156:159], v[56:59]
	v_mfma_f32_16x16x32_bf16 v[40:43], v[96:99], v[164:167], v[40:43]
	v_mfma_f32_16x16x32_bf16 v[44:47], v[72:75], v[164:167], v[44:47]
	v_mfma_f32_16x16x32_bf16 v[28:31], v[72:75], v[180:183], v[28:31]
	v_mfma_f32_16x16x32_bf16 v[24:27], v[96:99], v[180:183], v[24:27]
	v_mfma_f32_16x16x32_bf16 v[8:11], v[96:99], v[188:191], v[8:11]
	v_mfma_f32_16x16x32_bf16 v[12:15], v[72:75], v[188:191], v[12:15]
	v_mfma_f32_16x16x32_bf16 v[52:55], v[108:111], v[152:155], v[52:55]
	v_mfma_f32_16x16x32_bf16 v[48:51], v[128:131], v[152:155], v[48:51]
	v_mfma_f32_16x16x32_bf16 v[32:35], v[128:131], v[160:163], v[32:35]
	v_mfma_f32_16x16x32_bf16 v[36:39], v[108:111], v[160:163], v[36:39]
	v_mfma_f32_16x16x32_bf16 v[20:23], v[108:111], v[168:171], v[20:23]
	v_mfma_f32_16x16x32_bf16 v[16:19], v[128:131], v[168:171], v[16:19]
	v_mfma_f32_16x16x32_bf16 v[0:3], v[128:131], v[184:187], v[0:3]
	v_mfma_f32_16x16x32_bf16 v[4:7], v[108:111], v[184:187], v[4:7]
	v_mfma_f32_16x16x32_bf16 v[52:55], v[116:119], v[156:159], v[52:55]
	v_mfma_f32_16x16x32_bf16 v[48:51], v[140:143], v[156:159], v[48:51]
	v_mfma_f32_16x16x32_bf16 v[32:35], v[140:143], v[164:167], v[32:35]
	v_mfma_f32_16x16x32_bf16 v[36:39], v[116:119], v[164:167], v[36:39]
	v_mfma_f32_16x16x32_bf16 v[20:23], v[116:119], v[180:183], v[20:23]
	v_mfma_f32_16x16x32_bf16 v[16:19], v[140:143], v[180:183], v[16:19]
	v_mfma_f32_16x16x32_bf16 v[0:3], v[140:143], v[188:191], v[0:3]
	v_mfma_f32_16x16x32_bf16 v[4:7], v[116:119], v[188:191], v[4:7]
	s_barrier
	s_add_i32 s71, s71, 2
	s_add_u32 s88, s88, 0x100
	s_addc_u32 s89, s89, 0
	s_add_u32 s87, s87, 0x100
	s_addc_u32 vcc_hi, vcc_hi, 0
	s_cmp_gt_u32 s71, 29
	s_cbranch_scc0 .LBB0_965
	s_and_b64 vcc, exec, s[22:23]
	s_cbranch_vccz .LBB0_968
	s_barrier

.LBB0_1189:
	s_ashr_i32 s75, s74, 31
	s_lshl_b64 s[72:73], s[74:75], 20
	s_add_u32 s76, s2, s72
	s_addc_u32 s77, s3, s73
	s_and_b64 s[72:73], s[4:5], exec
	s_cselect_b32 s71, s77, s83
	s_cselect_b32 s72, s76, s82
	s_ashr_i32 s23, s22, 31
	s_lshl_b64 s[78:79], s[22:23], 20
	s_add_u32 s78, s14, s78
	s_addc_u32 s79, s15, s79
	s_and_b64 s[86:87], s[4:5], exec
	s_cselect_b32 s23, s79, s85
	s_cselect_b32 s73, s78, s84
	s_add_u32 s82, s82, 0x80080
	s_addc_u32 s83, s83, 0
	s_add_u32 s75, s84, 0x100
	s_addc_u32 s81, s85, 0
	s_mov_b32 s88, -2
	s_add_u32 s67, s82, 0xfff80080
	s_addc_u32 s84, s83, -1
	s_add_i32 s89, 0, 0x10000
	s_cmp_eq_u32 s88, 28
	s_cselect_b32 s87, s71, s84
	s_cselect_b32 s86, s72, s67
	s_cselect_b32 s85, s23, s81
	s_cselect_b32 s84, s73, s75
	s_add_i32 s67, 0, 0x14000
	v_add_u32_e32 v76, s89, v192
	v_add_u32_e32 v156, s67, v192
	ds_read_b128 v[64:67], v76
	ds_read_b128 v[68:71], v76 offset:1024
	ds_read_b128 v[72:75], v76 offset:2048
	ds_read_b128 v[76:79], v76 offset:3072
	ds_read_b128 v[80:83], v156
	ds_read_b128 v[116:119], v156 offset:1024
	ds_read_b128 v[152:155], v156 offset:2048
	ds_read_b128 v[156:159], v156 offset:3072
	v_lshl_add_u64 v[190:191], s[82:83], 0, v[186:187]
	s_add_i32 m0, s28, 0xc000
	ds_read_b128 v[160:163], v193
	ds_read_b128 v[164:167], v193 offset:1024
	ds_read_b128 v[168:171], v193 offset:2048
	ds_read_b128 v[172:175], v193 offset:3072
	ds_read_b128 v[194:197], v193 offset:4096
	ds_read_b128 v[198:201], v193 offset:5120
	ds_read_b128 v[202:205], v193 offset:6144
	ds_read_b128 v[206:209], v193 offset:7168
	global_load_lds_dwordx4 v[190:191], off
	v_lshl_add_u64 v[190:191], s[82:83], 0, v[188:189]
	s_add_i32 m0, s28, 0xe000
	s_nop 0
	global_load_lds_dwordx4 v[190:191], off
	s_waitcnt vmcnt(8)
	s_waitcnt lgkmcnt(0)
	s_barrier
	s_waitcnt lgkmcnt(0)
	v_mfma_f32_16x16x32_bf16 v[148:151], v[64:67], v[160:163], 0
	v_mfma_f32_16x16x32_bf16 v[144:147], v[72:75], v[160:163], 0
	v_mfma_f32_16x16x32_bf16 v[128:131], v[72:75], v[168:171], 0
	v_mfma_f32_16x16x32_bf16 v[132:135], v[64:67], v[168:171], 0
	v_mfma_f32_16x16x32_bf16 v[112:115], v[64:67], v[194:197], 0
	v_mfma_f32_16x16x32_bf16 v[108:111], v[72:75], v[194:197], 0
	v_mfma_f32_16x16x32_bf16 v[92:95], v[72:75], v[202:205], 0
	v_mfma_f32_16x16x32_bf16 v[96:99], v[64:67], v[202:205], 0
	v_mfma_f32_16x16x32_bf16 v[148:151], v[68:71], v[164:167], v[148:151]
	v_mfma_f32_16x16x32_bf16 v[144:147], v[76:79], v[164:167], v[144:147]
	v_mfma_f32_16x16x32_bf16 v[128:131], v[76:79], v[172:175], v[128:131]
	v_mfma_f32_16x16x32_bf16 v[132:135], v[68:71], v[172:175], v[132:135]
	v_mfma_f32_16x16x32_bf16 v[112:115], v[68:71], v[198:201], v[112:115]
	v_mfma_f32_16x16x32_bf16 v[108:111], v[76:79], v[198:201], v[108:111]
	v_mfma_f32_16x16x32_bf16 v[92:95], v[76:79], v[206:209], v[92:95]
	v_mfma_f32_16x16x32_bf16 v[96:99], v[68:71], v[206:209], v[96:99]
	v_mfma_f32_16x16x32_bf16 v[140:143], v[80:83], v[160:163], 0
	v_mfma_f32_16x16x32_bf16 v[136:139], v[152:155], v[160:163], 0
	v_mfma_f32_16x16x32_bf16 v[120:123], v[152:155], v[168:171], 0
	v_mfma_f32_16x16x32_bf16 v[124:127], v[80:83], v[168:171], 0
	v_mfma_f32_16x16x32_bf16 v[104:107], v[80:83], v[194:197], 0
	v_mfma_f32_16x16x32_bf16 v[100:103], v[152:155], v[194:197], 0
	v_mfma_f32_16x16x32_bf16 v[84:87], v[152:155], v[202:205], 0
	v_mfma_f32_16x16x32_bf16 v[88:91], v[80:83], v[202:205], 0
	v_mfma_f32_16x16x32_bf16 v[140:143], v[116:119], v[164:167], v[140:143]
	v_mfma_f32_16x16x32_bf16 v[136:139], v[156:159], v[164:167], v[136:139]
	v_mfma_f32_16x16x32_bf16 v[120:123], v[156:159], v[172:175], v[120:123]
	v_mfma_f32_16x16x32_bf16 v[124:127], v[116:119], v[172:175], v[124:127]
	v_mfma_f32_16x16x32_bf16 v[104:107], v[116:119], v[198:201], v[104:107]
	v_mfma_f32_16x16x32_bf16 v[100:103], v[156:159], v[198:201], v[100:103]
	v_mfma_f32_16x16x32_bf16 v[84:87], v[156:159], v[206:209], v[84:87]
	v_mfma_f32_16x16x32_bf16 v[88:91], v[116:119], v[206:209], v[88:91]
	s_barrier
	s_add_i32 s89, s89, s24
	v_lshl_add_u64 v[190:191], s[84:85], 0, v[180:181]
	s_mov_b32 m0, s89
	ds_read_b128 v[160:163], v193 offset:16384
	ds_read_b128 v[164:167], v193 offset:17408
	ds_read_b128 v[168:171], v193 offset:18432
	ds_read_b128 v[172:175], v193 offset:19456
	ds_read_b128 v[194:197], v193 offset:20480
	ds_read_b128 v[198:201], v193 offset:21504
	ds_read_b128 v[202:205], v193 offset:22528
	ds_read_b128 v[206:209], v193 offset:23552
	global_load_lds_dwordx4 v[190:191], off
	s_add_i32 m0, s89, 0x2000
	s_add_u32 s90, s84, 0x80000
	v_lshl_add_u64 v[210:211], s[84:85], 0, v[176:177]
	s_addc_u32 s91, s85, 0
	s_add_i32 s67, s67, s24
	global_load_lds_dwordx4 v[210:211], off
	v_lshl_add_u64 v[212:213], s[90:91], 0, v[180:181]
	s_mov_b32 m0, s67
	v_lshl_add_u64 v[214:215], s[86:87], 0, v[178:179]
	global_load_lds_dwordx4 v[212:213], off
	v_lshl_add_u64 v[212:213], s[90:91], 0, v[176:177]
	s_add_i32 m0, s67, 0x2000
	s_nop 0
	global_load_lds_dwordx4 v[212:213], off
	v_lshl_add_u64 v[212:213], s[86:87], 0, v[182:183]
	s_mov_b32 m0, s28
	s_nop 0
	global_load_lds_dwordx4 v[212:213], off
	s_mov_b32 m0, s29
	s_nop 0
	global_load_lds_dwordx4 v[214:215], off
	s_waitcnt vmcnt(8)
	s_waitcnt lgkmcnt(0)
	s_barrier
	s_waitcnt lgkmcnt(0)
	v_mfma_f32_16x16x32_bf16 v[60:63], v[64:67], v[160:163], 0
	v_mfma_f32_16x16x32_bf16 v[56:59], v[72:75], v[160:163], 0
	v_mfma_f32_16x16x32_bf16 v[40:43], v[72:75], v[168:171], 0
	v_mfma_f32_16x16x32_bf16 v[44:47], v[64:67], v[168:171], 0
	v_mfma_f32_16x16x32_bf16 v[28:31], v[64:67], v[194:197], 0
	v_mfma_f32_16x16x32_bf16 v[24:27], v[72:75], v[194:197], 0
	v_mfma_f32_16x16x32_bf16 v[8:11], v[72:75], v[202:205], 0
	v_mfma_f32_16x16x32_bf16 v[12:15], v[64:67], v[202:205], 0
	v_mfma_f32_16x16x32_bf16 v[60:63], v[68:71], v[164:167], v[60:63]
	v_mfma_f32_16x16x32_bf16 v[56:59], v[76:79], v[164:167], v[56:59]
	v_mfma_f32_16x16x32_bf16 v[40:43], v[76:79], v[172:175], v[40:43]
	v_mfma_f32_16x16x32_bf16 v[44:47], v[68:71], v[172:175], v[44:47]
	v_mfma_f32_16x16x32_bf16 v[28:31], v[68:71], v[198:201], v[28:31]
	v_mfma_f32_16x16x32_bf16 v[24:27], v[76:79], v[198:201], v[24:27]
	v_mfma_f32_16x16x32_bf16 v[8:11], v[76:79], v[206:209], v[8:11]
	v_mfma_f32_16x16x32_bf16 v[12:15], v[68:71], v[206:209], v[12:15]
	v_mfma_f32_16x16x32_bf16 v[52:55], v[80:83], v[160:163], 0
	v_mfma_f32_16x16x32_bf16 v[48:51], v[152:155], v[160:163], 0
	v_mfma_f32_16x16x32_bf16 v[32:35], v[152:155], v[168:171], 0
	v_mfma_f32_16x16x32_bf16 v[36:39], v[80:83], v[168:171], 0
	v_mfma_f32_16x16x32_bf16 v[20:23], v[80:83], v[194:197], 0
	v_mfma_f32_16x16x32_bf16 v[16:19], v[152:155], v[194:197], 0
	v_mfma_f32_16x16x32_bf16 v[0:3], v[152:155], v[202:205], 0
	v_mfma_f32_16x16x32_bf16 v[4:7], v[80:83], v[202:205], 0
	v_mfma_f32_16x16x32_bf16 v[52:55], v[116:119], v[164:167], v[52:55]
	v_mfma_f32_16x16x32_bf16 v[48:51], v[156:159], v[164:167], v[48:51]
	v_mfma_f32_16x16x32_bf16 v[32:35], v[156:159], v[172:175], v[32:35]
	v_mfma_f32_16x16x32_bf16 v[36:39], v[116:119], v[172:175], v[36:39]
	v_mfma_f32_16x16x32_bf16 v[20:23], v[116:119], v[198:201], v[20:23]
	v_mfma_f32_16x16x32_bf16 v[16:19], v[156:159], v[198:201], v[16:19]
	v_mfma_f32_16x16x32_bf16 v[0:3], v[156:159], v[206:209], v[0:3]
	v_mfma_f32_16x16x32_bf16 v[4:7], v[116:119], v[206:209], v[4:7]
	s_barrier
	s_add_i32 s67, 0, 0x18000
	s_add_i32 s89, 0, 0x1c000
	v_add_u32_e32 v76, s67, v192
	v_add_u32_e32 v156, s89, v192
	ds_read_b128 v[64:67], v76
	ds_read_b128 v[68:71], v76 offset:1024
	ds_read_b128 v[72:75], v76 offset:2048
	ds_read_b128 v[76:79], v76 offset:3072
	ds_read_b128 v[80:83], v156
	ds_read_b128 v[116:119], v156 offset:1024
	ds_read_b128 v[152:155], v156 offset:2048
	ds_read_b128 v[156:159], v156 offset:3072
	s_add_u32 s86, s86, 0x80000
	s_addc_u32 s87, s87, 0
	s_mov_b32 m0, s34
	v_lshl_add_u64 v[218:219], s[86:87], 0, v[182:183]
	ds_read_b128 v[160:163], v193 offset:32768
	ds_read_b128 v[164:167], v193 offset:33792
	ds_read_b128 v[168:171], v193 offset:34816
	ds_read_b128 v[172:175], v193 offset:35840
	ds_read_b128 v[194:197], v193 offset:36864
	ds_read_b128 v[198:201], v193 offset:37888
	ds_read_b128 v[202:205], v193 offset:38912
	ds_read_b128 v[206:209], v193 offset:39936
	global_load_lds_dwordx4 v[218:219], off
	v_lshl_add_u64 v[218:219], s[86:87], 0, v[178:179]
	s_mov_b32 m0, s35
	s_nop 0
	global_load_lds_dwordx4 v[218:219], off
	s_waitcnt vmcnt(8)
	s_waitcnt lgkmcnt(0)
	s_barrier
	s_waitcnt lgkmcnt(0)
	v_mfma_f32_16x16x32_bf16 v[148:151], v[64:67], v[160:163], v[148:151]
	v_mfma_f32_16x16x32_bf16 v[144:147], v[72:75], v[160:163], v[144:147]
	v_mfma_f32_16x16x32_bf16 v[128:131], v[72:75], v[168:171], v[128:131]
	v_mfma_f32_16x16x32_bf16 v[132:135], v[64:67], v[168:171], v[132:135]
	v_mfma_f32_16x16x32_bf16 v[112:115], v[64:67], v[194:197], v[112:115]
	v_mfma_f32_16x16x32_bf16 v[108:111], v[72:75], v[194:197], v[108:111]
	v_mfma_f32_16x16x32_bf16 v[92:95], v[72:75], v[202:205], v[92:95]
	v_mfma_f32_16x16x32_bf16 v[96:99], v[64:67], v[202:205], v[96:99]
	v_mfma_f32_16x16x32_bf16 v[148:151], v[68:71], v[164:167], v[148:151]
	v_mfma_f32_16x16x32_bf16 v[144:147], v[76:79], v[164:167], v[144:147]
	v_mfma_f32_16x16x32_bf16 v[128:131], v[76:79], v[172:175], v[128:131]
	v_mfma_f32_16x16x32_bf16 v[132:135], v[68:71], v[172:175], v[132:135]
	v_mfma_f32_16x16x32_bf16 v[112:115], v[68:71], v[198:201], v[112:115]
	v_mfma_f32_16x16x32_bf16 v[108:111], v[76:79], v[198:201], v[108:111]
	v_mfma_f32_16x16x32_bf16 v[92:95], v[76:79], v[206:209], v[92:95]
	v_mfma_f32_16x16x32_bf16 v[96:99], v[68:71], v[206:209], v[96:99]
	v_mfma_f32_16x16x32_bf16 v[140:143], v[80:83], v[160:163], v[140:143]
	v_mfma_f32_16x16x32_bf16 v[136:139], v[152:155], v[160:163], v[136:139]
	v_mfma_f32_16x16x32_bf16 v[120:123], v[152:155], v[168:171], v[120:123]
	v_mfma_f32_16x16x32_bf16 v[124:127], v[80:83], v[168:171], v[124:127]
	v_mfma_f32_16x16x32_bf16 v[104:107], v[80:83], v[194:197], v[104:107]
	v_mfma_f32_16x16x32_bf16 v[100:103], v[152:155], v[194:197], v[100:103]
	v_mfma_f32_16x16x32_bf16 v[84:87], v[152:155], v[202:205], v[84:87]
	v_mfma_f32_16x16x32_bf16 v[88:91], v[80:83], v[202:205], v[88:91]
	v_mfma_f32_16x16x32_bf16 v[140:143], v[116:119], v[164:167], v[140:143]
	v_mfma_f32_16x16x32_bf16 v[136:139], v[156:159], v[164:167], v[136:139]
	v_mfma_f32_16x16x32_bf16 v[120:123], v[156:159], v[172:175], v[120:123]
	v_mfma_f32_16x16x32_bf16 v[124:127], v[116:119], v[172:175], v[124:127]
	v_mfma_f32_16x16x32_bf16 v[104:107], v[116:119], v[198:201], v[104:107]
	v_mfma_f32_16x16x32_bf16 v[100:103], v[156:159], v[198:201], v[100:103]
	v_mfma_f32_16x16x32_bf16 v[84:87], v[156:159], v[206:209], v[84:87]
	v_mfma_f32_16x16x32_bf16 v[88:91], v[116:119], v[206:209], v[88:91]
	s_barrier
	s_add_i32 s67, s67, s24
	v_lshl_add_u64 v[190:191], v[190:191], 0, s[30:31]
	s_mov_b32 m0, s67
	ds_read_b128 v[160:163], v193 offset:49152
	ds_read_b128 v[164:167], v193 offset:50176
	ds_read_b128 v[168:171], v193 offset:51200
	ds_read_b128 v[172:175], v193 offset:52224
	ds_read_b128 v[194:197], v193 offset:53248
	ds_read_b128 v[198:201], v193 offset:54272
	ds_read_b128 v[202:205], v193 offset:55296
	ds_read_b128 v[206:209], v193 offset:56320
	global_load_lds_dwordx4 v[190:191], off
	s_add_i32 m0, s67, 0x2000
	s_add_u32 s84, s84, 0x80080
	v_lshl_add_u64 v[190:191], v[210:211], 0, s[30:31]
	s_addc_u32 s85, s85, 0
	s_add_i32 s67, s89, s24
	global_load_lds_dwordx4 v[190:191], off
	v_lshl_add_u64 v[190:191], s[84:85], 0, v[180:181]
	s_mov_b32 m0, s67
	s_nop 0
	global_load_lds_dwordx4 v[190:191], off
	v_lshl_add_u64 v[190:191], s[84:85], 0, v[176:177]
	s_add_i32 m0, s67, 0x2000
	s_nop 0
	global_load_lds_dwordx4 v[190:191], off
	v_lshl_add_u64 v[190:191], v[212:213], 0, s[30:31]
	s_mov_b32 m0, s53
	s_nop 0
	global_load_lds_dwordx4 v[190:191], off
	v_lshl_add_u64 v[190:191], v[214:215], 0, s[30:31]
	s_mov_b32 m0, s54
	s_nop 0
	global_load_lds_dwordx4 v[190:191], off
	s_waitcnt vmcnt(8)
	s_waitcnt lgkmcnt(0)
	s_barrier
	s_waitcnt lgkmcnt(0)
	v_mfma_f32_16x16x32_bf16 v[60:63], v[64:67], v[160:163], v[60:63]
	v_mfma_f32_16x16x32_bf16 v[56:59], v[72:75], v[160:163], v[56:59]
	v_mfma_f32_16x16x32_bf16 v[40:43], v[72:75], v[168:171], v[40:43]
	v_mfma_f32_16x16x32_bf16 v[44:47], v[64:67], v[168:171], v[44:47]
	v_mfma_f32_16x16x32_bf16 v[28:31], v[64:67], v[194:197], v[28:31]
	v_mfma_f32_16x16x32_bf16 v[24:27], v[72:75], v[194:197], v[24:27]
	v_mfma_f32_16x16x32_bf16 v[8:11], v[72:75], v[202:205], v[8:11]
	v_mfma_f32_16x16x32_bf16 v[12:15], v[64:67], v[202:205], v[12:15]
	v_mfma_f32_16x16x32_bf16 v[60:63], v[68:71], v[164:167], v[60:63]
	v_mfma_f32_16x16x32_bf16 v[56:59], v[76:79], v[164:167], v[56:59]
	v_mfma_f32_16x16x32_bf16 v[40:43], v[76:79], v[172:175], v[40:43]
	v_mfma_f32_16x16x32_bf16 v[44:47], v[68:71], v[172:175], v[44:47]
	v_mfma_f32_16x16x32_bf16 v[28:31], v[68:71], v[198:201], v[28:31]
	v_mfma_f32_16x16x32_bf16 v[24:27], v[76:79], v[198:201], v[24:27]
	v_mfma_f32_16x16x32_bf16 v[8:11], v[76:79], v[206:209], v[8:11]
	v_mfma_f32_16x16x32_bf16 v[12:15], v[68:71], v[206:209], v[12:15]
	v_mfma_f32_16x16x32_bf16 v[52:55], v[80:83], v[160:163], v[52:55]
	v_mfma_f32_16x16x32_bf16 v[48:51], v[152:155], v[160:163], v[48:51]
	v_mfma_f32_16x16x32_bf16 v[32:35], v[152:155], v[168:171], v[32:35]
	v_mfma_f32_16x16x32_bf16 v[36:39], v[80:83], v[168:171], v[36:39]
	v_mfma_f32_16x16x32_bf16 v[20:23], v[80:83], v[194:197], v[20:23]
	v_mfma_f32_16x16x32_bf16 v[16:19], v[152:155], v[194:197], v[16:19]
	v_mfma_f32_16x16x32_bf16 v[0:3], v[152:155], v[202:205], v[0:3]
	v_mfma_f32_16x16x32_bf16 v[4:7], v[80:83], v[202:205], v[4:7]
	v_mfma_f32_16x16x32_bf16 v[52:55], v[116:119], v[164:167], v[52:55]
	v_mfma_f32_16x16x32_bf16 v[48:51], v[156:159], v[164:167], v[48:51]
	v_mfma_f32_16x16x32_bf16 v[32:35], v[156:159], v[172:175], v[32:35]
	v_mfma_f32_16x16x32_bf16 v[36:39], v[116:119], v[172:175], v[36:39]
	v_mfma_f32_16x16x32_bf16 v[20:23], v[116:119], v[198:201], v[20:23]
	v_mfma_f32_16x16x32_bf16 v[16:19], v[156:159], v[198:201], v[16:19]
	v_mfma_f32_16x16x32_bf16 v[0:3], v[156:159], v[206:209], v[0:3]
	v_mfma_f32_16x16x32_bf16 v[4:7], v[116:119], v[206:209], v[4:7]
	s_barrier
	s_add_i32 s88, s88, 2
	s_add_u32 s82, s82, 0x100
	s_addc_u32 s83, s83, 0
	s_add_u32 s75, s75, 0x100
	s_addc_u32 s81, s81, 0
.LBB0_1190:
	s_add_u32 s67, s82, 0xfff80080
	s_addc_u32 s84, s83, -1
	s_add_i32 s89, 0, 0x10000
	s_cmp_eq_u32 s88, 28
	s_cselect_b32 s87, s71, s84
	s_cselect_b32 s86, s72, s67
	s_cselect_b32 s85, s23, s81
	s_cselect_b32 s84, s73, s75
	s_add_i32 s67, 0, 0x14000
	v_add_u32_e32 v76, s89, v192
	v_add_u32_e32 v156, s67, v192
	ds_read_b128 v[64:67], v76
	ds_read_b128 v[68:71], v76 offset:1024
	ds_read_b128 v[72:75], v76 offset:2048
	ds_read_b128 v[76:79], v76 offset:3072
	ds_read_b128 v[80:83], v156
	ds_read_b128 v[116:119], v156 offset:1024
	ds_read_b128 v[152:155], v156 offset:2048
	ds_read_b128 v[156:159], v156 offset:3072
	v_lshl_add_u64 v[190:191], s[82:83], 0, v[186:187]
	s_add_i32 m0, s28, 0xc000
	ds_read_b128 v[160:163], v193
	ds_read_b128 v[164:167], v193 offset:1024
	ds_read_b128 v[168:171], v193 offset:2048
	ds_read_b128 v[172:175], v193 offset:3072
	ds_read_b128 v[194:197], v193 offset:4096
	ds_read_b128 v[198:201], v193 offset:5120
	ds_read_b128 v[202:205], v193 offset:6144
	ds_read_b128 v[206:209], v193 offset:7168
	global_load_lds_dwordx4 v[190:191], off
	v_lshl_add_u64 v[190:191], s[82:83], 0, v[188:189]
	s_add_i32 m0, s28, 0xe000
	s_nop 0
	global_load_lds_dwordx4 v[190:191], off
	s_waitcnt vmcnt(8)
	s_waitcnt lgkmcnt(0)
	s_barrier
	s_waitcnt lgkmcnt(0)
	v_mfma_f32_16x16x32_bf16 v[148:151], v[64:67], v[160:163], v[148:151]
	v_mfma_f32_16x16x32_bf16 v[144:147], v[72:75], v[160:163], v[144:147]
	v_mfma_f32_16x16x32_bf16 v[128:131], v[72:75], v[168:171], v[128:131]
	v_mfma_f32_16x16x32_bf16 v[132:135], v[64:67], v[168:171], v[132:135]
	v_mfma_f32_16x16x32_bf16 v[112:115], v[64:67], v[194:197], v[112:115]
	v_mfma_f32_16x16x32_bf16 v[108:111], v[72:75], v[194:197], v[108:111]
	v_mfma_f32_16x16x32_bf16 v[92:95], v[72:75], v[202:205], v[92:95]
	v_mfma_f32_16x16x32_bf16 v[96:99], v[64:67], v[202:205], v[96:99]
	v_mfma_f32_16x16x32_bf16 v[148:151], v[68:71], v[164:167], v[148:151]
	v_mfma_f32_16x16x32_bf16 v[144:147], v[76:79], v[164:167], v[144:147]
	v_mfma_f32_16x16x32_bf16 v[128:131], v[76:79], v[172:175], v[128:131]
	v_mfma_f32_16x16x32_bf16 v[132:135], v[68:71], v[172:175], v[132:135]
	v_mfma_f32_16x16x32_bf16 v[112:115], v[68:71], v[198:201], v[112:115]
	v_mfma_f32_16x16x32_bf16 v[108:111], v[76:79], v[198:201], v[108:111]
	v_mfma_f32_16x16x32_bf16 v[92:95], v[76:79], v[206:209], v[92:95]
	v_mfma_f32_16x16x32_bf16 v[96:99], v[68:71], v[206:209], v[96:99]
	v_mfma_f32_16x16x32_bf16 v[140:143], v[80:83], v[160:163], v[140:143]
	v_mfma_f32_16x16x32_bf16 v[136:139], v[152:155], v[160:163], v[136:139]
	v_mfma_f32_16x16x32_bf16 v[120:123], v[152:155], v[168:171], v[120:123]
	v_mfma_f32_16x16x32_bf16 v[124:127], v[80:83], v[168:171], v[124:127]
	v_mfma_f32_16x16x32_bf16 v[104:107], v[80:83], v[194:197], v[104:107]
	v_mfma_f32_16x16x32_bf16 v[100:103], v[152:155], v[194:197], v[100:103]
	v_mfma_f32_16x16x32_bf16 v[84:87], v[152:155], v[202:205], v[84:87]
	v_mfma_f32_16x16x32_bf16 v[88:91], v[80:83], v[202:205], v[88:91]
	v_mfma_f32_16x16x32_bf16 v[140:143], v[116:119], v[164:167], v[140:143]
	v_mfma_f32_16x16x32_bf16 v[136:139], v[156:159], v[164:167], v[136:139]
	v_mfma_f32_16x16x32_bf16 v[120:123], v[156:159], v[172:175], v[120:123]
	v_mfma_f32_16x16x32_bf16 v[124:127], v[116:119], v[172:175], v[124:127]
	v_mfma_f32_16x16x32_bf16 v[104:107], v[116:119], v[198:201], v[104:107]
	v_mfma_f32_16x16x32_bf16 v[100:103], v[156:159], v[198:201], v[100:103]
	v_mfma_f32_16x16x32_bf16 v[84:87], v[156:159], v[206:209], v[84:87]
	v_mfma_f32_16x16x32_bf16 v[88:91], v[116:119], v[206:209], v[88:91]
	s_barrier
	s_add_i32 s89, s89, s24
	v_lshl_add_u64 v[190:191], s[84:85], 0, v[180:181]
	s_mov_b32 m0, s89
	ds_read_b128 v[160:163], v193 offset:16384
	ds_read_b128 v[164:167], v193 offset:17408
	ds_read_b128 v[168:171], v193 offset:18432
	ds_read_b128 v[172:175], v193 offset:19456
	ds_read_b128 v[194:197], v193 offset:20480
	ds_read_b128 v[198:201], v193 offset:21504
	ds_read_b128 v[202:205], v193 offset:22528
	ds_read_b128 v[206:209], v193 offset:23552
	global_load_lds_dwordx4 v[190:191], off
	s_add_i32 m0, s89, 0x2000
	s_add_u32 s90, s84, 0x80000
	v_lshl_add_u64 v[210:211], s[84:85], 0, v[176:177]
	s_addc_u32 s91, s85, 0
	s_add_i32 s67, s67, s24
	global_load_lds_dwordx4 v[210:211], off
	v_lshl_add_u64 v[212:213], s[90:91], 0, v[180:181]
	s_mov_b32 m0, s67
	v_lshl_add_u64 v[214:215], s[86:87], 0, v[178:179]
	global_load_lds_dwordx4 v[212:213], off
	v_lshl_add_u64 v[212:213], s[90:91], 0, v[176:177]
	s_add_i32 m0, s67, 0x2000
	s_nop 0
	global_load_lds_dwordx4 v[212:213], off
	v_lshl_add_u64 v[212:213], s[86:87], 0, v[182:183]
	s_mov_b32 m0, s28
	s_nop 0
	global_load_lds_dwordx4 v[212:213], off
	s_mov_b32 m0, s29
	s_nop 0
	global_load_lds_dwordx4 v[214:215], off
	s_waitcnt vmcnt(8)
	s_waitcnt lgkmcnt(0)
	s_barrier
	s_waitcnt lgkmcnt(0)
	v_mfma_f32_16x16x32_bf16 v[60:63], v[64:67], v[160:163], v[60:63]
	v_mfma_f32_16x16x32_bf16 v[56:59], v[72:75], v[160:163], v[56:59]
	v_mfma_f32_16x16x32_bf16 v[40:43], v[72:75], v[168:171], v[40:43]
	v_mfma_f32_16x16x32_bf16 v[44:47], v[64:67], v[168:171], v[44:47]
	v_mfma_f32_16x16x32_bf16 v[28:31], v[64:67], v[194:197], v[28:31]
	v_mfma_f32_16x16x32_bf16 v[24:27], v[72:75], v[194:197], v[24:27]
	v_mfma_f32_16x16x32_bf16 v[8:11], v[72:75], v[202:205], v[8:11]
	v_mfma_f32_16x16x32_bf16 v[12:15], v[64:67], v[202:205], v[12:15]
	v_mfma_f32_16x16x32_bf16 v[60:63], v[68:71], v[164:167], v[60:63]
	v_mfma_f32_16x16x32_bf16 v[56:59], v[76:79], v[164:167], v[56:59]
	v_mfma_f32_16x16x32_bf16 v[40:43], v[76:79], v[172:175], v[40:43]
	v_mfma_f32_16x16x32_bf16 v[44:47], v[68:71], v[172:175], v[44:47]
	v_mfma_f32_16x16x32_bf16 v[28:31], v[68:71], v[198:201], v[28:31]
	v_mfma_f32_16x16x32_bf16 v[24:27], v[76:79], v[198:201], v[24:27]
	v_mfma_f32_16x16x32_bf16 v[8:11], v[76:79], v[206:209], v[8:11]
	v_mfma_f32_16x16x32_bf16 v[12:15], v[68:71], v[206:209], v[12:15]
	v_mfma_f32_16x16x32_bf16 v[52:55], v[80:83], v[160:163], v[52:55]
	v_mfma_f32_16x16x32_bf16 v[48:51], v[152:155], v[160:163], v[48:51]
	v_mfma_f32_16x16x32_bf16 v[32:35], v[152:155], v[168:171], v[32:35]
	v_mfma_f32_16x16x32_bf16 v[36:39], v[80:83], v[168:171], v[36:39]
	v_mfma_f32_16x16x32_bf16 v[20:23], v[80:83], v[194:197], v[20:23]
	v_mfma_f32_16x16x32_bf16 v[16:19], v[152:155], v[194:197], v[16:19]
	v_mfma_f32_16x16x32_bf16 v[0:3], v[152:155], v[202:205], v[0:3]
	v_mfma_f32_16x16x32_bf16 v[4:7], v[80:83], v[202:205], v[4:7]
	v_mfma_f32_16x16x32_bf16 v[52:55], v[116:119], v[164:167], v[52:55]
	v_mfma_f32_16x16x32_bf16 v[48:51], v[156:159], v[164:167], v[48:51]
	v_mfma_f32_16x16x32_bf16 v[32:35], v[156:159], v[172:175], v[32:35]
	v_mfma_f32_16x16x32_bf16 v[36:39], v[116:119], v[172:175], v[36:39]
	v_mfma_f32_16x16x32_bf16 v[20:23], v[116:119], v[198:201], v[20:23]
	v_mfma_f32_16x16x32_bf16 v[16:19], v[156:159], v[198:201], v[16:19]
	v_mfma_f32_16x16x32_bf16 v[0:3], v[156:159], v[206:209], v[0:3]
	v_mfma_f32_16x16x32_bf16 v[4:7], v[116:119], v[206:209], v[4:7]
	s_barrier
	s_add_i32 s67, 0, 0x18000
	s_add_i32 s89, 0, 0x1c000
	v_add_u32_e32 v76, s67, v192
	v_add_u32_e32 v156, s89, v192
	ds_read_b128 v[64:67], v76
	ds_read_b128 v[68:71], v76 offset:1024
	ds_read_b128 v[72:75], v76 offset:2048
	ds_read_b128 v[76:79], v76 offset:3072
	ds_read_b128 v[80:83], v156
	ds_read_b128 v[116:119], v156 offset:1024
	ds_read_b128 v[152:155], v156 offset:2048
	ds_read_b128 v[156:159], v156 offset:3072
	s_add_u32 s86, s86, 0x80000
	s_addc_u32 s87, s87, 0
	s_mov_b32 m0, s34
	v_lshl_add_u64 v[218:219], s[86:87], 0, v[182:183]
	ds_read_b128 v[160:163], v193 offset:32768
	ds_read_b128 v[164:167], v193 offset:33792
	ds_read_b128 v[168:171], v193 offset:34816
	ds_read_b128 v[172:175], v193 offset:35840
	ds_read_b128 v[194:197], v193 offset:36864
	ds_read_b128 v[198:201], v193 offset:37888
	ds_read_b128 v[202:205], v193 offset:38912
	ds_read_b128 v[206:209], v193 offset:39936
	global_load_lds_dwordx4 v[218:219], off
	v_lshl_add_u64 v[218:219], s[86:87], 0, v[178:179]
	s_mov_b32 m0, s35
	s_nop 0
	global_load_lds_dwordx4 v[218:219], off
	s_waitcnt vmcnt(8)
	s_waitcnt lgkmcnt(0)
	s_barrier
	s_waitcnt lgkmcnt(0)
	v_mfma_f32_16x16x32_bf16 v[148:151], v[64:67], v[160:163], v[148:151]
	v_mfma_f32_16x16x32_bf16 v[144:147], v[72:75], v[160:163], v[144:147]
	v_mfma_f32_16x16x32_bf16 v[128:131], v[72:75], v[168:171], v[128:131]
	v_mfma_f32_16x16x32_bf16 v[132:135], v[64:67], v[168:171], v[132:135]
	v_mfma_f32_16x16x32_bf16 v[112:115], v[64:67], v[194:197], v[112:115]
	v_mfma_f32_16x16x32_bf16 v[108:111], v[72:75], v[194:197], v[108:111]
	v_mfma_f32_16x16x32_bf16 v[92:95], v[72:75], v[202:205], v[92:95]
	v_mfma_f32_16x16x32_bf16 v[96:99], v[64:67], v[202:205], v[96:99]
	v_mfma_f32_16x16x32_bf16 v[148:151], v[68:71], v[164:167], v[148:151]
	v_mfma_f32_16x16x32_bf16 v[144:147], v[76:79], v[164:167], v[144:147]
	v_mfma_f32_16x16x32_bf16 v[128:131], v[76:79], v[172:175], v[128:131]
	v_mfma_f32_16x16x32_bf16 v[132:135], v[68:71], v[172:175], v[132:135]
	v_mfma_f32_16x16x32_bf16 v[112:115], v[68:71], v[198:201], v[112:115]
	v_mfma_f32_16x16x32_bf16 v[108:111], v[76:79], v[198:201], v[108:111]
	v_mfma_f32_16x16x32_bf16 v[92:95], v[76:79], v[206:209], v[92:95]
	v_mfma_f32_16x16x32_bf16 v[96:99], v[68:71], v[206:209], v[96:99]
	v_mfma_f32_16x16x32_bf16 v[140:143], v[80:83], v[160:163], v[140:143]
	v_mfma_f32_16x16x32_bf16 v[136:139], v[152:155], v[160:163], v[136:139]
	v_mfma_f32_16x16x32_bf16 v[120:123], v[152:155], v[168:171], v[120:123]
	v_mfma_f32_16x16x32_bf16 v[124:127], v[80:83], v[168:171], v[124:127]
	v_mfma_f32_16x16x32_bf16 v[104:107], v[80:83], v[194:197], v[104:107]
	v_mfma_f32_16x16x32_bf16 v[100:103], v[152:155], v[194:197], v[100:103]
	v_mfma_f32_16x16x32_bf16 v[84:87], v[152:155], v[202:205], v[84:87]
	v_mfma_f32_16x16x32_bf16 v[88:91], v[80:83], v[202:205], v[88:91]
	v_mfma_f32_16x16x32_bf16 v[140:143], v[116:119], v[164:167], v[140:143]
	v_mfma_f32_16x16x32_bf16 v[136:139], v[156:159], v[164:167], v[136:139]
	v_mfma_f32_16x16x32_bf16 v[120:123], v[156:159], v[172:175], v[120:123]
	v_mfma_f32_16x16x32_bf16 v[124:127], v[116:119], v[172:175], v[124:127]
	v_mfma_f32_16x16x32_bf16 v[104:107], v[116:119], v[198:201], v[104:107]
	v_mfma_f32_16x16x32_bf16 v[100:103], v[156:159], v[198:201], v[100:103]
	v_mfma_f32_16x16x32_bf16 v[84:87], v[156:159], v[206:209], v[84:87]
	v_mfma_f32_16x16x32_bf16 v[88:91], v[116:119], v[206:209], v[88:91]
	s_barrier
	s_add_i32 s67, s67, s24
	v_lshl_add_u64 v[190:191], v[190:191], 0, s[30:31]
	s_mov_b32 m0, s67
	ds_read_b128 v[160:163], v193 offset:49152
	ds_read_b128 v[164:167], v193 offset:50176
	ds_read_b128 v[168:171], v193 offset:51200
	ds_read_b128 v[172:175], v193 offset:52224
	ds_read_b128 v[194:197], v193 offset:53248
	ds_read_b128 v[198:201], v193 offset:54272
	ds_read_b128 v[202:205], v193 offset:55296
	ds_read_b128 v[206:209], v193 offset:56320
	global_load_lds_dwordx4 v[190:191], off
	s_add_i32 m0, s67, 0x2000
	s_add_u32 s84, s84, 0x80080
	v_lshl_add_u64 v[190:191], v[210:211], 0, s[30:31]
	s_addc_u32 s85, s85, 0
	s_add_i32 s67, s89, s24
	global_load_lds_dwordx4 v[190:191], off
	v_lshl_add_u64 v[190:191], s[84:85], 0, v[180:181]
	s_mov_b32 m0, s67
	s_nop 0
	global_load_lds_dwordx4 v[190:191], off
	v_lshl_add_u64 v[190:191], s[84:85], 0, v[176:177]
	s_add_i32 m0, s67, 0x2000
	s_nop 0
	global_load_lds_dwordx4 v[190:191], off
	v_lshl_add_u64 v[190:191], v[212:213], 0, s[30:31]
	s_mov_b32 m0, s53
	s_nop 0
	global_load_lds_dwordx4 v[190:191], off
	v_lshl_add_u64 v[190:191], v[214:215], 0, s[30:31]
	s_mov_b32 m0, s54
	s_nop 0
	global_load_lds_dwordx4 v[190:191], off
	s_waitcnt vmcnt(8)
	s_waitcnt lgkmcnt(0)
	s_barrier
	s_waitcnt lgkmcnt(0)
	v_mfma_f32_16x16x32_bf16 v[60:63], v[64:67], v[160:163], v[60:63]
	v_mfma_f32_16x16x32_bf16 v[56:59], v[72:75], v[160:163], v[56:59]
	v_mfma_f32_16x16x32_bf16 v[40:43], v[72:75], v[168:171], v[40:43]
	v_mfma_f32_16x16x32_bf16 v[44:47], v[64:67], v[168:171], v[44:47]
	v_mfma_f32_16x16x32_bf16 v[28:31], v[64:67], v[194:197], v[28:31]
	v_mfma_f32_16x16x32_bf16 v[24:27], v[72:75], v[194:197], v[24:27]
	v_mfma_f32_16x16x32_bf16 v[8:11], v[72:75], v[202:205], v[8:11]
	v_mfma_f32_16x16x32_bf16 v[12:15], v[64:67], v[202:205], v[12:15]
	v_mfma_f32_16x16x32_bf16 v[60:63], v[68:71], v[164:167], v[60:63]
	v_mfma_f32_16x16x32_bf16 v[56:59], v[76:79], v[164:167], v[56:59]
	v_mfma_f32_16x16x32_bf16 v[40:43], v[76:79], v[172:175], v[40:43]
	v_mfma_f32_16x16x32_bf16 v[44:47], v[68:71], v[172:175], v[44:47]
	v_mfma_f32_16x16x32_bf16 v[28:31], v[68:71], v[198:201], v[28:31]
	v_mfma_f32_16x16x32_bf16 v[24:27], v[76:79], v[198:201], v[24:27]
	v_mfma_f32_16x16x32_bf16 v[8:11], v[76:79], v[206:209], v[8:11]
	v_mfma_f32_16x16x32_bf16 v[12:15], v[68:71], v[206:209], v[12:15]
	v_mfma_f32_16x16x32_bf16 v[52:55], v[80:83], v[160:163], v[52:55]
	v_mfma_f32_16x16x32_bf16 v[48:51], v[152:155], v[160:163], v[48:51]
	v_mfma_f32_16x16x32_bf16 v[32:35], v[152:155], v[168:171], v[32:35]
	v_mfma_f32_16x16x32_bf16 v[36:39], v[80:83], v[168:171], v[36:39]
	v_mfma_f32_16x16x32_bf16 v[20:23], v[80:83], v[194:197], v[20:23]
	v_mfma_f32_16x16x32_bf16 v[16:19], v[152:155], v[194:197], v[16:19]
	v_mfma_f32_16x16x32_bf16 v[0:3], v[152:155], v[202:205], v[0:3]
	v_mfma_f32_16x16x32_bf16 v[4:7], v[80:83], v[202:205], v[4:7]
	v_mfma_f32_16x16x32_bf16 v[52:55], v[116:119], v[164:167], v[52:55]
	v_mfma_f32_16x16x32_bf16 v[48:51], v[156:159], v[164:167], v[48:51]
	v_mfma_f32_16x16x32_bf16 v[32:35], v[156:159], v[172:175], v[32:35]
	v_mfma_f32_16x16x32_bf16 v[36:39], v[116:119], v[172:175], v[36:39]
	v_mfma_f32_16x16x32_bf16 v[20:23], v[116:119], v[198:201], v[20:23]
	v_mfma_f32_16x16x32_bf16 v[16:19], v[156:159], v[198:201], v[16:19]
	v_mfma_f32_16x16x32_bf16 v[0:3], v[156:159], v[206:209], v[0:3]
	v_mfma_f32_16x16x32_bf16 v[4:7], v[116:119], v[206:209], v[4:7]
	s_barrier
	s_add_i32 s88, s88, 2
	s_add_u32 s82, s82, 0x100
	s_addc_u32 s83, s83, 0
	s_add_u32 s75, s75, 0x100
	s_addc_u32 s81, s81, 0
	s_cmp_gt_u32 s88, 29
	s_cbranch_scc0 .LBB0_1190
	s_and_b64 vcc, exec, s[18:19]
	s_cbranch_vccz .LBB0_1193
	s_barrier

.LBB0_1285:
	s_cmp_eq_u32 s54, 4
	s_cbranch_scc0 .Lsk_nt2
	s_bfe_u32 s67, s1, 0x20003
	s_mulk_i32 s67, 0xa00
	s_add_u32 s74, s74, s67
	s_addc_u32 s75, s75, 0
	s_add_u32 s76, s76, s67
	s_addc_u32 s77, s77, 0

.LBB0_1289:
	s_lshl_b32 s80, s96, 8
	s_ashr_i32 s81, s80, 31
	s_lshl_b64 s[86:87], s[80:81], 2
	s_add_u32 s84, s84, s86
	s_addc_u32 s85, s85, s87
	s_add_i32 m0, s94, s41
	s_add_u32 s81, s82, 0x100
	global_load_lds_dwordx4 v239, s[84:85]
	s_addc_u32 s96, s83, 0
	s_cmp_eq_u32 s54, 5
	s_cselect_b32 vcc_lo, 66, -2
	s_bfe_u32 s86, s1, 0x20003
	s_cmp_eq_u32 s86, 3
	s_cselect_b32 s86, -8, 0
	s_cmp_eq_u32 s54, 5
	s_cselect_b32 s86, s86, 0
	s_add_i32 vcc_lo, vcc_lo, s86
	s_add_u32 s82, s78, 0x100
	s_addc_u32 s83, s79, 0
	s_add_i32 s94, 0, 0x10000
	s_cmpk_eq_i32 vcc_lo, 0x54
	s_cselect_b32 s87, s75, s83
	s_cselect_b32 s86, s74, s82
	s_cselect_b32 s85, s77, s96
	s_cselect_b32 s84, s76, s81
	s_add_i32 vcc_hi, 0, 0x14000
	v_add_u32_e32 v96, s94, v238
	v_add_u32_e32 v140, vcc_hi, v238
	ds_read_b128 v[64:67], v96
	ds_read_b128 v[72:75], v96 offset:1024
	ds_read_b128 v[88:91], v96 offset:2048
	ds_read_b128 v[96:99], v96 offset:3072
	ds_read_b128 v[108:111], v140
	ds_read_b128 v[116:119], v140 offset:1024
	ds_read_b128 v[128:131], v140 offset:2048
	ds_read_b128 v[140:143], v140 offset:3072
	v_lshl_add_u64 v[192:193], s[78:79], 0, v[230:231]
	s_add_i32 m0, s29, 0xc000
	ds_read_b128 v[152:155], v240
	ds_read_b128 v[156:159], v240 offset:1024
	ds_read_b128 v[160:163], v240 offset:2048
	ds_read_b128 v[164:167], v240 offset:3072
	ds_read_b128 v[168:171], v240 offset:4096
	ds_read_b128 v[180:183], v240 offset:5120
	ds_read_b128 v[184:187], v240 offset:6144
	ds_read_b128 v[188:191], v240 offset:7168
	global_load_lds_dwordx4 v[192:193], off
	v_lshl_add_u64 v[192:193], s[78:79], 0, v[232:233]
	s_add_i32 m0, s29, 0xe000
	s_nop 0
	global_load_lds_dwordx4 v[192:193], off
	s_waitcnt vmcnt(8)
	s_waitcnt lgkmcnt(0)
	s_barrier
	s_waitcnt lgkmcnt(0)
	v_mfma_f32_16x16x32_bf16 v[176:179], v[64:67], v[152:155], 0
	v_mfma_f32_16x16x32_bf16 v[172:175], v[88:91], v[152:155], 0
	v_mfma_f32_16x16x32_bf16 v[132:135], v[88:91], v[160:163], 0
	v_mfma_f32_16x16x32_bf16 v[136:139], v[64:67], v[160:163], 0
	v_mfma_f32_16x16x32_bf16 v[112:115], v[64:67], v[168:171], 0
	v_mfma_f32_16x16x32_bf16 v[104:107], v[88:91], v[168:171], 0
	v_mfma_f32_16x16x32_bf16 v[80:83], v[88:91], v[184:187], 0
	v_mfma_f32_16x16x32_bf16 v[84:87], v[64:67], v[184:187], 0
	v_mfma_f32_16x16x32_bf16 v[176:179], v[72:75], v[156:159], v[176:179]
	v_mfma_f32_16x16x32_bf16 v[172:175], v[96:99], v[156:159], v[172:175]
	v_mfma_f32_16x16x32_bf16 v[132:135], v[96:99], v[164:167], v[132:135]
	v_mfma_f32_16x16x32_bf16 v[136:139], v[72:75], v[164:167], v[136:139]
	v_mfma_f32_16x16x32_bf16 v[112:115], v[72:75], v[180:183], v[112:115]
	v_mfma_f32_16x16x32_bf16 v[104:107], v[96:99], v[180:183], v[104:107]
	v_mfma_f32_16x16x32_bf16 v[80:83], v[96:99], v[188:191], v[80:83]
	v_mfma_f32_16x16x32_bf16 v[84:87], v[72:75], v[188:191], v[84:87]
	v_mfma_f32_16x16x32_bf16 v[148:151], v[108:111], v[152:155], 0
	v_mfma_f32_16x16x32_bf16 v[144:147], v[128:131], v[152:155], 0
	v_mfma_f32_16x16x32_bf16 v[120:123], v[128:131], v[160:163], 0
	v_mfma_f32_16x16x32_bf16 v[124:127], v[108:111], v[160:163], 0
	v_mfma_f32_16x16x32_bf16 v[100:103], v[108:111], v[168:171], 0
	v_mfma_f32_16x16x32_bf16 v[92:95], v[128:131], v[168:171], 0
	v_mfma_f32_16x16x32_bf16 v[68:71], v[128:131], v[184:187], 0
	v_mfma_f32_16x16x32_bf16 v[76:79], v[108:111], v[184:187], 0
	v_mfma_f32_16x16x32_bf16 v[148:151], v[116:119], v[156:159], v[148:151]
	v_mfma_f32_16x16x32_bf16 v[144:147], v[140:143], v[156:159], v[144:147]
	v_mfma_f32_16x16x32_bf16 v[120:123], v[140:143], v[164:167], v[120:123]
	v_mfma_f32_16x16x32_bf16 v[124:127], v[116:119], v[164:167], v[124:127]
	v_mfma_f32_16x16x32_bf16 v[100:103], v[116:119], v[180:183], v[100:103]
	v_mfma_f32_16x16x32_bf16 v[92:95], v[140:143], v[180:183], v[92:95]
	v_mfma_f32_16x16x32_bf16 v[68:71], v[140:143], v[188:191], v[68:71]
	v_mfma_f32_16x16x32_bf16 v[76:79], v[116:119], v[188:191], v[76:79]
	s_barrier
	s_add_i32 s78, s94, s2
	v_lshl_add_u64 v[192:193], s[84:85], 0, v[216:217]
	s_mov_b32 m0, s78
	ds_read_b128 v[152:155], v240 offset:16384
	ds_read_b128 v[156:159], v240 offset:17408
	ds_read_b128 v[160:163], v240 offset:18432
	ds_read_b128 v[164:167], v240 offset:19456
	ds_read_b128 v[168:171], v240 offset:20480
	ds_read_b128 v[180:183], v240 offset:21504
	ds_read_b128 v[184:187], v240 offset:22528
	ds_read_b128 v[188:191], v240 offset:23552
	global_load_lds_dwordx4 v[192:193], off
	s_add_i32 m0, s78, 0x2000
	s_add_u32 s78, s84, 0x160000
	v_lshl_add_u64 v[194:195], s[84:85], 0, v[228:229]
	s_addc_u32 s79, s85, 0
	s_add_i32 s94, vcc_hi, s2
	global_load_lds_dwordx4 v[194:195], off
	v_lshl_add_u64 v[196:197], s[78:79], 0, v[216:217]
	s_mov_b32 m0, s94
	v_lshl_add_u64 v[198:199], s[86:87], 0, v[226:227]
	global_load_lds_dwordx4 v[196:197], off
	v_lshl_add_u64 v[196:197], s[78:79], 0, v[228:229]
	s_add_i32 m0, s94, 0x2000
	s_nop 0
	global_load_lds_dwordx4 v[196:197], off
	v_lshl_add_u64 v[196:197], s[86:87], 0, v[224:225]
	s_mov_b32 m0, s29
	s_nop 0
	global_load_lds_dwordx4 v[196:197], off
	s_mov_b32 m0, s34
	s_nop 0
	global_load_lds_dwordx4 v[198:199], off
	s_waitcnt vmcnt(8)
	s_waitcnt lgkmcnt(0)
	s_barrier
	s_waitcnt lgkmcnt(0)
	v_mfma_f32_16x16x32_bf16 v[60:63], v[64:67], v[152:155], 0
	v_mfma_f32_16x16x32_bf16 v[56:59], v[88:91], v[152:155], 0
	v_mfma_f32_16x16x32_bf16 v[40:43], v[88:91], v[160:163], 0
	v_mfma_f32_16x16x32_bf16 v[44:47], v[64:67], v[160:163], 0
	v_mfma_f32_16x16x32_bf16 v[28:31], v[64:67], v[168:171], 0
	v_mfma_f32_16x16x32_bf16 v[24:27], v[88:91], v[168:171], 0
	v_mfma_f32_16x16x32_bf16 v[8:11], v[88:91], v[184:187], 0
	v_mfma_f32_16x16x32_bf16 v[12:15], v[64:67], v[184:187], 0
	v_mfma_f32_16x16x32_bf16 v[60:63], v[72:75], v[156:159], v[60:63]
	v_mfma_f32_16x16x32_bf16 v[56:59], v[96:99], v[156:159], v[56:59]
	v_mfma_f32_16x16x32_bf16 v[40:43], v[96:99], v[164:167], v[40:43]
	v_mfma_f32_16x16x32_bf16 v[44:47], v[72:75], v[164:167], v[44:47]
	v_mfma_f32_16x16x32_bf16 v[28:31], v[72:75], v[180:183], v[28:31]
	v_mfma_f32_16x16x32_bf16 v[24:27], v[96:99], v[180:183], v[24:27]
	v_mfma_f32_16x16x32_bf16 v[8:11], v[96:99], v[188:191], v[8:11]
	v_mfma_f32_16x16x32_bf16 v[12:15], v[72:75], v[188:191], v[12:15]
	v_mfma_f32_16x16x32_bf16 v[52:55], v[108:111], v[152:155], 0
	v_mfma_f32_16x16x32_bf16 v[48:51], v[128:131], v[152:155], 0
	v_mfma_f32_16x16x32_bf16 v[32:35], v[128:131], v[160:163], 0
	v_mfma_f32_16x16x32_bf16 v[36:39], v[108:111], v[160:163], 0
	v_mfma_f32_16x16x32_bf16 v[20:23], v[108:111], v[168:171], 0
	v_mfma_f32_16x16x32_bf16 v[16:19], v[128:131], v[168:171], 0
	v_mfma_f32_16x16x32_bf16 v[0:3], v[128:131], v[184:187], 0
	v_mfma_f32_16x16x32_bf16 v[4:7], v[108:111], v[184:187], 0
	v_mfma_f32_16x16x32_bf16 v[52:55], v[116:119], v[156:159], v[52:55]
	v_mfma_f32_16x16x32_bf16 v[48:51], v[140:143], v[156:159], v[48:51]
	v_mfma_f32_16x16x32_bf16 v[32:35], v[140:143], v[164:167], v[32:35]
	v_mfma_f32_16x16x32_bf16 v[36:39], v[116:119], v[164:167], v[36:39]
	v_mfma_f32_16x16x32_bf16 v[20:23], v[116:119], v[180:183], v[20:23]
	v_mfma_f32_16x16x32_bf16 v[16:19], v[140:143], v[180:183], v[16:19]
	v_mfma_f32_16x16x32_bf16 v[0:3], v[140:143], v[188:191], v[0:3]
	v_mfma_f32_16x16x32_bf16 v[4:7], v[116:119], v[188:191], v[4:7]
	s_barrier
	s_add_i32 s94, 0, 0x18000
	s_add_i32 vcc_hi, 0, 0x1c000
	v_add_u32_e32 v96, s94, v238
	v_add_u32_e32 v140, vcc_hi, v238
	ds_read_b128 v[64:67], v96
	ds_read_b128 v[72:75], v96 offset:1024
	ds_read_b128 v[88:91], v96 offset:2048
	ds_read_b128 v[96:99], v96 offset:3072
	ds_read_b128 v[108:111], v140
	ds_read_b128 v[116:119], v140 offset:1024
	ds_read_b128 v[128:131], v140 offset:2048
	ds_read_b128 v[140:143], v140 offset:3072
	s_add_u32 s78, s86, 0x160000
	s_addc_u32 s79, s87, 0
	s_mov_b32 m0, s35
	v_lshl_add_u64 v[200:201], s[78:79], 0, v[224:225]
	ds_read_b128 v[152:155], v240 offset:32768
	ds_read_b128 v[156:159], v240 offset:33792
	ds_read_b128 v[160:163], v240 offset:34816
	ds_read_b128 v[164:167], v240 offset:35840
	ds_read_b128 v[168:171], v240 offset:36864
	ds_read_b128 v[180:183], v240 offset:37888
	ds_read_b128 v[184:187], v240 offset:38912
	ds_read_b128 v[188:191], v240 offset:39936
	global_load_lds_dwordx4 v[200:201], off
	v_lshl_add_u64 v[200:201], s[78:79], 0, v[226:227]
	s_mov_b32 m0, s38
	s_nop 0
	global_load_lds_dwordx4 v[200:201], off
	s_waitcnt vmcnt(8)
	s_waitcnt lgkmcnt(0)
	s_barrier
	s_waitcnt lgkmcnt(0)
	v_mfma_f32_16x16x32_bf16 v[176:179], v[64:67], v[152:155], v[176:179]
	v_mfma_f32_16x16x32_bf16 v[172:175], v[88:91], v[152:155], v[172:175]
	v_mfma_f32_16x16x32_bf16 v[132:135], v[88:91], v[160:163], v[132:135]
	v_mfma_f32_16x16x32_bf16 v[136:139], v[64:67], v[160:163], v[136:139]
	v_mfma_f32_16x16x32_bf16 v[112:115], v[64:67], v[168:171], v[112:115]
	v_mfma_f32_16x16x32_bf16 v[104:107], v[88:91], v[168:171], v[104:107]
	v_mfma_f32_16x16x32_bf16 v[80:83], v[88:91], v[184:187], v[80:83]
	v_mfma_f32_16x16x32_bf16 v[84:87], v[64:67], v[184:187], v[84:87]
	v_mfma_f32_16x16x32_bf16 v[176:179], v[72:75], v[156:159], v[176:179]
	v_mfma_f32_16x16x32_bf16 v[172:175], v[96:99], v[156:159], v[172:175]
	v_mfma_f32_16x16x32_bf16 v[132:135], v[96:99], v[164:167], v[132:135]
	v_mfma_f32_16x16x32_bf16 v[136:139], v[72:75], v[164:167], v[136:139]
	v_mfma_f32_16x16x32_bf16 v[112:115], v[72:75], v[180:183], v[112:115]
	v_mfma_f32_16x16x32_bf16 v[104:107], v[96:99], v[180:183], v[104:107]
	v_mfma_f32_16x16x32_bf16 v[80:83], v[96:99], v[188:191], v[80:83]
	v_mfma_f32_16x16x32_bf16 v[84:87], v[72:75], v[188:191], v[84:87]
	v_mfma_f32_16x16x32_bf16 v[148:151], v[108:111], v[152:155], v[148:151]
	v_mfma_f32_16x16x32_bf16 v[144:147], v[128:131], v[152:155], v[144:147]
	v_mfma_f32_16x16x32_bf16 v[120:123], v[128:131], v[160:163], v[120:123]
	v_mfma_f32_16x16x32_bf16 v[124:127], v[108:111], v[160:163], v[124:127]
	v_mfma_f32_16x16x32_bf16 v[100:103], v[108:111], v[168:171], v[100:103]
	v_mfma_f32_16x16x32_bf16 v[92:95], v[128:131], v[168:171], v[92:95]
	v_mfma_f32_16x16x32_bf16 v[68:71], v[128:131], v[184:187], v[68:71]
	v_mfma_f32_16x16x32_bf16 v[76:79], v[108:111], v[184:187], v[76:79]
	v_mfma_f32_16x16x32_bf16 v[148:151], v[116:119], v[156:159], v[148:151]
	v_mfma_f32_16x16x32_bf16 v[144:147], v[140:143], v[156:159], v[144:147]
	v_mfma_f32_16x16x32_bf16 v[120:123], v[140:143], v[164:167], v[120:123]
	v_mfma_f32_16x16x32_bf16 v[124:127], v[116:119], v[164:167], v[124:127]
	v_mfma_f32_16x16x32_bf16 v[100:103], v[116:119], v[180:183], v[100:103]
	v_mfma_f32_16x16x32_bf16 v[92:95], v[140:143], v[180:183], v[92:95]
	v_mfma_f32_16x16x32_bf16 v[68:71], v[140:143], v[188:191], v[68:71]
	v_mfma_f32_16x16x32_bf16 v[76:79], v[116:119], v[188:191], v[76:79]
	s_barrier
	s_add_i32 s78, s94, s2
	v_lshl_add_u64 v[192:193], v[192:193], 0, s[30:31]
	s_mov_b32 m0, s78
	ds_read_b128 v[152:155], v240 offset:49152
	ds_read_b128 v[156:159], v240 offset:50176
	ds_read_b128 v[160:163], v240 offset:51200
	ds_read_b128 v[164:167], v240 offset:52224
	ds_read_b128 v[168:171], v240 offset:53248
	ds_read_b128 v[180:183], v240 offset:54272
	ds_read_b128 v[184:187], v240 offset:55296
	ds_read_b128 v[188:191], v240 offset:56320
	global_load_lds_dwordx4 v[192:193], off
	s_add_i32 m0, s78, 0x2000
	s_add_u32 s78, s84, 0x160080
	v_lshl_add_u64 v[192:193], v[194:195], 0, s[30:31]
	s_addc_u32 s79, s85, 0
	s_add_i32 s84, vcc_hi, s2
	global_load_lds_dwordx4 v[192:193], off
	v_lshl_add_u64 v[192:193], s[78:79], 0, v[216:217]
	s_mov_b32 m0, s84
	s_nop 0
	global_load_lds_dwordx4 v[192:193], off
	v_lshl_add_u64 v[192:193], s[78:79], 0, v[228:229]
	s_add_i32 m0, s84, 0x2000
	s_nop 0
	global_load_lds_dwordx4 v[192:193], off
	v_lshl_add_u64 v[192:193], v[196:197], 0, s[30:31]
	s_mov_b32 m0, s60
	s_nop 0
	global_load_lds_dwordx4 v[192:193], off
	v_lshl_add_u64 v[192:193], v[198:199], 0, s[30:31]
	s_mov_b32 m0, s61
	s_nop 0
	global_load_lds_dwordx4 v[192:193], off
	s_waitcnt vmcnt(8)
	s_waitcnt lgkmcnt(0)
	s_barrier
	s_waitcnt lgkmcnt(0)
	v_mfma_f32_16x16x32_bf16 v[60:63], v[64:67], v[152:155], v[60:63]
	v_mfma_f32_16x16x32_bf16 v[56:59], v[88:91], v[152:155], v[56:59]
	v_mfma_f32_16x16x32_bf16 v[40:43], v[88:91], v[160:163], v[40:43]
	v_mfma_f32_16x16x32_bf16 v[44:47], v[64:67], v[160:163], v[44:47]
	v_mfma_f32_16x16x32_bf16 v[28:31], v[64:67], v[168:171], v[28:31]
	v_mfma_f32_16x16x32_bf16 v[24:27], v[88:91], v[168:171], v[24:27]
	v_mfma_f32_16x16x32_bf16 v[8:11], v[88:91], v[184:187], v[8:11]
	v_mfma_f32_16x16x32_bf16 v[12:15], v[64:67], v[184:187], v[12:15]
	v_mfma_f32_16x16x32_bf16 v[60:63], v[72:75], v[156:159], v[60:63]
	v_mfma_f32_16x16x32_bf16 v[56:59], v[96:99], v[156:159], v[56:59]
	v_mfma_f32_16x16x32_bf16 v[40:43], v[96:99], v[164:167], v[40:43]
	v_mfma_f32_16x16x32_bf16 v[44:47], v[72:75], v[164:167], v[44:47]
	v_mfma_f32_16x16x32_bf16 v[28:31], v[72:75], v[180:183], v[28:31]
	v_mfma_f32_16x16x32_bf16 v[24:27], v[96:99], v[180:183], v[24:27]
	v_mfma_f32_16x16x32_bf16 v[8:11], v[96:99], v[188:191], v[8:11]
	v_mfma_f32_16x16x32_bf16 v[12:15], v[72:75], v[188:191], v[12:15]
	v_mfma_f32_16x16x32_bf16 v[52:55], v[108:111], v[152:155], v[52:55]
	v_mfma_f32_16x16x32_bf16 v[48:51], v[128:131], v[152:155], v[48:51]
	v_mfma_f32_16x16x32_bf16 v[32:35], v[128:131], v[160:163], v[32:35]
	v_mfma_f32_16x16x32_bf16 v[36:39], v[108:111], v[160:163], v[36:39]
	v_mfma_f32_16x16x32_bf16 v[20:23], v[108:111], v[168:171], v[20:23]
	v_mfma_f32_16x16x32_bf16 v[16:19], v[128:131], v[168:171], v[16:19]
	v_mfma_f32_16x16x32_bf16 v[0:3], v[128:131], v[184:187], v[0:3]
	v_mfma_f32_16x16x32_bf16 v[4:7], v[108:111], v[184:187], v[4:7]
	v_mfma_f32_16x16x32_bf16 v[52:55], v[116:119], v[156:159], v[52:55]
	v_mfma_f32_16x16x32_bf16 v[48:51], v[140:143], v[156:159], v[48:51]
	v_mfma_f32_16x16x32_bf16 v[32:35], v[140:143], v[164:167], v[32:35]
	v_mfma_f32_16x16x32_bf16 v[36:39], v[116:119], v[164:167], v[36:39]
	v_mfma_f32_16x16x32_bf16 v[20:23], v[116:119], v[180:183], v[20:23]
	v_mfma_f32_16x16x32_bf16 v[16:19], v[140:143], v[180:183], v[16:19]
	v_mfma_f32_16x16x32_bf16 v[0:3], v[140:143], v[188:191], v[0:3]
	v_mfma_f32_16x16x32_bf16 v[4:7], v[116:119], v[188:191], v[4:7]
	s_barrier
	s_add_i32 vcc_lo, vcc_lo, 2
	s_add_u32 s81, s81, 0x100
	s_addc_u32 s96, s96, 0
	s_mov_b64 s[78:79], s[82:83]
.LBB0_1290:
	s_add_u32 s82, s78, 0x100
	s_addc_u32 s83, s79, 0
	s_add_i32 s94, 0, 0x10000
	s_cmpk_eq_i32 vcc_lo, 0x54
	s_cselect_b32 s87, s75, s83
	s_cselect_b32 s86, s74, s82
	s_cselect_b32 s85, s77, s96
	s_cselect_b32 s84, s76, s81
	s_add_i32 vcc_hi, 0, 0x14000
	v_add_u32_e32 v96, s94, v238
	v_add_u32_e32 v140, vcc_hi, v238
	ds_read_b128 v[64:67], v96
	ds_read_b128 v[72:75], v96 offset:1024
	ds_read_b128 v[88:91], v96 offset:2048
	ds_read_b128 v[96:99], v96 offset:3072
	ds_read_b128 v[108:111], v140
	ds_read_b128 v[116:119], v140 offset:1024
	ds_read_b128 v[128:131], v140 offset:2048
	ds_read_b128 v[140:143], v140 offset:3072
	v_lshl_add_u64 v[192:193], s[78:79], 0, v[230:231]
	s_add_i32 m0, s29, 0xc000
	ds_read_b128 v[152:155], v240
	ds_read_b128 v[156:159], v240 offset:1024
	ds_read_b128 v[160:163], v240 offset:2048
	ds_read_b128 v[164:167], v240 offset:3072
	ds_read_b128 v[168:171], v240 offset:4096
	ds_read_b128 v[180:183], v240 offset:5120
	ds_read_b128 v[184:187], v240 offset:6144
	ds_read_b128 v[188:191], v240 offset:7168
	global_load_lds_dwordx4 v[192:193], off
	v_lshl_add_u64 v[192:193], s[78:79], 0, v[232:233]
	s_add_i32 m0, s29, 0xe000
	s_nop 0
	global_load_lds_dwordx4 v[192:193], off
	s_waitcnt vmcnt(8)
	s_waitcnt lgkmcnt(0)
	s_barrier
	s_waitcnt lgkmcnt(0)
	v_mfma_f32_16x16x32_bf16 v[176:179], v[64:67], v[152:155], v[176:179]
	v_mfma_f32_16x16x32_bf16 v[172:175], v[88:91], v[152:155], v[172:175]
	v_mfma_f32_16x16x32_bf16 v[132:135], v[88:91], v[160:163], v[132:135]
	v_mfma_f32_16x16x32_bf16 v[136:139], v[64:67], v[160:163], v[136:139]
	v_mfma_f32_16x16x32_bf16 v[112:115], v[64:67], v[168:171], v[112:115]
	v_mfma_f32_16x16x32_bf16 v[104:107], v[88:91], v[168:171], v[104:107]
	v_mfma_f32_16x16x32_bf16 v[80:83], v[88:91], v[184:187], v[80:83]
	v_mfma_f32_16x16x32_bf16 v[84:87], v[64:67], v[184:187], v[84:87]
	v_mfma_f32_16x16x32_bf16 v[176:179], v[72:75], v[156:159], v[176:179]
	v_mfma_f32_16x16x32_bf16 v[172:175], v[96:99], v[156:159], v[172:175]
	v_mfma_f32_16x16x32_bf16 v[132:135], v[96:99], v[164:167], v[132:135]
	v_mfma_f32_16x16x32_bf16 v[136:139], v[72:75], v[164:167], v[136:139]
	v_mfma_f32_16x16x32_bf16 v[112:115], v[72:75], v[180:183], v[112:115]
	v_mfma_f32_16x16x32_bf16 v[104:107], v[96:99], v[180:183], v[104:107]
	v_mfma_f32_16x16x32_bf16 v[80:83], v[96:99], v[188:191], v[80:83]
	v_mfma_f32_16x16x32_bf16 v[84:87], v[72:75], v[188:191], v[84:87]
	v_mfma_f32_16x16x32_bf16 v[148:151], v[108:111], v[152:155], v[148:151]
	v_mfma_f32_16x16x32_bf16 v[144:147], v[128:131], v[152:155], v[144:147]
	v_mfma_f32_16x16x32_bf16 v[120:123], v[128:131], v[160:163], v[120:123]
	v_mfma_f32_16x16x32_bf16 v[124:127], v[108:111], v[160:163], v[124:127]
	v_mfma_f32_16x16x32_bf16 v[100:103], v[108:111], v[168:171], v[100:103]
	v_mfma_f32_16x16x32_bf16 v[92:95], v[128:131], v[168:171], v[92:95]
	v_mfma_f32_16x16x32_bf16 v[68:71], v[128:131], v[184:187], v[68:71]
	v_mfma_f32_16x16x32_bf16 v[76:79], v[108:111], v[184:187], v[76:79]
	v_mfma_f32_16x16x32_bf16 v[148:151], v[116:119], v[156:159], v[148:151]
	v_mfma_f32_16x16x32_bf16 v[144:147], v[140:143], v[156:159], v[144:147]
	v_mfma_f32_16x16x32_bf16 v[120:123], v[140:143], v[164:167], v[120:123]
	v_mfma_f32_16x16x32_bf16 v[124:127], v[116:119], v[164:167], v[124:127]
	v_mfma_f32_16x16x32_bf16 v[100:103], v[116:119], v[180:183], v[100:103]
	v_mfma_f32_16x16x32_bf16 v[92:95], v[140:143], v[180:183], v[92:95]
	v_mfma_f32_16x16x32_bf16 v[68:71], v[140:143], v[188:191], v[68:71]
	v_mfma_f32_16x16x32_bf16 v[76:79], v[116:119], v[188:191], v[76:79]
	s_barrier
	s_add_i32 s78, s94, s2
	v_lshl_add_u64 v[192:193], s[84:85], 0, v[216:217]
	s_mov_b32 m0, s78
	ds_read_b128 v[152:155], v240 offset:16384
	ds_read_b128 v[156:159], v240 offset:17408
	ds_read_b128 v[160:163], v240 offset:18432
	ds_read_b128 v[164:167], v240 offset:19456
	ds_read_b128 v[168:171], v240 offset:20480
	ds_read_b128 v[180:183], v240 offset:21504
	ds_read_b128 v[184:187], v240 offset:22528
	ds_read_b128 v[188:191], v240 offset:23552
	global_load_lds_dwordx4 v[192:193], off
	s_add_i32 m0, s78, 0x2000
	s_add_u32 s78, s84, 0x160000
	v_lshl_add_u64 v[194:195], s[84:85], 0, v[228:229]
	s_addc_u32 s79, s85, 0
	s_add_i32 s94, vcc_hi, s2
	global_load_lds_dwordx4 v[194:195], off
	v_lshl_add_u64 v[196:197], s[78:79], 0, v[216:217]
	s_mov_b32 m0, s94
	v_lshl_add_u64 v[198:199], s[86:87], 0, v[226:227]
	global_load_lds_dwordx4 v[196:197], off
	v_lshl_add_u64 v[196:197], s[78:79], 0, v[228:229]
	s_add_i32 m0, s94, 0x2000
	s_nop 0
	global_load_lds_dwordx4 v[196:197], off
	v_lshl_add_u64 v[196:197], s[86:87], 0, v[224:225]
	s_mov_b32 m0, s29
	s_nop 0
	global_load_lds_dwordx4 v[196:197], off
	s_mov_b32 m0, s34
	s_nop 0
	global_load_lds_dwordx4 v[198:199], off
	s_waitcnt vmcnt(8)
	s_waitcnt lgkmcnt(0)
	s_barrier
	s_waitcnt lgkmcnt(0)
	v_mfma_f32_16x16x32_bf16 v[60:63], v[64:67], v[152:155], v[60:63]
	v_mfma_f32_16x16x32_bf16 v[56:59], v[88:91], v[152:155], v[56:59]
	v_mfma_f32_16x16x32_bf16 v[40:43], v[88:91], v[160:163], v[40:43]
	v_mfma_f32_16x16x32_bf16 v[44:47], v[64:67], v[160:163], v[44:47]
	v_mfma_f32_16x16x32_bf16 v[28:31], v[64:67], v[168:171], v[28:31]
	v_mfma_f32_16x16x32_bf16 v[24:27], v[88:91], v[168:171], v[24:27]
	v_mfma_f32_16x16x32_bf16 v[8:11], v[88:91], v[184:187], v[8:11]
	v_mfma_f32_16x16x32_bf16 v[12:15], v[64:67], v[184:187], v[12:15]
	v_mfma_f32_16x16x32_bf16 v[60:63], v[72:75], v[156:159], v[60:63]
	v_mfma_f32_16x16x32_bf16 v[56:59], v[96:99], v[156:159], v[56:59]
	v_mfma_f32_16x16x32_bf16 v[40:43], v[96:99], v[164:167], v[40:43]
	v_mfma_f32_16x16x32_bf16 v[44:47], v[72:75], v[164:167], v[44:47]
	v_mfma_f32_16x16x32_bf16 v[28:31], v[72:75], v[180:183], v[28:31]
	v_mfma_f32_16x16x32_bf16 v[24:27], v[96:99], v[180:183], v[24:27]
	v_mfma_f32_16x16x32_bf16 v[8:11], v[96:99], v[188:191], v[8:11]
	v_mfma_f32_16x16x32_bf16 v[12:15], v[72:75], v[188:191], v[12:15]
	v_mfma_f32_16x16x32_bf16 v[52:55], v[108:111], v[152:155], v[52:55]
	v_mfma_f32_16x16x32_bf16 v[48:51], v[128:131], v[152:155], v[48:51]
	v_mfma_f32_16x16x32_bf16 v[32:35], v[128:131], v[160:163], v[32:35]
	v_mfma_f32_16x16x32_bf16 v[36:39], v[108:111], v[160:163], v[36:39]
	v_mfma_f32_16x16x32_bf16 v[20:23], v[108:111], v[168:171], v[20:23]
	v_mfma_f32_16x16x32_bf16 v[16:19], v[128:131], v[168:171], v[16:19]
	v_mfma_f32_16x16x32_bf16 v[0:3], v[128:131], v[184:187], v[0:3]
	v_mfma_f32_16x16x32_bf16 v[4:7], v[108:111], v[184:187], v[4:7]
	v_mfma_f32_16x16x32_bf16 v[52:55], v[116:119], v[156:159], v[52:55]
	v_mfma_f32_16x16x32_bf16 v[48:51], v[140:143], v[156:159], v[48:51]
	v_mfma_f32_16x16x32_bf16 v[32:35], v[140:143], v[164:167], v[32:35]
	v_mfma_f32_16x16x32_bf16 v[36:39], v[116:119], v[164:167], v[36:39]
	v_mfma_f32_16x16x32_bf16 v[20:23], v[116:119], v[180:183], v[20:23]
	v_mfma_f32_16x16x32_bf16 v[16:19], v[140:143], v[180:183], v[16:19]
	v_mfma_f32_16x16x32_bf16 v[0:3], v[140:143], v[188:191], v[0:3]
	v_mfma_f32_16x16x32_bf16 v[4:7], v[116:119], v[188:191], v[4:7]
	s_barrier
	s_add_i32 s94, 0, 0x18000
	s_add_i32 vcc_hi, 0, 0x1c000
	v_add_u32_e32 v96, s94, v238
	v_add_u32_e32 v140, vcc_hi, v238
	ds_read_b128 v[64:67], v96
	ds_read_b128 v[72:75], v96 offset:1024
	ds_read_b128 v[88:91], v96 offset:2048
	ds_read_b128 v[96:99], v96 offset:3072
	ds_read_b128 v[108:111], v140
	ds_read_b128 v[116:119], v140 offset:1024
	ds_read_b128 v[128:131], v140 offset:2048
	ds_read_b128 v[140:143], v140 offset:3072
	s_add_u32 s78, s86, 0x160000
	s_addc_u32 s79, s87, 0
	s_mov_b32 m0, s35
	v_lshl_add_u64 v[200:201], s[78:79], 0, v[224:225]
	ds_read_b128 v[152:155], v240 offset:32768
	ds_read_b128 v[156:159], v240 offset:33792
	ds_read_b128 v[160:163], v240 offset:34816
	ds_read_b128 v[164:167], v240 offset:35840
	ds_read_b128 v[168:171], v240 offset:36864
	ds_read_b128 v[180:183], v240 offset:37888
	ds_read_b128 v[184:187], v240 offset:38912
	ds_read_b128 v[188:191], v240 offset:39936
	global_load_lds_dwordx4 v[200:201], off
	v_lshl_add_u64 v[200:201], s[78:79], 0, v[226:227]
	s_mov_b32 m0, s38
	s_nop 0
	global_load_lds_dwordx4 v[200:201], off
	s_waitcnt vmcnt(8)
	s_waitcnt lgkmcnt(0)
	s_barrier
	s_waitcnt lgkmcnt(0)
	v_mfma_f32_16x16x32_bf16 v[176:179], v[64:67], v[152:155], v[176:179]
	v_mfma_f32_16x16x32_bf16 v[172:175], v[88:91], v[152:155], v[172:175]
	v_mfma_f32_16x16x32_bf16 v[132:135], v[88:91], v[160:163], v[132:135]
	v_mfma_f32_16x16x32_bf16 v[136:139], v[64:67], v[160:163], v[136:139]
	v_mfma_f32_16x16x32_bf16 v[112:115], v[64:67], v[168:171], v[112:115]
	v_mfma_f32_16x16x32_bf16 v[104:107], v[88:91], v[168:171], v[104:107]
	v_mfma_f32_16x16x32_bf16 v[80:83], v[88:91], v[184:187], v[80:83]
	v_mfma_f32_16x16x32_bf16 v[84:87], v[64:67], v[184:187], v[84:87]
	v_mfma_f32_16x16x32_bf16 v[176:179], v[72:75], v[156:159], v[176:179]
	v_mfma_f32_16x16x32_bf16 v[172:175], v[96:99], v[156:159], v[172:175]
	v_mfma_f32_16x16x32_bf16 v[132:135], v[96:99], v[164:167], v[132:135]
	v_mfma_f32_16x16x32_bf16 v[136:139], v[72:75], v[164:167], v[136:139]
	v_mfma_f32_16x16x32_bf16 v[112:115], v[72:75], v[180:183], v[112:115]
	v_mfma_f32_16x16x32_bf16 v[104:107], v[96:99], v[180:183], v[104:107]
	v_mfma_f32_16x16x32_bf16 v[80:83], v[96:99], v[188:191], v[80:83]
	v_mfma_f32_16x16x32_bf16 v[84:87], v[72:75], v[188:191], v[84:87]
	v_mfma_f32_16x16x32_bf16 v[148:151], v[108:111], v[152:155], v[148:151]
	v_mfma_f32_16x16x32_bf16 v[144:147], v[128:131], v[152:155], v[144:147]
	v_mfma_f32_16x16x32_bf16 v[120:123], v[128:131], v[160:163], v[120:123]
	v_mfma_f32_16x16x32_bf16 v[124:127], v[108:111], v[160:163], v[124:127]
	v_mfma_f32_16x16x32_bf16 v[100:103], v[108:111], v[168:171], v[100:103]
	v_mfma_f32_16x16x32_bf16 v[92:95], v[128:131], v[168:171], v[92:95]
	v_mfma_f32_16x16x32_bf16 v[68:71], v[128:131], v[184:187], v[68:71]
	v_mfma_f32_16x16x32_bf16 v[76:79], v[108:111], v[184:187], v[76:79]
	v_mfma_f32_16x16x32_bf16 v[148:151], v[116:119], v[156:159], v[148:151]
	v_mfma_f32_16x16x32_bf16 v[144:147], v[140:143], v[156:159], v[144:147]
	v_mfma_f32_16x16x32_bf16 v[120:123], v[140:143], v[164:167], v[120:123]
	v_mfma_f32_16x16x32_bf16 v[124:127], v[116:119], v[164:167], v[124:127]
	v_mfma_f32_16x16x32_bf16 v[100:103], v[116:119], v[180:183], v[100:103]
	v_mfma_f32_16x16x32_bf16 v[92:95], v[140:143], v[180:183], v[92:95]
	v_mfma_f32_16x16x32_bf16 v[68:71], v[140:143], v[188:191], v[68:71]
	v_mfma_f32_16x16x32_bf16 v[76:79], v[116:119], v[188:191], v[76:79]
	s_barrier
	s_add_i32 s78, s94, s2
	v_lshl_add_u64 v[192:193], v[192:193], 0, s[30:31]
	s_mov_b32 m0, s78
	ds_read_b128 v[152:155], v240 offset:49152
	ds_read_b128 v[156:159], v240 offset:50176
	ds_read_b128 v[160:163], v240 offset:51200
	ds_read_b128 v[164:167], v240 offset:52224
	ds_read_b128 v[168:171], v240 offset:53248
	ds_read_b128 v[180:183], v240 offset:54272
	ds_read_b128 v[184:187], v240 offset:55296
	ds_read_b128 v[188:191], v240 offset:56320
	global_load_lds_dwordx4 v[192:193], off
	s_add_i32 m0, s78, 0x2000
	s_add_u32 s78, s84, 0x160080
	v_lshl_add_u64 v[192:193], v[194:195], 0, s[30:31]
	s_addc_u32 s79, s85, 0
	s_add_i32 s84, vcc_hi, s2
	global_load_lds_dwordx4 v[192:193], off
	v_lshl_add_u64 v[192:193], s[78:79], 0, v[216:217]
	s_mov_b32 m0, s84
	s_nop 0
	global_load_lds_dwordx4 v[192:193], off
	v_lshl_add_u64 v[192:193], s[78:79], 0, v[228:229]
	s_add_i32 m0, s84, 0x2000
	s_nop 0
	global_load_lds_dwordx4 v[192:193], off
	v_lshl_add_u64 v[192:193], v[196:197], 0, s[30:31]
	s_mov_b32 m0, s60
	s_nop 0
	global_load_lds_dwordx4 v[192:193], off
	v_lshl_add_u64 v[192:193], v[198:199], 0, s[30:31]
	s_mov_b32 m0, s61
	s_nop 0
	global_load_lds_dwordx4 v[192:193], off
	s_waitcnt vmcnt(8)
	s_waitcnt lgkmcnt(0)
	s_barrier
	s_waitcnt lgkmcnt(0)
	v_mfma_f32_16x16x32_bf16 v[60:63], v[64:67], v[152:155], v[60:63]
	v_mfma_f32_16x16x32_bf16 v[56:59], v[88:91], v[152:155], v[56:59]
	v_mfma_f32_16x16x32_bf16 v[40:43], v[88:91], v[160:163], v[40:43]
	v_mfma_f32_16x16x32_bf16 v[44:47], v[64:67], v[160:163], v[44:47]
	v_mfma_f32_16x16x32_bf16 v[28:31], v[64:67], v[168:171], v[28:31]
	v_mfma_f32_16x16x32_bf16 v[24:27], v[88:91], v[168:171], v[24:27]
	v_mfma_f32_16x16x32_bf16 v[8:11], v[88:91], v[184:187], v[8:11]
	v_mfma_f32_16x16x32_bf16 v[12:15], v[64:67], v[184:187], v[12:15]
	v_mfma_f32_16x16x32_bf16 v[60:63], v[72:75], v[156:159], v[60:63]
	v_mfma_f32_16x16x32_bf16 v[56:59], v[96:99], v[156:159], v[56:59]
	v_mfma_f32_16x16x32_bf16 v[40:43], v[96:99], v[164:167], v[40:43]
	v_mfma_f32_16x16x32_bf16 v[44:47], v[72:75], v[164:167], v[44:47]
	v_mfma_f32_16x16x32_bf16 v[28:31], v[72:75], v[180:183], v[28:31]
	v_mfma_f32_16x16x32_bf16 v[24:27], v[96:99], v[180:183], v[24:27]
	v_mfma_f32_16x16x32_bf16 v[8:11], v[96:99], v[188:191], v[8:11]
	v_mfma_f32_16x16x32_bf16 v[12:15], v[72:75], v[188:191], v[12:15]
	v_mfma_f32_16x16x32_bf16 v[52:55], v[108:111], v[152:155], v[52:55]
	v_mfma_f32_16x16x32_bf16 v[48:51], v[128:131], v[152:155], v[48:51]
	v_mfma_f32_16x16x32_bf16 v[32:35], v[128:131], v[160:163], v[32:35]
	v_mfma_f32_16x16x32_bf16 v[36:39], v[108:111], v[160:163], v[36:39]
	v_mfma_f32_16x16x32_bf16 v[20:23], v[108:111], v[168:171], v[20:23]
	v_mfma_f32_16x16x32_bf16 v[16:19], v[128:131], v[168:171], v[16:19]
	v_mfma_f32_16x16x32_bf16 v[0:3], v[128:131], v[184:187], v[0:3]
	v_mfma_f32_16x16x32_bf16 v[4:7], v[108:111], v[184:187], v[4:7]
	v_mfma_f32_16x16x32_bf16 v[52:55], v[116:119], v[156:159], v[52:55]
	v_mfma_f32_16x16x32_bf16 v[48:51], v[140:143], v[156:159], v[48:51]
	v_mfma_f32_16x16x32_bf16 v[32:35], v[140:143], v[164:167], v[32:35]
	v_mfma_f32_16x16x32_bf16 v[36:39], v[116:119], v[164:167], v[36:39]
	v_mfma_f32_16x16x32_bf16 v[20:23], v[116:119], v[180:183], v[20:23]
	v_mfma_f32_16x16x32_bf16 v[16:19], v[140:143], v[180:183], v[16:19]
	v_mfma_f32_16x16x32_bf16 v[0:3], v[140:143], v[188:191], v[0:3]
	v_mfma_f32_16x16x32_bf16 v[4:7], v[116:119], v[188:191], v[4:7]
	s_barrier
	s_add_i32 vcc_lo, vcc_lo, 2
	s_add_u32 s81, s81, 0x100
	s_addc_u32 s96, s96, 0
	s_cmpk_gt_u32 vcc_lo, 0x55
	s_mov_b64 s[78:79], s[82:83]
	s_cbranch_scc0 .LBB0_1290
	s_and_b64 vcc, exec, s[70:71]
	s_cbranch_vccz .LBB0_1293
	s_barrier
